# sec 7.11 back-edge rotation: K-loop counter/pointer SALU block and exit compare moved ahead of the last barrier in 8 GEMM K-loops
# baseline (speedup 1.0000x reference)
; #define PG8_STAGE(bufoff, gbase, voff) do { _Pragma("unroll") for (int _i = 0; _i < 2; ++_i) \
;         __builtin_amdgcn_global_load_lds((const unsigned*)((const char*)(gbase) + (voff)[_i]), (LAS unsigned*)(lds + (bufoff) + ldsw + _i * 8192), 16, 0, 0); } while (0)
; #define PG8_LDA(dst, b, h) do { _Pragma("unroll") for (int m = 0; m < 4; ++m) _Pragma("unroll") for (int k = 0; k < 2; ++k) dst[m][k] = *(const LAS bf16x8*)(lds + PG8_SA(b, h) + aoff + m * 2048 + k * 1024); } while (0)
; #define PG8_LDB(dst, b, h) do { _Pragma("unroll") for (int n = 0; n < 2; ++n) _Pragma("unroll") for (int k = 0; k < 2; ++k) dst[n][k] = *(const LAS bf16x8*)(lds + PG8_SB(b, h) + boff + n * 2048 + k * 1024); } while (0)
; #define PG8_MMA(ai, bj, At, Bt) do { __builtin_amdgcn_s_setprio(1); _Pragma("unroll") for (int m = 0; m < 4; ++m) _Pragma("unroll") for (int n = 0; n < 2; ++n) _Pragma("unroll") for (int k = 0; k < 2; ++k) \
;         acc[ai][bj][m][n] = __builtin_amdgcn_mfma_f32_16x16x32_bf16(Bt[n][k], At[m][k], acc[ai][bj][m][n], 0, 0, 0); __builtin_amdgcn_s_setprio(0); } while (0)
; #define PG8_WAIT_V(n) asm volatile("s_waitcnt vmcnt(" #n ")" ::: "memory")
; #define PG8_WAIT_L(n) asm volatile("s_waitcnt lgkmcnt(" #n ")" ::: "memory")
; #define PG8_BAR __builtin_amdgcn_s_barrier()
; #define PG8_SCHED __builtin_amdgcn_sched_barrier(0)
; template <class Epi, class Sched, bool ALIGN_EPI>
; DI void gemm_phase(LAS unsigned char* lds, const Gemm g, const Sched& Sc, const Epi& E, const int tid) {
;     ...
;         for (int t = 0; t < nt; t += 2) {
;             const bool last = (t == nt - 2);
;             const char* a1 = cA + (size_t)(t + 1) * kstep;
;             const char* a2 = last ? nA : cA + (size_t)(t + 2) * kstep; const char* b2 = last ? nB : cB + (size_t)(t + 2) * kstep;
;             const char* a3 = a2 + kstep; const char* b3 = b2 + kstep;
;             PG8_LDB(B0, 0, 0); PG8_LDB(B1, 0, 1); PG8_SCHED; PG8_LDA(At, 0, 0); PG8_STAGE(PG8_SA(1, 1), a1 + hA, voffA);
;             PG8_WAIT_V(8); PG8_WAIT_L(0); PG8_BAR; PG8_MMA(0, 0, At, B0); PG8_MMA(0, 1, At, B1); PG8_BAR; PG8_SCHED;
;             PG8_LDA(At, 0, 1); PG8_STAGE(PG8_SB(0, 0), b2, voffB); PG8_STAGE(PG8_SB(0, 1), b2 + hB, voffB); PG8_STAGE(PG8_SA(0, 0), a2, voffA);
;             PG8_WAIT_V(8); PG8_WAIT_L(0); PG8_BAR; PG8_MMA(1, 0, At, B0); PG8_MMA(1, 1, At, B1); PG8_BAR; PG8_SCHED;
.LBB0_482:
	v_add_u32_e32 v18, s70, v151
	ds_read_b128 v[124:127], v18
	ds_read_b128 v[128:131], v18 offset:1024
	ds_read_b128 v[160:163], v18 offset:2048
	ds_read_b128 v[164:167], v18 offset:3072
	v_add_u32_e32 v18, s73, v151
	ds_read_b128 v[170:173], v18
	ds_read_b128 v[174:177], v18 offset:1024
	ds_read_b128 v[178:181], v18 offset:2048
	ds_read_b128 v[182:185], v18 offset:3072
	s_add_u32 s22, s12, 0xfff80080
	s_addc_u32 s23, s13, -1
	s_cmp_eq_u32 s47, 28
	s_cselect_b32 s31, s40, s23
	s_cselect_b32 s30, s41, s22
	s_cselect_b32 s23, s42, s45
	s_cselect_b32 s22, s43, s44
	v_lshl_add_u64 v[194:195], s[12:13], 0, v[154:155]
	s_add_i32 m0, s76, 0xc000
	ds_read_b128 v[186:189], v169
	ds_read_b128 v[190:193], v169 offset:1024
	ds_read_b128 v[210:213], v169 offset:2048
	ds_read_b128 v[214:217], v169 offset:3072
	ds_read_b128 v[218:221], v169 offset:4096
	ds_read_b128 v[222:225], v169 offset:5120
	ds_read_b128 v[226:229], v169 offset:6144
	ds_read_b128 v[240:243], v169 offset:7168
	global_load_lds_dwordx4 v[194:195], off
	v_lshl_add_u64 v[194:195], s[12:13], 0, v[152:153]
	s_add_i32 m0, s76, 0xe000
	s_nop 0
	global_load_lds_dwordx4 v[194:195], off
	s_waitcnt vmcnt(8)
	s_waitcnt lgkmcnt(0)
	s_barrier
	s_setprio 1
	s_waitcnt lgkmcnt(0)
	v_mfma_f32_16x16x32_bf16 v[116:119], v[124:127], v[186:189], v[116:119]
	v_mfma_f32_16x16x32_bf16 v[120:123], v[160:163], v[186:189], v[120:123]
	v_mfma_f32_16x16x32_bf16 v[112:115], v[124:127], v[210:213], v[112:115]
	v_mfma_f32_16x16x32_bf16 v[104:107], v[160:163], v[210:213], v[104:107]
	v_mfma_f32_16x16x32_bf16 v[96:99], v[124:127], v[218:221], v[96:99]
	v_mfma_f32_16x16x32_bf16 v[92:95], v[160:163], v[218:221], v[92:95]
	v_mfma_f32_16x16x32_bf16 v[80:83], v[124:127], v[226:229], v[80:83]
	v_mfma_f32_16x16x32_bf16 v[72:75], v[160:163], v[226:229], v[72:75]
	v_mfma_f32_16x16x32_bf16 v[116:119], v[128:131], v[190:193], v[116:119]
	v_mfma_f32_16x16x32_bf16 v[120:123], v[164:167], v[190:193], v[120:123]
	v_mfma_f32_16x16x32_bf16 v[112:115], v[128:131], v[214:217], v[112:115]
	v_mfma_f32_16x16x32_bf16 v[104:107], v[164:167], v[214:217], v[104:107]
	v_mfma_f32_16x16x32_bf16 v[96:99], v[128:131], v[222:225], v[96:99]
	v_mfma_f32_16x16x32_bf16 v[92:95], v[164:167], v[222:225], v[92:95]
	v_mfma_f32_16x16x32_bf16 v[80:83], v[128:131], v[240:243], v[80:83]
	v_mfma_f32_16x16x32_bf16 v[72:75], v[164:167], v[240:243], v[72:75]
	s_setprio 0
	s_setprio 1
	v_mfma_f32_16x16x32_bf16 v[108:111], v[170:173], v[186:189], v[108:111]
	v_mfma_f32_16x16x32_bf16 v[100:103], v[178:181], v[186:189], v[100:103]
	v_mfma_f32_16x16x32_bf16 v[88:91], v[170:173], v[210:213], v[88:91]
	v_mfma_f32_16x16x32_bf16 v[84:87], v[178:181], v[210:213], v[84:87]
	v_mfma_f32_16x16x32_bf16 v[76:79], v[170:173], v[218:221], v[76:79]
	v_mfma_f32_16x16x32_bf16 v[68:71], v[178:181], v[218:221], v[68:71]
	v_mfma_f32_16x16x32_bf16 v[64:67], v[170:173], v[226:229], v[64:67]
	v_mfma_f32_16x16x32_bf16 v[60:63], v[178:181], v[226:229], v[60:63]
	v_mfma_f32_16x16x32_bf16 v[108:111], v[174:177], v[190:193], v[108:111]
	v_mfma_f32_16x16x32_bf16 v[100:103], v[182:185], v[190:193], v[100:103]
	v_mfma_f32_16x16x32_bf16 v[88:91], v[174:177], v[214:217], v[88:91]
	v_mfma_f32_16x16x32_bf16 v[84:87], v[182:185], v[214:217], v[84:87]
	v_mfma_f32_16x16x32_bf16 v[76:79], v[174:177], v[222:225], v[76:79]
	v_mfma_f32_16x16x32_bf16 v[68:71], v[182:185], v[222:225], v[68:71]
	v_mfma_f32_16x16x32_bf16 v[64:67], v[174:177], v[240:243], v[64:67]
	v_mfma_f32_16x16x32_bf16 v[60:63], v[182:185], v[240:243], v[60:63]
	s_setprio 0
	s_barrier
	s_mov_b32 m0, s71
	v_lshl_add_u64 v[194:195], s[22:23], 0, v[142:143]
	s_add_u32 s54, s22, 0x80000
	ds_read_b128 v[186:189], v169 offset:16384
	ds_read_b128 v[190:193], v169 offset:17408
	ds_read_b128 v[210:213], v169 offset:18432
	ds_read_b128 v[214:217], v169 offset:19456
	ds_read_b128 v[218:221], v169 offset:20480
	ds_read_b128 v[222:225], v169 offset:21504
	ds_read_b128 v[226:229], v169 offset:22528
	ds_read_b128 v[240:243], v169 offset:23552
	global_load_lds_dwordx4 v[194:195], off
	v_lshl_add_u64 v[198:199], s[22:23], 0, v[146:147]
	s_mov_b32 m0, s72
	s_addc_u32 s55, s23, 0
	global_load_lds_dwordx4 v[198:199], off
	v_lshl_add_u64 v[200:201], s[54:55], 0, v[142:143]
	s_mov_b32 m0, s74
	v_lshl_add_u64 v[230:231], s[30:31], 0, v[144:145]
	global_load_lds_dwordx4 v[200:201], off
	v_lshl_add_u64 v[200:201], s[54:55], 0, v[146:147]
	s_mov_b32 m0, s75
	s_nop 0
	global_load_lds_dwordx4 v[200:201], off
	v_lshl_add_u64 v[200:201], s[30:31], 0, v[140:141]
	s_mov_b32 m0, s76
	s_nop 0
	global_load_lds_dwordx4 v[200:201], off
	s_mov_b32 m0, s77
	s_nop 0
	global_load_lds_dwordx4 v[230:231], off
	s_waitcnt vmcnt(8)
	s_waitcnt lgkmcnt(0)
	s_barrier
; #define PG8_STAGE(bufoff, gbase, voff) do { _Pragma("unroll") for (int _i = 0; _i < 2; ++_i) \
;         __builtin_amdgcn_global_load_lds((const unsigned*)((const char*)(gbase) + (voff)[_i]), (LAS unsigned*)(lds + (bufoff) + ldsw + _i * 8192), 16, 0, 0); } while (0)
; #define PG8_LDA(dst, b, h) do { _Pragma("unroll") for (int m = 0; m < 4; ++m) _Pragma("unroll") for (int k = 0; k < 2; ++k) dst[m][k] = *(const LAS bf16x8*)(lds + PG8_SA(b, h) + aoff + m * 2048 + k * 1024); } while (0)
; #define PG8_LDB(dst, b, h) do { _Pragma("unroll") for (int n = 0; n < 2; ++n) _Pragma("unroll") for (int k = 0; k < 2; ++k) dst[n][k] = *(const LAS bf16x8*)(lds + PG8_SB(b, h) + boff + n * 2048 + k * 1024); } while (0)
; #define PG8_MMA(ai, bj, At, Bt) do { __builtin_amdgcn_s_setprio(1); _Pragma("unroll") for (int m = 0; m < 4; ++m) _Pragma("unroll") for (int n = 0; n < 2; ++n) _Pragma("unroll") for (int k = 0; k < 2; ++k) \
;         acc[ai][bj][m][n] = __builtin_amdgcn_mfma_f32_16x16x32_bf16(Bt[n][k], At[m][k], acc[ai][bj][m][n], 0, 0, 0); __builtin_amdgcn_s_setprio(0); } while (0)
; #define PG8_WAIT_V(n) asm volatile("s_waitcnt vmcnt(" #n ")" ::: "memory")
; #define PG8_WAIT_L(n) asm volatile("s_waitcnt lgkmcnt(" #n ")" ::: "memory")
; #define PG8_BAR __builtin_amdgcn_s_barrier()
; #define PG8_SCHED __builtin_amdgcn_sched_barrier(0)
; template <class Epi, class Sched, bool ALIGN_EPI>
; DI void gemm_phase(LAS unsigned char* lds, const Gemm g, const Sched& Sc, const Epi& E, const int tid) {
;     ...
;             PG8_WAIT_V(8); PG8_WAIT_L(0); PG8_BAR; PG8_MMA(1, 0, At, B0); PG8_MMA(1, 1, At, B1); PG8_BAR; PG8_SCHED;
;             PG8_LDB(B0, 1, 0); PG8_LDB(B1, 1, 1); PG8_SCHED; PG8_LDA(At, 1, 0); PG8_STAGE(PG8_SA(0, 1), a2 + hA, voffA);
;             PG8_WAIT_V(8); PG8_WAIT_L(0); PG8_BAR; PG8_MMA(0, 0, At, B0); PG8_MMA(0, 1, At, B1); PG8_BAR; PG8_SCHED;
;             PG8_LDA(At, 1, 1); PG8_STAGE(PG8_SB(1, 0), b3, voffB); PG8_STAGE(PG8_SB(1, 1), b3 + hB, voffB); PG8_STAGE(PG8_SA(1, 0), a3, voffA);
;             PG8_WAIT_V(8); PG8_WAIT_L(0); PG8_BAR; PG8_MMA(1, 0, At, B0); PG8_MMA(1, 1, At, B1); PG8_BAR; PG8_SCHED;
	s_setprio 1
	s_waitcnt lgkmcnt(0)
	v_mfma_f32_16x16x32_bf16 v[52:55], v[124:127], v[186:189], v[52:55]
	v_mfma_f32_16x16x32_bf16 v[56:59], v[160:163], v[186:189], v[56:59]
	v_mfma_f32_16x16x32_bf16 v[48:51], v[124:127], v[210:213], v[48:51]
	v_mfma_f32_16x16x32_bf16 v[40:43], v[160:163], v[210:213], v[40:43]
	v_mfma_f32_16x16x32_bf16 v[32:35], v[124:127], v[218:221], v[32:35]
	v_mfma_f32_16x16x32_bf16 v[28:31], v[160:163], v[218:221], v[28:31]
	v_mfma_f32_16x16x32_bf16 v[124:127], v[124:127], v[226:229], v[136:139]
	v_mfma_f32_16x16x32_bf16 v[52:55], v[128:131], v[190:193], v[52:55]
	v_mfma_f32_16x16x32_bf16 v[56:59], v[164:167], v[190:193], v[56:59]
	v_mfma_f32_16x16x32_bf16 v[48:51], v[128:131], v[214:217], v[48:51]
	v_mfma_f32_16x16x32_bf16 v[40:43], v[164:167], v[214:217], v[40:43]
	v_mfma_f32_16x16x32_bf16 v[32:35], v[128:131], v[222:225], v[32:35]
	v_mfma_f32_16x16x32_bf16 v[28:31], v[164:167], v[222:225], v[28:31]
	v_mfma_f32_16x16x32_bf16 v[124:127], v[128:131], v[240:243], v[124:127]
	v_mfma_f32_16x16x32_bf16 v[128:131], v[160:163], v[226:229], v[132:135]
	v_mfma_f32_16x16x32_bf16 v[128:131], v[164:167], v[240:243], v[128:131]
	s_setprio 0
	s_setprio 1
	v_mfma_f32_16x16x32_bf16 v[44:47], v[170:173], v[186:189], v[44:47]
	v_mfma_f32_16x16x32_bf16 v[36:39], v[178:181], v[186:189], v[36:39]
	v_mfma_f32_16x16x32_bf16 v[24:27], v[170:173], v[210:213], v[24:27]
	v_mfma_f32_16x16x32_bf16 v[20:23], v[178:181], v[210:213], v[20:23]
	v_mfma_f32_16x16x32_bf16 v[10:13], v[170:173], v[218:221], v[10:13]
	v_mfma_f32_16x16x32_bf16 v[2:5], v[178:181], v[218:221], v[2:5]
	v_mfma_f32_16x16x32_bf16 v[14:17], v[170:173], v[226:229], v[14:17]
	v_mfma_f32_16x16x32_bf16 v[6:9], v[178:181], v[226:229], v[6:9]
	v_mfma_f32_16x16x32_bf16 v[44:47], v[174:177], v[190:193], v[44:47]
	v_mfma_f32_16x16x32_bf16 v[36:39], v[182:185], v[190:193], v[36:39]
	v_mfma_f32_16x16x32_bf16 v[24:27], v[174:177], v[214:217], v[24:27]
	v_mfma_f32_16x16x32_bf16 v[20:23], v[182:185], v[214:217], v[20:23]
	v_mfma_f32_16x16x32_bf16 v[10:13], v[174:177], v[222:225], v[10:13]
	v_mfma_f32_16x16x32_bf16 v[2:5], v[182:185], v[222:225], v[2:5]
	v_mfma_f32_16x16x32_bf16 v[14:17], v[174:177], v[240:243], v[14:17]
	v_mfma_f32_16x16x32_bf16 v[6:9], v[182:185], v[240:243], v[6:9]
	s_setprio 0
	s_barrier
	v_add_u32_e32 v18, s80, v151
	ds_read_b128 v[132:135], v18
	ds_read_b128 v[136:139], v18 offset:1024
	ds_read_b128 v[160:163], v18 offset:2048
	ds_read_b128 v[164:167], v18 offset:3072
	v_add_u32_e32 v18, s85, v151
	ds_read_b128 v[170:173], v18
	ds_read_b128 v[174:177], v18 offset:1024
	ds_read_b128 v[178:181], v18 offset:2048
	ds_read_b128 v[182:185], v18 offset:3072
	s_add_u32 s30, s30, 0x80000
	s_addc_u32 s31, s31, 0
	s_mov_b32 m0, s78
	v_lshl_add_u64 v[232:233], s[30:31], 0, v[140:141]
	ds_read_b128 v[186:189], v169 offset:32768
	ds_read_b128 v[190:193], v169 offset:33792
	ds_read_b128 v[210:213], v169 offset:34816
	ds_read_b128 v[214:217], v169 offset:35840
	ds_read_b128 v[218:221], v169 offset:36864
	ds_read_b128 v[222:225], v169 offset:37888
	ds_read_b128 v[226:229], v169 offset:38912
	ds_read_b128 v[240:243], v169 offset:39936
	global_load_lds_dwordx4 v[232:233], off
	v_lshl_add_u64 v[232:233], s[30:31], 0, v[144:145]
	s_mov_b32 m0, s79
	s_nop 0
	global_load_lds_dwordx4 v[232:233], off
	s_waitcnt vmcnt(8)
	s_waitcnt lgkmcnt(0)
	s_barrier
	s_setprio 1
	s_waitcnt lgkmcnt(0)
	v_mfma_f32_16x16x32_bf16 v[116:119], v[132:135], v[186:189], v[116:119]
	v_mfma_f32_16x16x32_bf16 v[120:123], v[160:163], v[186:189], v[120:123]
	v_mfma_f32_16x16x32_bf16 v[112:115], v[132:135], v[210:213], v[112:115]
	v_mfma_f32_16x16x32_bf16 v[104:107], v[160:163], v[210:213], v[104:107]
	v_mfma_f32_16x16x32_bf16 v[96:99], v[132:135], v[218:221], v[96:99]
	v_mfma_f32_16x16x32_bf16 v[92:95], v[160:163], v[218:221], v[92:95]
	v_mfma_f32_16x16x32_bf16 v[80:83], v[132:135], v[226:229], v[80:83]
	v_mfma_f32_16x16x32_bf16 v[72:75], v[160:163], v[226:229], v[72:75]
	v_mfma_f32_16x16x32_bf16 v[116:119], v[136:139], v[190:193], v[116:119]
	v_mfma_f32_16x16x32_bf16 v[120:123], v[164:167], v[190:193], v[120:123]
	v_mfma_f32_16x16x32_bf16 v[112:115], v[136:139], v[214:217], v[112:115]
	v_mfma_f32_16x16x32_bf16 v[104:107], v[164:167], v[214:217], v[104:107]
	v_mfma_f32_16x16x32_bf16 v[96:99], v[136:139], v[222:225], v[96:99]
	v_mfma_f32_16x16x32_bf16 v[92:95], v[164:167], v[222:225], v[92:95]
	v_mfma_f32_16x16x32_bf16 v[80:83], v[136:139], v[240:243], v[80:83]
	v_mfma_f32_16x16x32_bf16 v[72:75], v[164:167], v[240:243], v[72:75]
	s_setprio 0
	s_setprio 1
	v_mfma_f32_16x16x32_bf16 v[108:111], v[170:173], v[186:189], v[108:111]
	v_mfma_f32_16x16x32_bf16 v[100:103], v[178:181], v[186:189], v[100:103]
	v_mfma_f32_16x16x32_bf16 v[88:91], v[170:173], v[210:213], v[88:91]
	v_mfma_f32_16x16x32_bf16 v[84:87], v[178:181], v[210:213], v[84:87]
	v_mfma_f32_16x16x32_bf16 v[76:79], v[170:173], v[218:221], v[76:79]
	v_mfma_f32_16x16x32_bf16 v[68:71], v[178:181], v[218:221], v[68:71]
	v_mfma_f32_16x16x32_bf16 v[64:67], v[170:173], v[226:229], v[64:67]
	v_mfma_f32_16x16x32_bf16 v[60:63], v[178:181], v[226:229], v[60:63]
	v_mfma_f32_16x16x32_bf16 v[108:111], v[174:177], v[190:193], v[108:111]
	v_mfma_f32_16x16x32_bf16 v[100:103], v[182:185], v[190:193], v[100:103]
	v_mfma_f32_16x16x32_bf16 v[88:91], v[174:177], v[214:217], v[88:91]
	v_mfma_f32_16x16x32_bf16 v[84:87], v[182:185], v[214:217], v[84:87]
	v_mfma_f32_16x16x32_bf16 v[76:79], v[174:177], v[222:225], v[76:79]
	v_mfma_f32_16x16x32_bf16 v[68:71], v[182:185], v[222:225], v[68:71]
	v_mfma_f32_16x16x32_bf16 v[64:67], v[174:177], v[240:243], v[64:67]
	v_mfma_f32_16x16x32_bf16 v[60:63], v[182:185], v[240:243], v[60:63]
	s_setprio 0
	s_barrier
; #define PG8_STAGE(bufoff, gbase, voff) do { _Pragma("unroll") for (int _i = 0; _i < 2; ++_i) \
;         __builtin_amdgcn_global_load_lds((const unsigned*)((const char*)(gbase) + (voff)[_i]), (LAS unsigned*)(lds + (bufoff) + ldsw + _i * 8192), 16, 0, 0); } while (0)
; #define PG8_LDA(dst, b, h) do { _Pragma("unroll") for (int m = 0; m < 4; ++m) _Pragma("unroll") for (int k = 0; k < 2; ++k) dst[m][k] = *(const LAS bf16x8*)(lds + PG8_SA(b, h) + aoff + m * 2048 + k * 1024); } while (0)
; #define PG8_MMA(ai, bj, At, Bt) do { __builtin_amdgcn_s_setprio(1); _Pragma("unroll") for (int m = 0; m < 4; ++m) _Pragma("unroll") for (int n = 0; n < 2; ++n) _Pragma("unroll") for (int k = 0; k < 2; ++k) \
;         acc[ai][bj][m][n] = __builtin_amdgcn_mfma_f32_16x16x32_bf16(Bt[n][k], At[m][k], acc[ai][bj][m][n], 0, 0, 0); __builtin_amdgcn_s_setprio(0); } while (0)
; #define PG8_WAIT_V(n) asm volatile("s_waitcnt vmcnt(" #n ")" ::: "memory")
; #define PG8_WAIT_L(n) asm volatile("s_waitcnt lgkmcnt(" #n ")" ::: "memory")
; #define PG8_BAR __builtin_amdgcn_s_barrier()
; #define PG8_SCHED __builtin_amdgcn_sched_barrier(0)
; template <class Epi, class Sched, bool ALIGN_EPI>
; DI void gemm_phase(LAS unsigned char* lds, const Gemm g, const Sched& Sc, const Epi& E, const int tid) {
;     ...
;             PG8_LDA(At, 1, 1); PG8_STAGE(PG8_SB(1, 0), b3, voffB); PG8_STAGE(PG8_SB(1, 1), b3 + hB, voffB); PG8_STAGE(PG8_SA(1, 0), a3, voffA);
;             PG8_WAIT_V(8); PG8_WAIT_L(0); PG8_BAR; PG8_MMA(1, 0, At, B0); PG8_MMA(1, 1, At, B1); PG8_BAR; PG8_SCHED;
;         }
	s_mov_b32 m0, s81
	v_lshl_add_u64 v[194:195], v[194:195], 0, s[60:61]
	s_add_u32 s22, s22, 0x80080
	ds_read_b128 v[186:189], v169 offset:49152
	ds_read_b128 v[190:193], v169 offset:50176
	ds_read_b128 v[210:213], v169 offset:51200
	ds_read_b128 v[214:217], v169 offset:52224
	ds_read_b128 v[218:221], v169 offset:53248
	ds_read_b128 v[222:225], v169 offset:54272
	ds_read_b128 v[226:229], v169 offset:55296
	ds_read_b128 v[240:243], v169 offset:56320
	global_load_lds_dwordx4 v[194:195], off
	v_lshl_add_u64 v[194:195], v[198:199], 0, s[60:61]
	s_mov_b32 m0, s82
	s_addc_u32 s23, s23, 0
	global_load_lds_dwordx4 v[194:195], off
	v_lshl_add_u64 v[194:195], s[22:23], 0, v[142:143]
	s_mov_b32 m0, s86
	s_nop 0
	global_load_lds_dwordx4 v[194:195], off
	v_lshl_add_u64 v[194:195], s[22:23], 0, v[146:147]
	s_mov_b32 m0, s87
	s_nop 0
	global_load_lds_dwordx4 v[194:195], off
	v_lshl_add_u64 v[194:195], v[200:201], 0, s[60:61]
	s_mov_b32 m0, s83
	s_nop 0
	global_load_lds_dwordx4 v[194:195], off
	v_lshl_add_u64 v[194:195], v[230:231], 0, s[60:61]
	s_mov_b32 m0, s84
	s_nop 0
	global_load_lds_dwordx4 v[194:195], off
	s_waitcnt vmcnt(8)
	s_waitcnt lgkmcnt(0)
	s_barrier
	s_setprio 1
	s_waitcnt lgkmcnt(0)
	v_mfma_f32_16x16x32_bf16 v[52:55], v[132:135], v[186:189], v[52:55]
	v_mfma_f32_16x16x32_bf16 v[48:51], v[132:135], v[210:213], v[48:51]
	v_mfma_f32_16x16x32_bf16 v[32:35], v[132:135], v[218:221], v[32:35]
	v_mfma_f32_16x16x32_bf16 v[124:127], v[132:135], v[226:229], v[124:127]
	v_mfma_f32_16x16x32_bf16 v[52:55], v[136:139], v[190:193], v[52:55]
	v_mfma_f32_16x16x32_bf16 v[56:59], v[160:163], v[186:189], v[56:59]
	v_mfma_f32_16x16x32_bf16 v[48:51], v[136:139], v[214:217], v[48:51]
	v_mfma_f32_16x16x32_bf16 v[40:43], v[160:163], v[210:213], v[40:43]
	v_mfma_f32_16x16x32_bf16 v[32:35], v[136:139], v[222:225], v[32:35]
	v_mfma_f32_16x16x32_bf16 v[28:31], v[160:163], v[218:221], v[28:31]
	v_mfma_f32_16x16x32_bf16 v[136:139], v[136:139], v[240:243], v[124:127]
	v_mfma_f32_16x16x32_bf16 v[124:127], v[160:163], v[226:229], v[128:131]
	v_mfma_f32_16x16x32_bf16 v[56:59], v[164:167], v[190:193], v[56:59]
	v_mfma_f32_16x16x32_bf16 v[40:43], v[164:167], v[214:217], v[40:43]
	v_mfma_f32_16x16x32_bf16 v[28:31], v[164:167], v[222:225], v[28:31]
	v_mfma_f32_16x16x32_bf16 v[132:135], v[164:167], v[240:243], v[124:127]
	s_setprio 0
	s_setprio 1
	v_mfma_f32_16x16x32_bf16 v[44:47], v[170:173], v[186:189], v[44:47]
	v_mfma_f32_16x16x32_bf16 v[36:39], v[178:181], v[186:189], v[36:39]
	v_mfma_f32_16x16x32_bf16 v[24:27], v[170:173], v[210:213], v[24:27]
	v_mfma_f32_16x16x32_bf16 v[20:23], v[178:181], v[210:213], v[20:23]
	v_mfma_f32_16x16x32_bf16 v[10:13], v[170:173], v[218:221], v[10:13]
	v_mfma_f32_16x16x32_bf16 v[2:5], v[178:181], v[218:221], v[2:5]
	v_mfma_f32_16x16x32_bf16 v[14:17], v[170:173], v[226:229], v[14:17]
	v_mfma_f32_16x16x32_bf16 v[6:9], v[178:181], v[226:229], v[6:9]
	v_mfma_f32_16x16x32_bf16 v[44:47], v[174:177], v[190:193], v[44:47]
	v_mfma_f32_16x16x32_bf16 v[36:39], v[182:185], v[190:193], v[36:39]
	v_mfma_f32_16x16x32_bf16 v[24:27], v[174:177], v[214:217], v[24:27]
	v_mfma_f32_16x16x32_bf16 v[20:23], v[182:185], v[214:217], v[20:23]
	v_mfma_f32_16x16x32_bf16 v[10:13], v[174:177], v[222:225], v[10:13]
	v_mfma_f32_16x16x32_bf16 v[2:5], v[182:185], v[222:225], v[2:5]
	v_mfma_f32_16x16x32_bf16 v[14:17], v[174:177], v[240:243], v[14:17]
	v_mfma_f32_16x16x32_bf16 v[6:9], v[182:185], v[240:243], v[6:9]
	s_add_i32 s47, s47, 2
	s_add_u32 s44, s44, 0x100
	s_addc_u32 s45, s45, 0
	s_add_u32 s12, s12, 0x100
	s_addc_u32 s13, s13, 0
	s_cmp_gt_u32 s47, 29
	s_setprio 0
	s_barrier
	s_cbranch_scc0 .LBB0_482
	s_and_b64 vcc, exec, s[26:27]
	s_cbranch_vccz .LBB0_485
	s_barrier

; #define PG8_STAGE(bufoff, gbase, voff) do { _Pragma("unroll") for (int _i = 0; _i < 2; ++_i) \
;         __builtin_amdgcn_global_load_lds((const unsigned*)((const char*)(gbase) + (voff)[_i]), (LAS unsigned*)(lds + (bufoff) + ldsw + _i * 8192), 16, 0, 0); } while (0)
; #define PG8_LDA(dst, b, h) do { _Pragma("unroll") for (int m = 0; m < 4; ++m) _Pragma("unroll") for (int k = 0; k < 2; ++k) dst[m][k] = *(const LAS bf16x8*)(lds + PG8_SA(b, h) + aoff + m * 2048 + k * 1024); } while (0)
; #define PG8_LDB(dst, b, h) do { _Pragma("unroll") for (int n = 0; n < 2; ++n) _Pragma("unroll") for (int k = 0; k < 2; ++k) dst[n][k] = *(const LAS bf16x8*)(lds + PG8_SB(b, h) + boff + n * 2048 + k * 1024); } while (0)
; #define PG8_MMA(ai, bj, At, Bt) do { __builtin_amdgcn_s_setprio(1); _Pragma("unroll") for (int m = 0; m < 4; ++m) _Pragma("unroll") for (int n = 0; n < 2; ++n) _Pragma("unroll") for (int k = 0; k < 2; ++k) \
;         acc[ai][bj][m][n] = __builtin_amdgcn_mfma_f32_16x16x32_bf16(Bt[n][k], At[m][k], acc[ai][bj][m][n], 0, 0, 0); __builtin_amdgcn_s_setprio(0); } while (0)
; #define PG8_WAIT_V(n) asm volatile("s_waitcnt vmcnt(" #n ")" ::: "memory")
; #define PG8_WAIT_L(n) asm volatile("s_waitcnt lgkmcnt(" #n ")" ::: "memory")
; #define PG8_BAR __builtin_amdgcn_s_barrier()
; #define PG8_SCHED __builtin_amdgcn_sched_barrier(0)
; template <class Epi, class Sched, bool ALIGN_EPI>
; DI void gemm_phase(LAS unsigned char* lds, const Gemm g, const Sched& Sc, const Epi& E, const int tid) {
;     ...
;         for (int t = 0; t < nt; t += 2) {
;             const bool last = (t == nt - 2);
;             const char* a1 = cA + (size_t)(t + 1) * kstep;
;             const char* a2 = last ? nA : cA + (size_t)(t + 2) * kstep; const char* b2 = last ? nB : cB + (size_t)(t + 2) * kstep;
;             const char* a3 = a2 + kstep; const char* b3 = b2 + kstep;
;             PG8_LDB(B0, 0, 0); PG8_LDB(B1, 0, 1); PG8_SCHED; PG8_LDA(At, 0, 0); PG8_STAGE(PG8_SA(1, 1), a1 + hA, voffA);
;             PG8_WAIT_V(8); PG8_WAIT_L(0); PG8_BAR; PG8_MMA(0, 0, At, B0); PG8_MMA(0, 1, At, B1); PG8_BAR; PG8_SCHED;
;             PG8_LDA(At, 0, 1); PG8_STAGE(PG8_SB(0, 0), b2, voffB); PG8_STAGE(PG8_SB(0, 1), b2 + hB, voffB); PG8_STAGE(PG8_SA(0, 0), a2, voffA);
;             PG8_WAIT_V(8); PG8_WAIT_L(0); PG8_BAR; PG8_MMA(1, 0, At, B0); PG8_MMA(1, 1, At, B1); PG8_BAR; PG8_SCHED;
.LBB0_664:
	v_add_u32_e32 v160, s17, v146
	s_add_u32 s22, s55, s2
	ds_read_b128 v[148:151], v160
	ds_read_b128 v[152:155], v160 offset:1024
	ds_read_b128 v[156:159], v160 offset:2048
	ds_read_b128 v[160:163], v160 offset:3072
	s_addc_u32 s23, s56, s3
	s_add_u32 s22, s22, 0x24300100
	s_addc_u32 s23, s23, 0
	s_add_u32 s62, s53, s2
	s_addc_u32 s63, s54, s3
	s_cmpk_eq_i32 s2, 0xf00
	s_cselect_b32 s27, s19, s23
	s_cselect_b32 s26, s18, s22
	s_cselect_b32 s23, s13, s63
	s_cselect_b32 s22, s12, s62
	v_lshl_add_u64 v[198:199], v[140:141], 0, s[2:3]
	s_add_i32 m0, s39, 0xc000
	ds_read_b128 v[180:183], v147
	ds_read_b128 v[184:187], v147 offset:1024
	ds_read_b128 v[188:191], v147 offset:2048
	ds_read_b128 v[192:195], v147 offset:3072
	ds_read_b128 v[210:213], v147 offset:4096
	ds_read_b128 v[214:217], v147 offset:5120
	ds_read_b128 v[218:221], v147 offset:6144
	ds_read_b128 v[222:225], v147 offset:7168
	global_load_lds_dwordx4 v[198:199], off
	v_lshl_add_u64 v[198:199], v[138:139], 0, s[2:3]
	s_add_i32 m0, s39, 0xe000
	s_nop 0
	global_load_lds_dwordx4 v[198:199], off
	s_waitcnt vmcnt(6)
	s_waitcnt lgkmcnt(0)
	s_barrier
	s_setprio 1
	s_waitcnt lgkmcnt(0)
	v_mfma_f32_16x16x32_bf16 v[128:131], v[148:151], v[180:183], v[128:131]
	v_mfma_f32_16x16x32_bf16 v[124:127], v[156:159], v[180:183], v[124:127]
	v_mfma_f32_16x16x32_bf16 v[120:123], v[148:151], v[188:191], v[120:123]
	v_mfma_f32_16x16x32_bf16 v[116:119], v[156:159], v[188:191], v[116:119]
	v_mfma_f32_16x16x32_bf16 v[96:99], v[148:151], v[210:213], v[96:99]
	v_mfma_f32_16x16x32_bf16 v[92:95], v[156:159], v[210:213], v[92:95]
	v_mfma_f32_16x16x32_bf16 v[88:91], v[148:151], v[218:221], v[88:91]
	v_mfma_f32_16x16x32_bf16 v[84:87], v[156:159], v[218:221], v[84:87]
	v_mfma_f32_16x16x32_bf16 v[128:131], v[152:155], v[184:187], v[128:131]
	v_mfma_f32_16x16x32_bf16 v[124:127], v[160:163], v[184:187], v[124:127]
	v_mfma_f32_16x16x32_bf16 v[120:123], v[152:155], v[192:195], v[120:123]
	v_mfma_f32_16x16x32_bf16 v[116:119], v[160:163], v[192:195], v[116:119]
	v_mfma_f32_16x16x32_bf16 v[96:99], v[152:155], v[214:217], v[96:99]
	v_mfma_f32_16x16x32_bf16 v[92:95], v[160:163], v[214:217], v[92:95]
	v_mfma_f32_16x16x32_bf16 v[88:91], v[152:155], v[222:225], v[88:91]
	v_mfma_f32_16x16x32_bf16 v[84:87], v[160:163], v[222:225], v[84:87]
	s_setprio 0
	s_barrier
	s_mov_b32 m0, s20
	v_lshl_add_u64 v[198:199], s[22:23], 0, v[132:133]
	s_add_u32 s62, s22, 0x80000
	ds_read_b128 v[180:183], v147 offset:16384
	ds_read_b128 v[184:187], v147 offset:17408
	ds_read_b128 v[188:191], v147 offset:18432
	ds_read_b128 v[192:195], v147 offset:19456
	ds_read_b128 v[210:213], v147 offset:20480
	ds_read_b128 v[214:217], v147 offset:21504
	ds_read_b128 v[218:221], v147 offset:22528
	ds_read_b128 v[222:225], v147 offset:23552
	global_load_lds_dwordx4 v[198:199], off
	v_lshl_add_u64 v[200:201], s[22:23], 0, v[136:137]
	s_mov_b32 m0, s31
	s_addc_u32 s63, s23, 0
	global_load_lds_dwordx4 v[200:201], off
	v_lshl_add_u64 v[226:227], s[62:63], 0, v[132:133]
	v_lshl_add_u64 v[228:229], s[26:27], 0, v[134:135]
	v_lshl_add_u64 v[226:227], s[62:63], 0, v[136:137]
	v_lshl_add_u64 v[226:227], s[26:27], 0, v[18:19]
	s_mov_b32 m0, s39
	s_nop 0
	global_load_lds_dwordx4 v[226:227], off
	s_mov_b32 m0, s40
	s_nop 0
	global_load_lds_dwordx4 v[228:229], off
	s_waitcnt vmcnt(6)
	s_waitcnt lgkmcnt(0)
	s_barrier
	s_setprio 1
	s_waitcnt lgkmcnt(0)
	v_mfma_f32_16x16x32_bf16 v[64:67], v[148:151], v[180:183], v[64:67]
	v_mfma_f32_16x16x32_bf16 v[60:63], v[156:159], v[180:183], v[60:63]
	v_mfma_f32_16x16x32_bf16 v[56:59], v[148:151], v[188:191], v[56:59]
	v_mfma_f32_16x16x32_bf16 v[52:55], v[156:159], v[188:191], v[52:55]
	v_mfma_f32_16x16x32_bf16 v[32:35], v[148:151], v[210:213], v[32:35]
	v_mfma_f32_16x16x32_bf16 v[28:31], v[156:159], v[210:213], v[28:31]
	v_mfma_f32_16x16x32_bf16 v[24:27], v[148:151], v[218:221], v[24:27]
	v_mfma_f32_16x16x32_bf16 v[20:23], v[156:159], v[218:221], v[20:23]
	v_mfma_f32_16x16x32_bf16 v[64:67], v[152:155], v[184:187], v[64:67]
	v_mfma_f32_16x16x32_bf16 v[60:63], v[160:163], v[184:187], v[60:63]
	v_mfma_f32_16x16x32_bf16 v[56:59], v[152:155], v[192:195], v[56:59]
	v_mfma_f32_16x16x32_bf16 v[52:55], v[160:163], v[192:195], v[52:55]
	v_mfma_f32_16x16x32_bf16 v[32:35], v[152:155], v[214:217], v[32:35]
	v_mfma_f32_16x16x32_bf16 v[28:31], v[160:163], v[214:217], v[28:31]
	v_mfma_f32_16x16x32_bf16 v[24:27], v[152:155], v[222:225], v[24:27]
	v_mfma_f32_16x16x32_bf16 v[20:23], v[160:163], v[222:225], v[20:23]
	s_setprio 0
	s_barrier
; #define PG8_STAGE(bufoff, gbase, voff) do { _Pragma("unroll") for (int _i = 0; _i < 2; ++_i) \
;         __builtin_amdgcn_global_load_lds((const unsigned*)((const char*)(gbase) + (voff)[_i]), (LAS unsigned*)(lds + (bufoff) + ldsw + _i * 8192), 16, 0, 0); } while (0)
; #define PG8_LDA(dst, b, h) do { _Pragma("unroll") for (int m = 0; m < 4; ++m) _Pragma("unroll") for (int k = 0; k < 2; ++k) dst[m][k] = *(const LAS bf16x8*)(lds + PG8_SA(b, h) + aoff + m * 2048 + k * 1024); } while (0)
; #define PG8_LDB(dst, b, h) do { _Pragma("unroll") for (int n = 0; n < 2; ++n) _Pragma("unroll") for (int k = 0; k < 2; ++k) dst[n][k] = *(const LAS bf16x8*)(lds + PG8_SB(b, h) + boff + n * 2048 + k * 1024); } while (0)
; #define PG8_MMA(ai, bj, At, Bt) do { __builtin_amdgcn_s_setprio(1); _Pragma("unroll") for (int m = 0; m < 4; ++m) _Pragma("unroll") for (int n = 0; n < 2; ++n) _Pragma("unroll") for (int k = 0; k < 2; ++k) \
;         acc[ai][bj][m][n] = __builtin_amdgcn_mfma_f32_16x16x32_bf16(Bt[n][k], At[m][k], acc[ai][bj][m][n], 0, 0, 0); __builtin_amdgcn_s_setprio(0); } while (0)
; #define PG8_WAIT_V(n) asm volatile("s_waitcnt vmcnt(" #n ")" ::: "memory")
; #define PG8_WAIT_L(n) asm volatile("s_waitcnt lgkmcnt(" #n ")" ::: "memory")
; #define PG8_BAR __builtin_amdgcn_s_barrier()
; #define PG8_SCHED __builtin_amdgcn_sched_barrier(0)
; template <class Epi, class Sched, bool ALIGN_EPI>
; DI void gemm_phase(LAS unsigned char* lds, const Gemm g, const Sched& Sc, const Epi& E, const int tid) {
;     ...
;             PG8_LDB(B0, 1, 0); PG8_LDB(B1, 1, 1); PG8_SCHED; PG8_LDA(At, 1, 0); PG8_STAGE(PG8_SA(0, 1), a2 + hA, voffA);
;             PG8_WAIT_V(8); PG8_WAIT_L(0); PG8_BAR; PG8_MMA(0, 0, At, B0); PG8_MMA(0, 1, At, B1); PG8_BAR; PG8_SCHED;
;             PG8_LDA(At, 1, 1); PG8_STAGE(PG8_SB(1, 0), b3, voffB); PG8_STAGE(PG8_SB(1, 1), b3 + hB, voffB); PG8_STAGE(PG8_SA(1, 0), a3, voffA);
;             PG8_WAIT_V(8); PG8_WAIT_L(0); PG8_BAR; PG8_MMA(1, 0, At, B0); PG8_MMA(1, 1, At, B1); PG8_BAR; PG8_SCHED;
;         }
	v_add_u32_e32 v160, s45, v146
	ds_read_b128 v[148:151], v160
	ds_read_b128 v[152:155], v160 offset:1024
	ds_read_b128 v[156:159], v160 offset:2048
	ds_read_b128 v[160:163], v160 offset:3072
	s_add_u32 s26, s26, 0x80000
	s_addc_u32 s27, s27, 0
	s_mov_b32 m0, s41
	v_lshl_add_u64 v[230:231], s[26:27], 0, v[18:19]
	ds_read_b128 v[180:183], v147 offset:32768
	ds_read_b128 v[184:187], v147 offset:33792
	ds_read_b128 v[188:191], v147 offset:34816
	ds_read_b128 v[192:195], v147 offset:35840
	ds_read_b128 v[210:213], v147 offset:36864
	ds_read_b128 v[214:217], v147 offset:37888
	ds_read_b128 v[218:221], v147 offset:38912
	ds_read_b128 v[222:225], v147 offset:39936
	global_load_lds_dwordx4 v[230:231], off
	v_lshl_add_u64 v[230:231], s[26:27], 0, v[134:135]
	s_mov_b32 m0, s42
	s_nop 0
	global_load_lds_dwordx4 v[230:231], off
	s_waitcnt vmcnt(6)
	s_waitcnt lgkmcnt(0)
	s_barrier
	s_setprio 1
	s_waitcnt lgkmcnt(0)
	v_mfma_f32_16x16x32_bf16 v[128:131], v[148:151], v[180:183], v[128:131]
	v_mfma_f32_16x16x32_bf16 v[124:127], v[156:159], v[180:183], v[124:127]
	v_mfma_f32_16x16x32_bf16 v[120:123], v[148:151], v[188:191], v[120:123]
	v_mfma_f32_16x16x32_bf16 v[116:119], v[156:159], v[188:191], v[116:119]
	v_mfma_f32_16x16x32_bf16 v[96:99], v[148:151], v[210:213], v[96:99]
	v_mfma_f32_16x16x32_bf16 v[92:95], v[156:159], v[210:213], v[92:95]
	v_mfma_f32_16x16x32_bf16 v[88:91], v[148:151], v[218:221], v[88:91]
	v_mfma_f32_16x16x32_bf16 v[84:87], v[156:159], v[218:221], v[84:87]
	v_mfma_f32_16x16x32_bf16 v[128:131], v[152:155], v[184:187], v[128:131]
	v_mfma_f32_16x16x32_bf16 v[124:127], v[160:163], v[184:187], v[124:127]
	v_mfma_f32_16x16x32_bf16 v[120:123], v[152:155], v[192:195], v[120:123]
	v_mfma_f32_16x16x32_bf16 v[116:119], v[160:163], v[192:195], v[116:119]
	v_mfma_f32_16x16x32_bf16 v[96:99], v[152:155], v[214:217], v[96:99]
	v_mfma_f32_16x16x32_bf16 v[92:95], v[160:163], v[214:217], v[92:95]
	v_mfma_f32_16x16x32_bf16 v[88:91], v[152:155], v[222:225], v[88:91]
	v_mfma_f32_16x16x32_bf16 v[84:87], v[160:163], v[222:225], v[84:87]
	s_setprio 0
	s_barrier
	s_mov_b32 m0, s46
	v_lshl_add_u64 v[198:199], v[198:199], 0, s[60:61]
	s_add_u32 s22, s22, 0x80080
	ds_read_b128 v[180:183], v147 offset:49152
	ds_read_b128 v[184:187], v147 offset:50176
	ds_read_b128 v[188:191], v147 offset:51200
	ds_read_b128 v[192:195], v147 offset:52224
	ds_read_b128 v[210:213], v147 offset:53248
	ds_read_b128 v[214:217], v147 offset:54272
	ds_read_b128 v[218:221], v147 offset:55296
	ds_read_b128 v[222:225], v147 offset:56320
	global_load_lds_dwordx4 v[198:199], off
	v_lshl_add_u64 v[198:199], v[200:201], 0, s[60:61]
	s_mov_b32 m0, s47
	s_addc_u32 s23, s23, 0
	global_load_lds_dwordx4 v[198:199], off
	v_lshl_add_u64 v[198:199], s[22:23], 0, v[132:133]
	v_lshl_add_u64 v[198:199], s[22:23], 0, v[136:137]
	v_lshl_add_u64 v[198:199], v[226:227], 0, s[60:61]
	s_mov_b32 m0, s48
	s_nop 0
	global_load_lds_dwordx4 v[198:199], off
	v_lshl_add_u64 v[198:199], v[228:229], 0, s[60:61]
	s_mov_b32 m0, s49
	s_nop 0
	global_load_lds_dwordx4 v[198:199], off
	s_waitcnt vmcnt(6)
	s_waitcnt lgkmcnt(0)
	s_barrier
	s_setprio 1
	s_waitcnt lgkmcnt(0)
	v_mfma_f32_16x16x32_bf16 v[64:67], v[148:151], v[180:183], v[64:67]
	v_mfma_f32_16x16x32_bf16 v[60:63], v[156:159], v[180:183], v[60:63]
	v_mfma_f32_16x16x32_bf16 v[56:59], v[148:151], v[188:191], v[56:59]
	v_mfma_f32_16x16x32_bf16 v[52:55], v[156:159], v[188:191], v[52:55]
	v_mfma_f32_16x16x32_bf16 v[32:35], v[148:151], v[210:213], v[32:35]
	v_mfma_f32_16x16x32_bf16 v[28:31], v[156:159], v[210:213], v[28:31]
	v_mfma_f32_16x16x32_bf16 v[24:27], v[148:151], v[218:221], v[24:27]
	v_mfma_f32_16x16x32_bf16 v[20:23], v[156:159], v[218:221], v[20:23]
	v_mfma_f32_16x16x32_bf16 v[64:67], v[152:155], v[184:187], v[64:67]
	v_mfma_f32_16x16x32_bf16 v[60:63], v[160:163], v[184:187], v[60:63]
	v_mfma_f32_16x16x32_bf16 v[56:59], v[152:155], v[192:195], v[56:59]
	v_mfma_f32_16x16x32_bf16 v[52:55], v[160:163], v[192:195], v[52:55]
	v_mfma_f32_16x16x32_bf16 v[32:35], v[152:155], v[214:217], v[32:35]
	v_mfma_f32_16x16x32_bf16 v[28:31], v[160:163], v[214:217], v[28:31]
	v_mfma_f32_16x16x32_bf16 v[24:27], v[152:155], v[222:225], v[24:27]
	v_mfma_f32_16x16x32_bf16 v[20:23], v[160:163], v[222:225], v[20:23]
	s_add_i32 s57, s57, 2
	s_add_u32 s2, s2, 0x100
	s_addc_u32 s3, s3, 0
	s_cmp_gt_u32 s57, 29
	s_setprio 0
	s_barrier
	s_cbranch_scc0 .LBB0_664
	s_cmpk_lt_u32 s30, 0x100
	s_cbranch_scc0 .LBB0_667
	s_barrier

; #define PG8_STAGE(bufoff, gbase, voff) do { _Pragma("unroll") for (int _i = 0; _i < 2; ++_i) \
;         __builtin_amdgcn_global_load_lds((const unsigned*)((const char*)(gbase) + (voff)[_i]), (LAS unsigned*)(lds + (bufoff) + ldsw + _i * 8192), 16, 0, 0); } while (0)
; #define PG8_LDA(dst, b, h) do { _Pragma("unroll") for (int m = 0; m < 4; ++m) _Pragma("unroll") for (int k = 0; k < 2; ++k) dst[m][k] = *(const LAS bf16x8*)(lds + PG8_SA(b, h) + aoff + m * 2048 + k * 1024); } while (0)
; #define PG8_LDB(dst, b, h) do { _Pragma("unroll") for (int n = 0; n < 2; ++n) _Pragma("unroll") for (int k = 0; k < 2; ++k) dst[n][k] = *(const LAS bf16x8*)(lds + PG8_SB(b, h) + boff + n * 2048 + k * 1024); } while (0)
; #define PG8_MMA(ai, bj, At, Bt) do { __builtin_amdgcn_s_setprio(1); _Pragma("unroll") for (int m = 0; m < 4; ++m) _Pragma("unroll") for (int n = 0; n < 2; ++n) _Pragma("unroll") for (int k = 0; k < 2; ++k) \
;         acc[ai][bj][m][n] = __builtin_amdgcn_mfma_f32_16x16x32_bf16(Bt[n][k], At[m][k], acc[ai][bj][m][n], 0, 0, 0); __builtin_amdgcn_s_setprio(0); } while (0)
; #define PG8_WAIT_V(n) asm volatile("s_waitcnt vmcnt(" #n ")" ::: "memory")
; #define PG8_WAIT_L(n) asm volatile("s_waitcnt lgkmcnt(" #n ")" ::: "memory")
; #define PG8_BAR __builtin_amdgcn_s_barrier()
; #define PG8_SCHED __builtin_amdgcn_sched_barrier(0)
; template <class Epi, class Sched, bool ALIGN_EPI>
; DI void gemm_phase(LAS unsigned char* lds, const Gemm g, const Sched& Sc, const Epi& E, const int tid) {
;     ...
;             const bool last = (t == nt - 2);
;             const char* a1 = cA + (size_t)(t + 1) * kstep;
;             const char* a2 = last ? nA : cA + (size_t)(t + 2) * kstep; const char* b2 = last ? nB : cB + (size_t)(t + 2) * kstep;
;             const char* a3 = a2 + kstep; const char* b3 = b2 + kstep;
;             PG8_LDB(B0, 0, 0); PG8_LDB(B1, 0, 1); PG8_SCHED; PG8_LDA(At, 0, 0); PG8_STAGE(PG8_SA(1, 1), a1 + hA, voffA);
;             PG8_WAIT_V(8); PG8_WAIT_L(0); PG8_BAR; PG8_MMA(0, 0, At, B0); PG8_MMA(0, 1, At, B1); PG8_BAR; PG8_SCHED;
.LBB0_771:
	v_add_u32_e32 v149, s13, v147
	ds_read_b128 v[150:153], v149
	ds_read_b128 v[154:157], v149 offset:1024
	ds_read_b128 v[158:161], v149 offset:2048
	ds_read_b128 v[162:165], v149 offset:3072
	v_add_u32_e32 v149, s54, v147
	s_add_u32 s42, s16, s2
	ds_read_b128 v[168:171], v149
	ds_read_b128 v[174:177], v149 offset:1024
	ds_read_b128 v[178:181], v149 offset:2048
	ds_read_b128 v[182:185], v149 offset:3072
	s_addc_u32 s43, s17, s3
	s_add_u32 s42, s42, 0x100
	s_addc_u32 s43, s43, 0
	s_add_u32 s82, s77, s2
	s_addc_u32 s83, s78, s3
	s_cmpk_eq_i32 s2, 0x300
	s_cselect_b32 s45, s23, s43
	s_cselect_b32 s44, s79, s42
	s_cselect_b32 s43, s19, s83
	s_cselect_b32 s42, s80, s82
	v_lshl_add_u64 v[194:195], v[144:145], 0, s[2:3]
	s_add_i32 m0, s57, 0xc000
	ds_read_b128 v[186:189], v148
	ds_read_b128 v[190:193], v148 offset:1024
	ds_read_b128 v[210:213], v148 offset:2048
	ds_read_b128 v[214:217], v148 offset:3072
	ds_read_b128 v[218:221], v148 offset:4096
	ds_read_b128 v[222:225], v148 offset:5120
	ds_read_b128 v[226:229], v148 offset:6144
	ds_read_b128 v[240:243], v148 offset:7168
	global_load_lds_dwordx4 v[194:195], off
	v_lshl_add_u64 v[194:195], v[142:143], 0, s[2:3]
	s_add_i32 m0, s57, 0xe000
	s_nop 0
	global_load_lds_dwordx4 v[194:195], off
	s_waitcnt vmcnt(8)
	s_waitcnt lgkmcnt(0)
	s_barrier
	s_setprio 1
	s_waitcnt lgkmcnt(0)
	v_mfma_f32_16x16x32_bf16 v[128:131], v[150:153], v[186:189], v[128:131]
	v_mfma_f32_16x16x32_bf16 v[124:127], v[158:161], v[186:189], v[124:127]
	v_mfma_f32_16x16x32_bf16 v[112:115], v[150:153], v[210:213], v[112:115]
	v_mfma_f32_16x16x32_bf16 v[108:111], v[158:161], v[210:213], v[108:111]
	v_mfma_f32_16x16x32_bf16 v[96:99], v[150:153], v[218:221], v[96:99]
	v_mfma_f32_16x16x32_bf16 v[92:95], v[158:161], v[218:221], v[92:95]
	v_mfma_f32_16x16x32_bf16 v[80:83], v[150:153], v[226:229], v[80:83]
	v_mfma_f32_16x16x32_bf16 v[76:79], v[158:161], v[226:229], v[76:79]
	v_mfma_f32_16x16x32_bf16 v[128:131], v[154:157], v[190:193], v[128:131]
	v_mfma_f32_16x16x32_bf16 v[124:127], v[162:165], v[190:193], v[124:127]
	v_mfma_f32_16x16x32_bf16 v[112:115], v[154:157], v[214:217], v[112:115]
	v_mfma_f32_16x16x32_bf16 v[108:111], v[162:165], v[214:217], v[108:111]
	v_mfma_f32_16x16x32_bf16 v[96:99], v[154:157], v[222:225], v[96:99]
	v_mfma_f32_16x16x32_bf16 v[92:95], v[162:165], v[222:225], v[92:95]
	v_mfma_f32_16x16x32_bf16 v[80:83], v[154:157], v[240:243], v[80:83]
	v_mfma_f32_16x16x32_bf16 v[76:79], v[162:165], v[240:243], v[76:79]
	s_setprio 0
	s_setprio 1
	v_mfma_f32_16x16x32_bf16 v[120:123], v[168:171], v[186:189], v[120:123]
	v_mfma_f32_16x16x32_bf16 v[116:119], v[178:181], v[186:189], v[116:119]
	v_mfma_f32_16x16x32_bf16 v[104:107], v[168:171], v[210:213], v[104:107]
	v_mfma_f32_16x16x32_bf16 v[100:103], v[178:181], v[210:213], v[100:103]
	v_mfma_f32_16x16x32_bf16 v[88:91], v[168:171], v[218:221], v[88:91]
	v_mfma_f32_16x16x32_bf16 v[84:87], v[178:181], v[218:221], v[84:87]
	v_mfma_f32_16x16x32_bf16 v[72:75], v[168:171], v[226:229], v[72:75]
	v_mfma_f32_16x16x32_bf16 v[68:71], v[178:181], v[226:229], v[68:71]
	v_mfma_f32_16x16x32_bf16 v[120:123], v[174:177], v[190:193], v[120:123]
	v_mfma_f32_16x16x32_bf16 v[116:119], v[182:185], v[190:193], v[116:119]
	v_mfma_f32_16x16x32_bf16 v[104:107], v[174:177], v[214:217], v[104:107]
	v_mfma_f32_16x16x32_bf16 v[100:103], v[182:185], v[214:217], v[100:103]
	v_mfma_f32_16x16x32_bf16 v[88:91], v[174:177], v[222:225], v[88:91]
	v_mfma_f32_16x16x32_bf16 v[84:87], v[182:185], v[222:225], v[84:87]
	v_mfma_f32_16x16x32_bf16 v[72:75], v[174:177], v[240:243], v[72:75]
	v_mfma_f32_16x16x32_bf16 v[68:71], v[182:185], v[240:243], v[68:71]
	s_setprio 0
	s_barrier
	s_mov_b32 m0, s52
	v_lshl_add_u64 v[194:195], s[42:43], 0, v[18:19]
	s_add_u32 s82, s42, 0x20000
	ds_read_b128 v[186:189], v148 offset:16384
	ds_read_b128 v[190:193], v148 offset:17408
	ds_read_b128 v[210:213], v148 offset:18432
	ds_read_b128 v[214:217], v148 offset:19456
	ds_read_b128 v[218:221], v148 offset:20480
	ds_read_b128 v[222:225], v148 offset:21504
	ds_read_b128 v[226:229], v148 offset:22528
	ds_read_b128 v[240:243], v148 offset:23552
	global_load_lds_dwordx4 v[194:195], off
	v_lshl_add_u64 v[198:199], s[42:43], 0, v[136:137]
	s_mov_b32 m0, s53
	s_addc_u32 s83, s43, 0
	global_load_lds_dwordx4 v[198:199], off
	v_lshl_add_u64 v[200:201], s[82:83], 0, v[18:19]
	s_mov_b32 m0, s55
	v_lshl_add_u64 v[230:231], s[44:45], 0, v[134:135]
	global_load_lds_dwordx4 v[200:201], off
	v_lshl_add_u64 v[200:201], s[82:83], 0, v[136:137]
	s_mov_b32 m0, s56
	s_nop 0
	global_load_lds_dwordx4 v[200:201], off
	v_lshl_add_u64 v[200:201], s[44:45], 0, v[132:133]
	s_mov_b32 m0, s57
	s_nop 0
	global_load_lds_dwordx4 v[200:201], off
	s_mov_b32 m0, s62
	s_nop 0
	global_load_lds_dwordx4 v[230:231], off
	s_waitcnt vmcnt(8)
	s_waitcnt lgkmcnt(0)
	s_barrier
; #define PG8_STAGE(bufoff, gbase, voff) do { _Pragma("unroll") for (int _i = 0; _i < 2; ++_i) \
;         __builtin_amdgcn_global_load_lds((const unsigned*)((const char*)(gbase) + (voff)[_i]), (LAS unsigned*)(lds + (bufoff) + ldsw + _i * 8192), 16, 0, 0); } while (0)
; #define PG8_LDA(dst, b, h) do { _Pragma("unroll") for (int m = 0; m < 4; ++m) _Pragma("unroll") for (int k = 0; k < 2; ++k) dst[m][k] = *(const LAS bf16x8*)(lds + PG8_SA(b, h) + aoff + m * 2048 + k * 1024); } while (0)
; #define PG8_LDB(dst, b, h) do { _Pragma("unroll") for (int n = 0; n < 2; ++n) _Pragma("unroll") for (int k = 0; k < 2; ++k) dst[n][k] = *(const LAS bf16x8*)(lds + PG8_SB(b, h) + boff + n * 2048 + k * 1024); } while (0)
; #define PG8_MMA(ai, bj, At, Bt) do { __builtin_amdgcn_s_setprio(1); _Pragma("unroll") for (int m = 0; m < 4; ++m) _Pragma("unroll") for (int n = 0; n < 2; ++n) _Pragma("unroll") for (int k = 0; k < 2; ++k) \
;         acc[ai][bj][m][n] = __builtin_amdgcn_mfma_f32_16x16x32_bf16(Bt[n][k], At[m][k], acc[ai][bj][m][n], 0, 0, 0); __builtin_amdgcn_s_setprio(0); } while (0)
; #define PG8_WAIT_V(n) asm volatile("s_waitcnt vmcnt(" #n ")" ::: "memory")
; #define PG8_WAIT_L(n) asm volatile("s_waitcnt lgkmcnt(" #n ")" ::: "memory")
; #define PG8_BAR __builtin_amdgcn_s_barrier()
; #define PG8_SCHED __builtin_amdgcn_sched_barrier(0)
; template <class Epi, class Sched, bool ALIGN_EPI>
; DI void gemm_phase(LAS unsigned char* lds, const Gemm g, const Sched& Sc, const Epi& E, const int tid) {
;     ...
;             PG8_LDA(At, 0, 1); PG8_STAGE(PG8_SB(0, 0), b2, voffB); PG8_STAGE(PG8_SB(0, 1), b2 + hB, voffB); PG8_STAGE(PG8_SA(0, 0), a2, voffA);
;             PG8_WAIT_V(8); PG8_WAIT_L(0); PG8_BAR; PG8_MMA(1, 0, At, B0); PG8_MMA(1, 1, At, B1); PG8_BAR; PG8_SCHED;
;             PG8_LDB(B0, 1, 0); PG8_LDB(B1, 1, 1); PG8_SCHED; PG8_LDA(At, 1, 0); PG8_STAGE(PG8_SA(0, 1), a2 + hA, voffA);
;             PG8_WAIT_V(8); PG8_WAIT_L(0); PG8_BAR; PG8_MMA(0, 0, At, B0); PG8_MMA(0, 1, At, B1); PG8_BAR; PG8_SCHED;
	s_setprio 1
	s_waitcnt lgkmcnt(0)
	v_mfma_f32_16x16x32_bf16 v[64:67], v[150:153], v[186:189], v[64:67]
	v_mfma_f32_16x16x32_bf16 v[60:63], v[158:161], v[186:189], v[60:63]
	v_mfma_f32_16x16x32_bf16 v[48:51], v[150:153], v[210:213], v[48:51]
	v_mfma_f32_16x16x32_bf16 v[44:47], v[158:161], v[210:213], v[44:47]
	v_mfma_f32_16x16x32_bf16 v[32:35], v[150:153], v[218:221], v[32:35]
	v_mfma_f32_16x16x32_bf16 v[28:31], v[158:161], v[218:221], v[28:31]
	v_mfma_f32_16x16x32_bf16 v[14:17], v[150:153], v[226:229], v[14:17]
	v_mfma_f32_16x16x32_bf16 v[10:13], v[158:161], v[226:229], v[10:13]
	v_mfma_f32_16x16x32_bf16 v[64:67], v[154:157], v[190:193], v[64:67]
	v_mfma_f32_16x16x32_bf16 v[60:63], v[162:165], v[190:193], v[60:63]
	v_mfma_f32_16x16x32_bf16 v[48:51], v[154:157], v[214:217], v[48:51]
	v_mfma_f32_16x16x32_bf16 v[44:47], v[162:165], v[214:217], v[44:47]
	v_mfma_f32_16x16x32_bf16 v[32:35], v[154:157], v[222:225], v[32:35]
	v_mfma_f32_16x16x32_bf16 v[28:31], v[162:165], v[222:225], v[28:31]
	v_mfma_f32_16x16x32_bf16 v[14:17], v[154:157], v[240:243], v[14:17]
	v_mfma_f32_16x16x32_bf16 v[10:13], v[162:165], v[240:243], v[10:13]
	s_setprio 0
	s_setprio 1
	v_mfma_f32_16x16x32_bf16 v[56:59], v[168:171], v[186:189], v[56:59]
	v_mfma_f32_16x16x32_bf16 v[52:55], v[178:181], v[186:189], v[52:55]
	v_mfma_f32_16x16x32_bf16 v[40:43], v[168:171], v[210:213], v[40:43]
	v_mfma_f32_16x16x32_bf16 v[36:39], v[178:181], v[210:213], v[36:39]
	v_mfma_f32_16x16x32_bf16 v[24:27], v[168:171], v[218:221], v[24:27]
	v_mfma_f32_16x16x32_bf16 v[20:23], v[178:181], v[218:221], v[20:23]
	v_mfma_f32_16x16x32_bf16 v[6:9], v[168:171], v[226:229], v[6:9]
	v_mfma_f32_16x16x32_bf16 v[2:5], v[178:181], v[226:229], v[2:5]
	v_mfma_f32_16x16x32_bf16 v[56:59], v[174:177], v[190:193], v[56:59]
	v_mfma_f32_16x16x32_bf16 v[52:55], v[182:185], v[190:193], v[52:55]
	v_mfma_f32_16x16x32_bf16 v[40:43], v[174:177], v[214:217], v[40:43]
	v_mfma_f32_16x16x32_bf16 v[36:39], v[182:185], v[214:217], v[36:39]
	v_mfma_f32_16x16x32_bf16 v[24:27], v[174:177], v[222:225], v[24:27]
	v_mfma_f32_16x16x32_bf16 v[20:23], v[182:185], v[222:225], v[20:23]
	v_mfma_f32_16x16x32_bf16 v[6:9], v[174:177], v[240:243], v[6:9]
	v_mfma_f32_16x16x32_bf16 v[2:5], v[182:185], v[240:243], v[2:5]
	s_setprio 0
	s_barrier
	v_add_u32_e32 v149, s66, v147
	ds_read_b128 v[150:153], v149
	ds_read_b128 v[154:157], v149 offset:1024
	ds_read_b128 v[158:161], v149 offset:2048
	ds_read_b128 v[162:165], v149 offset:3072
	v_add_u32_e32 v149, s71, v147
	ds_read_b128 v[168:171], v149
	ds_read_b128 v[174:177], v149 offset:1024
	ds_read_b128 v[178:181], v149 offset:2048
	ds_read_b128 v[182:185], v149 offset:3072
	s_add_u32 s44, s44, 0x20000
	s_addc_u32 s45, s45, 0
	s_mov_b32 m0, s63
	v_lshl_add_u64 v[232:233], s[44:45], 0, v[132:133]
	ds_read_b128 v[186:189], v148 offset:32768
	ds_read_b128 v[190:193], v148 offset:33792
	ds_read_b128 v[210:213], v148 offset:34816
	ds_read_b128 v[214:217], v148 offset:35840
	ds_read_b128 v[218:221], v148 offset:36864
	ds_read_b128 v[222:225], v148 offset:37888
	ds_read_b128 v[226:229], v148 offset:38912
	ds_read_b128 v[240:243], v148 offset:39936
	global_load_lds_dwordx4 v[232:233], off
	v_lshl_add_u64 v[232:233], s[44:45], 0, v[134:135]
	s_mov_b32 m0, s64
	s_nop 0
	global_load_lds_dwordx4 v[232:233], off
	s_waitcnt vmcnt(8)
	s_waitcnt lgkmcnt(0)
	s_barrier
	s_setprio 1
	s_waitcnt lgkmcnt(0)
	v_mfma_f32_16x16x32_bf16 v[128:131], v[150:153], v[186:189], v[128:131]
	v_mfma_f32_16x16x32_bf16 v[124:127], v[158:161], v[186:189], v[124:127]
	v_mfma_f32_16x16x32_bf16 v[112:115], v[150:153], v[210:213], v[112:115]
	v_mfma_f32_16x16x32_bf16 v[108:111], v[158:161], v[210:213], v[108:111]
	v_mfma_f32_16x16x32_bf16 v[96:99], v[150:153], v[218:221], v[96:99]
	v_mfma_f32_16x16x32_bf16 v[92:95], v[158:161], v[218:221], v[92:95]
	v_mfma_f32_16x16x32_bf16 v[80:83], v[150:153], v[226:229], v[80:83]
	v_mfma_f32_16x16x32_bf16 v[76:79], v[158:161], v[226:229], v[76:79]
	v_mfma_f32_16x16x32_bf16 v[128:131], v[154:157], v[190:193], v[128:131]
	v_mfma_f32_16x16x32_bf16 v[124:127], v[162:165], v[190:193], v[124:127]
	v_mfma_f32_16x16x32_bf16 v[112:115], v[154:157], v[214:217], v[112:115]
	v_mfma_f32_16x16x32_bf16 v[108:111], v[162:165], v[214:217], v[108:111]
	v_mfma_f32_16x16x32_bf16 v[96:99], v[154:157], v[222:225], v[96:99]
	v_mfma_f32_16x16x32_bf16 v[92:95], v[162:165], v[222:225], v[92:95]
	v_mfma_f32_16x16x32_bf16 v[80:83], v[154:157], v[240:243], v[80:83]
	v_mfma_f32_16x16x32_bf16 v[76:79], v[162:165], v[240:243], v[76:79]
	s_setprio 0
	s_setprio 1
	v_mfma_f32_16x16x32_bf16 v[120:123], v[168:171], v[186:189], v[120:123]
	v_mfma_f32_16x16x32_bf16 v[116:119], v[178:181], v[186:189], v[116:119]
	v_mfma_f32_16x16x32_bf16 v[104:107], v[168:171], v[210:213], v[104:107]
	v_mfma_f32_16x16x32_bf16 v[100:103], v[178:181], v[210:213], v[100:103]
	v_mfma_f32_16x16x32_bf16 v[88:91], v[168:171], v[218:221], v[88:91]
	v_mfma_f32_16x16x32_bf16 v[84:87], v[178:181], v[218:221], v[84:87]
	v_mfma_f32_16x16x32_bf16 v[72:75], v[168:171], v[226:229], v[72:75]
	v_mfma_f32_16x16x32_bf16 v[68:71], v[178:181], v[226:229], v[68:71]
	v_mfma_f32_16x16x32_bf16 v[120:123], v[174:177], v[190:193], v[120:123]
	v_mfma_f32_16x16x32_bf16 v[116:119], v[182:185], v[190:193], v[116:119]
	v_mfma_f32_16x16x32_bf16 v[104:107], v[174:177], v[214:217], v[104:107]
	v_mfma_f32_16x16x32_bf16 v[100:103], v[182:185], v[214:217], v[100:103]
	v_mfma_f32_16x16x32_bf16 v[88:91], v[174:177], v[222:225], v[88:91]
	v_mfma_f32_16x16x32_bf16 v[84:87], v[182:185], v[222:225], v[84:87]
	v_mfma_f32_16x16x32_bf16 v[72:75], v[174:177], v[240:243], v[72:75]
	v_mfma_f32_16x16x32_bf16 v[68:71], v[182:185], v[240:243], v[68:71]
	s_setprio 0
	s_barrier
; #define PG8_STAGE(bufoff, gbase, voff) do { _Pragma("unroll") for (int _i = 0; _i < 2; ++_i) \
;         __builtin_amdgcn_global_load_lds((const unsigned*)((const char*)(gbase) + (voff)[_i]), (LAS unsigned*)(lds + (bufoff) + ldsw + _i * 8192), 16, 0, 0); } while (0)
; #define PG8_LDA(dst, b, h) do { _Pragma("unroll") for (int m = 0; m < 4; ++m) _Pragma("unroll") for (int k = 0; k < 2; ++k) dst[m][k] = *(const LAS bf16x8*)(lds + PG8_SA(b, h) + aoff + m * 2048 + k * 1024); } while (0)
; #define PG8_MMA(ai, bj, At, Bt) do { __builtin_amdgcn_s_setprio(1); _Pragma("unroll") for (int m = 0; m < 4; ++m) _Pragma("unroll") for (int n = 0; n < 2; ++n) _Pragma("unroll") for (int k = 0; k < 2; ++k) \
;         acc[ai][bj][m][n] = __builtin_amdgcn_mfma_f32_16x16x32_bf16(Bt[n][k], At[m][k], acc[ai][bj][m][n], 0, 0, 0); __builtin_amdgcn_s_setprio(0); } while (0)
; #define PG8_WAIT_V(n) asm volatile("s_waitcnt vmcnt(" #n ")" ::: "memory")
; #define PG8_WAIT_L(n) asm volatile("s_waitcnt lgkmcnt(" #n ")" ::: "memory")
; #define PG8_BAR __builtin_amdgcn_s_barrier()
; #define PG8_SCHED __builtin_amdgcn_sched_barrier(0)
; template <class Epi, class Sched, bool ALIGN_EPI>
; DI void gemm_phase(LAS unsigned char* lds, const Gemm g, const Sched& Sc, const Epi& E, const int tid) {
;     ...
;             PG8_LDA(At, 1, 1); PG8_STAGE(PG8_SB(1, 0), b3, voffB); PG8_STAGE(PG8_SB(1, 1), b3 + hB, voffB); PG8_STAGE(PG8_SA(1, 0), a3, voffA);
;             PG8_WAIT_V(8); PG8_WAIT_L(0); PG8_BAR; PG8_MMA(1, 0, At, B0); PG8_MMA(1, 1, At, B1); PG8_BAR; PG8_SCHED;
;     ...
;         if (zero) {
; #pragma unroll
;         for (int a = 0; a < 2; ++a)
; #pragma unroll
;             for (int b = 0; b < 2; ++b)
; #pragma unroll
;                 for (int m = 0; m < 4; ++m)
; #pragma unroll
;                     for (int n = 0; n < 2; ++n) acc[a][b][m][n] = (f32x4){0.f, 0.f, 0.f, 0.f};
;         }
;         cur = nxt; cA = nA; cB = nB; ++ui;
	s_mov_b32 m0, s67
	v_lshl_add_u64 v[194:195], v[194:195], 0, s[60:61]
	s_add_u32 s42, s42, 0x20080
	ds_read_b128 v[186:189], v148 offset:49152
	ds_read_b128 v[190:193], v148 offset:50176
	ds_read_b128 v[210:213], v148 offset:51200
	ds_read_b128 v[214:217], v148 offset:52224
	ds_read_b128 v[218:221], v148 offset:53248
	ds_read_b128 v[222:225], v148 offset:54272
	ds_read_b128 v[226:229], v148 offset:55296
	ds_read_b128 v[240:243], v148 offset:56320
	global_load_lds_dwordx4 v[194:195], off
	v_lshl_add_u64 v[194:195], v[198:199], 0, s[60:61]
	s_mov_b32 m0, s68
	s_addc_u32 s43, s43, 0
	global_load_lds_dwordx4 v[194:195], off
	v_lshl_add_u64 v[194:195], s[42:43], 0, v[18:19]
	s_mov_b32 m0, s72
	s_nop 0
	global_load_lds_dwordx4 v[194:195], off
	v_lshl_add_u64 v[194:195], s[42:43], 0, v[136:137]
	s_mov_b32 m0, s73
	s_nop 0
	global_load_lds_dwordx4 v[194:195], off
	v_lshl_add_u64 v[194:195], v[200:201], 0, s[60:61]
	s_mov_b32 m0, s69
	s_nop 0
	global_load_lds_dwordx4 v[194:195], off
	v_lshl_add_u64 v[194:195], v[230:231], 0, s[60:61]
	s_mov_b32 m0, s70
	s_nop 0
	global_load_lds_dwordx4 v[194:195], off
	s_waitcnt vmcnt(8)
	s_waitcnt lgkmcnt(0)
	s_barrier
	s_setprio 1
	s_waitcnt lgkmcnt(0)
	v_mfma_f32_16x16x32_bf16 v[64:67], v[150:153], v[186:189], v[64:67]
	v_mfma_f32_16x16x32_bf16 v[60:63], v[158:161], v[186:189], v[60:63]
	v_mfma_f32_16x16x32_bf16 v[48:51], v[150:153], v[210:213], v[48:51]
	v_mfma_f32_16x16x32_bf16 v[44:47], v[158:161], v[210:213], v[44:47]
	v_mfma_f32_16x16x32_bf16 v[32:35], v[150:153], v[218:221], v[32:35]
	v_mfma_f32_16x16x32_bf16 v[28:31], v[158:161], v[218:221], v[28:31]
	v_mfma_f32_16x16x32_bf16 v[14:17], v[150:153], v[226:229], v[14:17]
	v_mfma_f32_16x16x32_bf16 v[10:13], v[158:161], v[226:229], v[10:13]
	v_mfma_f32_16x16x32_bf16 v[64:67], v[154:157], v[190:193], v[64:67]
	v_mfma_f32_16x16x32_bf16 v[60:63], v[162:165], v[190:193], v[60:63]
	v_mfma_f32_16x16x32_bf16 v[48:51], v[154:157], v[214:217], v[48:51]
	v_mfma_f32_16x16x32_bf16 v[44:47], v[162:165], v[214:217], v[44:47]
	v_mfma_f32_16x16x32_bf16 v[32:35], v[154:157], v[222:225], v[32:35]
	v_mfma_f32_16x16x32_bf16 v[28:31], v[162:165], v[222:225], v[28:31]
	v_mfma_f32_16x16x32_bf16 v[14:17], v[154:157], v[240:243], v[14:17]
	v_mfma_f32_16x16x32_bf16 v[10:13], v[162:165], v[240:243], v[10:13]
	s_setprio 0
	s_setprio 1
	v_mfma_f32_16x16x32_bf16 v[56:59], v[168:171], v[186:189], v[56:59]
	v_mfma_f32_16x16x32_bf16 v[52:55], v[178:181], v[186:189], v[52:55]
	v_mfma_f32_16x16x32_bf16 v[40:43], v[168:171], v[210:213], v[40:43]
	v_mfma_f32_16x16x32_bf16 v[36:39], v[178:181], v[210:213], v[36:39]
	v_mfma_f32_16x16x32_bf16 v[24:27], v[168:171], v[218:221], v[24:27]
	v_mfma_f32_16x16x32_bf16 v[20:23], v[178:181], v[218:221], v[20:23]
	v_mfma_f32_16x16x32_bf16 v[6:9], v[168:171], v[226:229], v[6:9]
	v_mfma_f32_16x16x32_bf16 v[2:5], v[178:181], v[226:229], v[2:5]
	v_mfma_f32_16x16x32_bf16 v[56:59], v[174:177], v[190:193], v[56:59]
	v_mfma_f32_16x16x32_bf16 v[52:55], v[182:185], v[190:193], v[52:55]
	v_mfma_f32_16x16x32_bf16 v[40:43], v[174:177], v[214:217], v[40:43]
	v_mfma_f32_16x16x32_bf16 v[36:39], v[182:185], v[214:217], v[36:39]
	v_mfma_f32_16x16x32_bf16 v[24:27], v[174:177], v[222:225], v[24:27]
	v_mfma_f32_16x16x32_bf16 v[20:23], v[182:185], v[222:225], v[20:23]
	v_mfma_f32_16x16x32_bf16 v[6:9], v[174:177], v[240:243], v[6:9]
	v_mfma_f32_16x16x32_bf16 v[2:5], v[182:185], v[240:243], v[2:5]
	s_add_i32 s81, s81, 2
	s_add_u32 s2, s2, 0x100
	s_addc_u32 s3, s3, 0
	s_cmp_gt_u32 s81, 5
	s_setprio 0
	s_barrier
	s_cbranch_scc0 .LBB0_771
	s_add_u32 s2, s77, 0xffffff00
	s_addc_u32 s3, s78, -1
	s_andn2_b64 vcc, exec, s[38:39]
	s_cbranch_vccnz .LBB0_774
	v_mov_b32_e32 v2, 0
	s_mov_b32 s20, s75
	s_mov_b32 s12, s22
	s_mov_b64 s[16:17], s[40:41]
	s_mov_b32 s74, s76
	v_mov_b32_e32 v3, v2
	v_mov_b32_e32 v4, v2
	v_mov_b32_e32 v5, v2
	v_mov_b32_e32 v6, v2
	v_mov_b32_e32 v7, v2
	v_mov_b32_e32 v8, v2
	v_mov_b32_e32 v9, v2
	v_mov_b32_e32 v20, v2
	v_mov_b32_e32 v21, v2
	v_mov_b32_e32 v22, v2
	v_mov_b32_e32 v23, v2
	v_mov_b32_e32 v24, v2
	v_mov_b32_e32 v25, v2
	v_mov_b32_e32 v26, v2
	v_mov_b32_e32 v27, v2
	v_mov_b32_e32 v36, v2
	v_mov_b32_e32 v37, v2
	v_mov_b32_e32 v38, v2
	v_mov_b32_e32 v39, v2
	v_mov_b32_e32 v40, v2
	v_mov_b32_e32 v41, v2
	v_mov_b32_e32 v42, v2
	v_mov_b32_e32 v43, v2
	v_mov_b32_e32 v52, v2
	v_mov_b32_e32 v53, v2
	v_mov_b32_e32 v54, v2
	v_mov_b32_e32 v55, v2
	v_mov_b32_e32 v56, v2
	v_mov_b32_e32 v57, v2
	v_mov_b32_e32 v58, v2
	v_mov_b32_e32 v59, v2
	v_mov_b32_e32 v10, v2
	v_mov_b32_e32 v11, v2
	v_mov_b32_e32 v12, v2
	v_mov_b32_e32 v13, v2
	v_mov_b32_e32 v14, v2
	v_mov_b32_e32 v15, v2
	v_mov_b32_e32 v16, v2
	v_mov_b32_e32 v17, v2
	v_mov_b32_e32 v28, v2
	v_mov_b32_e32 v29, v2
	v_mov_b32_e32 v30, v2
	v_mov_b32_e32 v31, v2
	v_mov_b32_e32 v32, v2
	v_mov_b32_e32 v33, v2
	v_mov_b32_e32 v34, v2
	v_mov_b32_e32 v35, v2
	v_mov_b32_e32 v44, v2
	v_mov_b32_e32 v45, v2
	v_mov_b32_e32 v46, v2
	v_mov_b32_e32 v47, v2
	v_mov_b32_e32 v48, v2
	v_mov_b32_e32 v49, v2
	v_mov_b32_e32 v50, v2
	v_mov_b32_e32 v51, v2
	v_mov_b32_e32 v60, v2
	v_mov_b32_e32 v61, v2
	v_mov_b32_e32 v62, v2
	v_mov_b32_e32 v63, v2
	v_mov_b32_e32 v64, v2
	v_mov_b32_e32 v65, v2
	v_mov_b32_e32 v66, v2
	v_mov_b32_e32 v67, v2
	v_mov_b32_e32 v68, v2
	v_mov_b32_e32 v69, v2
	v_mov_b32_e32 v70, v2
	v_mov_b32_e32 v71, v2
	v_mov_b32_e32 v72, v2
	v_mov_b32_e32 v73, v2
	v_mov_b32_e32 v74, v2
	v_mov_b32_e32 v75, v2
	v_mov_b32_e32 v84, v2
	v_mov_b32_e32 v85, v2
	v_mov_b32_e32 v86, v2
	v_mov_b32_e32 v87, v2
	v_mov_b32_e32 v88, v2
	v_mov_b32_e32 v89, v2
	v_mov_b32_e32 v90, v2
	v_mov_b32_e32 v91, v2
	v_mov_b32_e32 v100, v2
	v_mov_b32_e32 v101, v2
	v_mov_b32_e32 v102, v2
	v_mov_b32_e32 v103, v2
	v_mov_b32_e32 v104, v2
	v_mov_b32_e32 v105, v2
	v_mov_b32_e32 v106, v2
	v_mov_b32_e32 v107, v2
	v_mov_b32_e32 v116, v2
	v_mov_b32_e32 v117, v2
	v_mov_b32_e32 v118, v2
	v_mov_b32_e32 v119, v2
	v_mov_b32_e32 v120, v2
	v_mov_b32_e32 v121, v2
	v_mov_b32_e32 v122, v2
	v_mov_b32_e32 v123, v2
	v_mov_b32_e32 v76, v2
	v_mov_b32_e32 v77, v2
	v_mov_b32_e32 v78, v2
	v_mov_b32_e32 v79, v2
	v_mov_b32_e32 v80, v2
	v_mov_b32_e32 v81, v2
	v_mov_b32_e32 v82, v2
	v_mov_b32_e32 v83, v2
	v_mov_b32_e32 v92, v2
	v_mov_b32_e32 v93, v2
	v_mov_b32_e32 v94, v2
	v_mov_b32_e32 v95, v2
	v_mov_b32_e32 v96, v2
	v_mov_b32_e32 v97, v2
	v_mov_b32_e32 v98, v2
	v_mov_b32_e32 v99, v2
	v_mov_b32_e32 v108, v2
	v_mov_b32_e32 v109, v2
	v_mov_b32_e32 v110, v2
	v_mov_b32_e32 v111, v2
	v_mov_b32_e32 v112, v2
	v_mov_b32_e32 v113, v2
	v_mov_b32_e32 v114, v2
	v_mov_b32_e32 v115, v2
	v_mov_b32_e32 v124, v2
	v_mov_b32_e32 v125, v2
	v_mov_b32_e32 v126, v2
	v_mov_b32_e32 v127, v2
	v_mov_b32_e32 v128, v2
	v_mov_b32_e32 v129, v2
	v_mov_b32_e32 v130, v2
	v_mov_b32_e32 v131, v2
	s_branch .LBB0_775

; #define PG8_STAGE(bufoff, gbase, voff) do { _Pragma("unroll") for (int _i = 0; _i < 2; ++_i) \
;         __builtin_amdgcn_global_load_lds((const unsigned*)((const char*)(gbase) + (voff)[_i]), (LAS unsigned*)(lds + (bufoff) + ldsw + _i * 8192), 16, 0, 0); } while (0)
; #define PG8_LDA(dst, b, h) do { _Pragma("unroll") for (int m = 0; m < 4; ++m) _Pragma("unroll") for (int k = 0; k < 2; ++k) dst[m][k] = *(const LAS bf16x8*)(lds + PG8_SA(b, h) + aoff + m * 2048 + k * 1024); } while (0)
; #define PG8_LDB(dst, b, h) do { _Pragma("unroll") for (int n = 0; n < 2; ++n) _Pragma("unroll") for (int k = 0; k < 2; ++k) dst[n][k] = *(const LAS bf16x8*)(lds + PG8_SB(b, h) + boff + n * 2048 + k * 1024); } while (0)
; #define PG8_MMA(ai, bj, At, Bt) do { __builtin_amdgcn_s_setprio(1); _Pragma("unroll") for (int m = 0; m < 4; ++m) _Pragma("unroll") for (int n = 0; n < 2; ++n) _Pragma("unroll") for (int k = 0; k < 2; ++k) \
;         acc[ai][bj][m][n] = __builtin_amdgcn_mfma_f32_16x16x32_bf16(Bt[n][k], At[m][k], acc[ai][bj][m][n], 0, 0, 0); __builtin_amdgcn_s_setprio(0); } while (0)
; #define PG8_WAIT_V(n) asm volatile("s_waitcnt vmcnt(" #n ")" ::: "memory")
; #define PG8_WAIT_L(n) asm volatile("s_waitcnt lgkmcnt(" #n ")" ::: "memory")
; #define PG8_BAR __builtin_amdgcn_s_barrier()
; #define PG8_SCHED __builtin_amdgcn_sched_barrier(0)
; template <class Epi, class Sched, bool ALIGN_EPI>
; DI void gemm_phase(LAS unsigned char* lds, const Gemm g, const Sched& Sc, const Epi& E, const int tid) {
;     ...
;             const bool last = (t == nt - 2);
;             const char* a1 = cA + (size_t)(t + 1) * kstep;
;             const char* a2 = last ? nA : cA + (size_t)(t + 2) * kstep; const char* b2 = last ? nB : cB + (size_t)(t + 2) * kstep;
;             const char* a3 = a2 + kstep; const char* b3 = b2 + kstep;
;             PG8_LDB(B0, 0, 0); PG8_LDB(B1, 0, 1); PG8_SCHED; PG8_LDA(At, 0, 0); PG8_STAGE(PG8_SA(1, 1), a1 + hA, voffA);
;             PG8_WAIT_V(8); PG8_WAIT_L(0); PG8_BAR; PG8_MMA(0, 0, At, B0); PG8_MMA(0, 1, At, B1); PG8_BAR; PG8_SCHED;
.LBB0_914:
	v_add_u32_e32 v83, s48, v81
	ds_read_b128 v[84:87], v83
	ds_read_b128 v[88:91], v83 offset:1024
	ds_read_b128 v[92:95], v83 offset:2048
	ds_read_b128 v[96:99], v83 offset:3072
	s_add_u32 s44, s42, 0xfffe0080
	s_addc_u32 s45, s43, -1
	s_cmp_eq_u32 s72, 4
	s_cselect_b32 s47, s23, s45
	s_cselect_b32 s46, s31, s44
	s_cselect_b32 s45, s37, s71
	s_cselect_b32 s44, s69, s70
	v_lshl_add_u64 v[132:133], s[42:43], 0, v[78:79]
	s_add_i32 m0, s53, 0xc000
	ds_read_b128 v[100:103], v82
	ds_read_b128 v[104:107], v82 offset:1024
	ds_read_b128 v[108:111], v82 offset:2048
	ds_read_b128 v[112:115], v82 offset:3072
	ds_read_b128 v[116:119], v82 offset:4096
	ds_read_b128 v[120:123], v82 offset:5120
	ds_read_b128 v[124:127], v82 offset:6144
	ds_read_b128 v[128:131], v82 offset:7168
	global_load_lds_dwordx4 v[132:133], off
	v_lshl_add_u64 v[132:133], s[42:43], 0, v[76:77]
	s_add_i32 m0, s53, 0xe000
	s_nop 0
	global_load_lds_dwordx4 v[132:133], off
	s_waitcnt vmcnt(8)
	s_waitcnt lgkmcnt(0)
	s_barrier
	s_setprio 1
	s_waitcnt lgkmcnt(0)
	v_mfma_f32_16x16x32_bf16 v[64:67], v[84:87], v[100:103], v[64:67]
	v_mfma_f32_16x16x32_bf16 v[60:63], v[92:95], v[100:103], v[60:63]
	v_mfma_f32_16x16x32_bf16 v[56:59], v[84:87], v[108:111], v[56:59]
	v_mfma_f32_16x16x32_bf16 v[52:55], v[92:95], v[108:111], v[52:55]
	v_mfma_f32_16x16x32_bf16 v[48:51], v[84:87], v[116:119], v[48:51]
	v_mfma_f32_16x16x32_bf16 v[44:47], v[92:95], v[116:119], v[44:47]
	v_mfma_f32_16x16x32_bf16 v[40:43], v[84:87], v[124:127], v[40:43]
	v_mfma_f32_16x16x32_bf16 v[36:39], v[92:95], v[124:127], v[36:39]
	v_mfma_f32_16x16x32_bf16 v[64:67], v[88:91], v[104:107], v[64:67]
	v_mfma_f32_16x16x32_bf16 v[60:63], v[96:99], v[104:107], v[60:63]
	v_mfma_f32_16x16x32_bf16 v[56:59], v[88:91], v[112:115], v[56:59]
	v_mfma_f32_16x16x32_bf16 v[52:55], v[96:99], v[112:115], v[52:55]
	v_mfma_f32_16x16x32_bf16 v[48:51], v[88:91], v[120:123], v[48:51]
	v_mfma_f32_16x16x32_bf16 v[44:47], v[96:99], v[120:123], v[44:47]
	v_mfma_f32_16x16x32_bf16 v[40:43], v[88:91], v[128:131], v[40:43]
	v_mfma_f32_16x16x32_bf16 v[36:39], v[96:99], v[128:131], v[36:39]
	s_setprio 0
	s_setprio 1
	s_setprio 0
	s_barrier
	s_mov_b32 m0, s49
	v_lshl_add_u64 v[132:133], s[44:45], 0, v[70:71]
	s_add_u32 s74, s44, 0x20000
	ds_read_b128 v[100:103], v82 offset:16384
	ds_read_b128 v[104:107], v82 offset:17408
	ds_read_b128 v[108:111], v82 offset:18432
	ds_read_b128 v[112:115], v82 offset:19456
	ds_read_b128 v[116:119], v82 offset:20480
	ds_read_b128 v[120:123], v82 offset:21504
	ds_read_b128 v[124:127], v82 offset:22528
	ds_read_b128 v[128:131], v82 offset:23552
	global_load_lds_dwordx4 v[132:133], off
	v_lshl_add_u64 v[134:135], s[44:45], 0, v[74:75]
	s_mov_b32 m0, s50
	s_addc_u32 s75, s45, 0
	global_load_lds_dwordx4 v[134:135], off
	v_lshl_add_u64 v[136:137], s[74:75], 0, v[70:71]
	s_mov_b32 m0, s51
	v_lshl_add_u64 v[138:139], s[46:47], 0, v[72:73]
	global_load_lds_dwordx4 v[136:137], off
	v_lshl_add_u64 v[136:137], s[74:75], 0, v[74:75]
	s_mov_b32 m0, s52
	s_nop 0
	global_load_lds_dwordx4 v[136:137], off
	v_lshl_add_u64 v[136:137], s[46:47], 0, v[68:69]
	s_mov_b32 m0, s53
	s_nop 0
	global_load_lds_dwordx4 v[136:137], off
	s_mov_b32 m0, s54
	s_nop 0
	global_load_lds_dwordx4 v[138:139], off
	s_waitcnt vmcnt(8)
	s_waitcnt lgkmcnt(0)
	s_barrier
	s_setprio 1
	s_waitcnt lgkmcnt(0)
	v_mfma_f32_16x16x32_bf16 v[32:35], v[84:87], v[100:103], v[32:35]
	v_mfma_f32_16x16x32_bf16 v[28:31], v[92:95], v[100:103], v[28:31]
	v_mfma_f32_16x16x32_bf16 v[24:27], v[84:87], v[108:111], v[24:27]
	v_mfma_f32_16x16x32_bf16 v[20:23], v[92:95], v[108:111], v[20:23]
	v_mfma_f32_16x16x32_bf16 v[14:17], v[84:87], v[116:119], v[14:17]
	v_mfma_f32_16x16x32_bf16 v[10:13], v[92:95], v[116:119], v[10:13]
	v_mfma_f32_16x16x32_bf16 v[6:9], v[84:87], v[124:127], v[6:9]
	v_mfma_f32_16x16x32_bf16 v[2:5], v[92:95], v[124:127], v[2:5]
	v_mfma_f32_16x16x32_bf16 v[32:35], v[88:91], v[104:107], v[32:35]
	v_mfma_f32_16x16x32_bf16 v[28:31], v[96:99], v[104:107], v[28:31]
	v_mfma_f32_16x16x32_bf16 v[24:27], v[88:91], v[112:115], v[24:27]
	v_mfma_f32_16x16x32_bf16 v[20:23], v[96:99], v[112:115], v[20:23]
	v_mfma_f32_16x16x32_bf16 v[14:17], v[88:91], v[120:123], v[14:17]
	v_mfma_f32_16x16x32_bf16 v[10:13], v[96:99], v[120:123], v[10:13]
	v_mfma_f32_16x16x32_bf16 v[6:9], v[88:91], v[128:131], v[6:9]
	v_mfma_f32_16x16x32_bf16 v[2:5], v[96:99], v[128:131], v[2:5]
	s_setprio 0
	s_setprio 1
	s_setprio 0
	s_barrier
; #define PG8_STAGE(bufoff, gbase, voff) do { _Pragma("unroll") for (int _i = 0; _i < 2; ++_i) \
;         __builtin_amdgcn_global_load_lds((const unsigned*)((const char*)(gbase) + (voff)[_i]), (LAS unsigned*)(lds + (bufoff) + ldsw + _i * 8192), 16, 0, 0); } while (0)
; #define PG8_LDA(dst, b, h) do { _Pragma("unroll") for (int m = 0; m < 4; ++m) _Pragma("unroll") for (int k = 0; k < 2; ++k) dst[m][k] = *(const LAS bf16x8*)(lds + PG8_SA(b, h) + aoff + m * 2048 + k * 1024); } while (0)
; #define PG8_LDB(dst, b, h) do { _Pragma("unroll") for (int n = 0; n < 2; ++n) _Pragma("unroll") for (int k = 0; k < 2; ++k) dst[n][k] = *(const LAS bf16x8*)(lds + PG8_SB(b, h) + boff + n * 2048 + k * 1024); } while (0)
; #define PG8_MMA(ai, bj, At, Bt) do { __builtin_amdgcn_s_setprio(1); _Pragma("unroll") for (int m = 0; m < 4; ++m) _Pragma("unroll") for (int n = 0; n < 2; ++n) _Pragma("unroll") for (int k = 0; k < 2; ++k) \
;         acc[ai][bj][m][n] = __builtin_amdgcn_mfma_f32_16x16x32_bf16(Bt[n][k], At[m][k], acc[ai][bj][m][n], 0, 0, 0); __builtin_amdgcn_s_setprio(0); } while (0)
; #define PG8_WAIT_V(n) asm volatile("s_waitcnt vmcnt(" #n ")" ::: "memory")
; #define PG8_WAIT_L(n) asm volatile("s_waitcnt lgkmcnt(" #n ")" ::: "memory")
; #define PG8_BAR __builtin_amdgcn_s_barrier()
; #define PG8_SCHED __builtin_amdgcn_sched_barrier(0)
; template <class Epi, class Sched, bool ALIGN_EPI>
; DI void gemm_phase(LAS unsigned char* lds, const Gemm g, const Sched& Sc, const Epi& E, const int tid) {
;     ...
;             PG8_LDA(At, 0, 1); PG8_STAGE(PG8_SB(0, 0), b2, voffB); PG8_STAGE(PG8_SB(0, 1), b2 + hB, voffB); PG8_STAGE(PG8_SA(0, 0), a2, voffA);
;             PG8_WAIT_V(8); PG8_WAIT_L(0); PG8_BAR; PG8_MMA(1, 0, At, B0); PG8_MMA(1, 1, At, B1); PG8_BAR; PG8_SCHED;
;             PG8_LDB(B0, 1, 0); PG8_LDB(B1, 1, 1); PG8_SCHED; PG8_LDA(At, 1, 0); PG8_STAGE(PG8_SA(0, 1), a2 + hA, voffA);
;             PG8_WAIT_V(8); PG8_WAIT_L(0); PG8_BAR; PG8_MMA(0, 0, At, B0); PG8_MMA(0, 1, At, B1); PG8_BAR; PG8_SCHED;
;             PG8_LDA(At, 1, 1); PG8_STAGE(PG8_SB(1, 0), b3, voffB); PG8_STAGE(PG8_SB(1, 1), b3 + hB, voffB); PG8_STAGE(PG8_SA(1, 0), a3, voffA);
;             PG8_WAIT_V(8); PG8_WAIT_L(0); PG8_BAR; PG8_MMA(1, 0, At, B0); PG8_MMA(1, 1, At, B1); PG8_BAR; PG8_SCHED;
;         }
;         if constexpr (ALIGN_EPI) { if (wr == 0) PG8_BAR; }
	v_add_u32_e32 v83, s57, v81
	ds_read_b128 v[84:87], v83
	ds_read_b128 v[88:91], v83 offset:1024
	ds_read_b128 v[92:95], v83 offset:2048
	ds_read_b128 v[96:99], v83 offset:3072
	s_add_u32 s46, s46, 0x20000
	s_addc_u32 s47, s47, 0
	s_mov_b32 m0, s55
	v_lshl_add_u64 v[140:141], s[46:47], 0, v[68:69]
	ds_read_b128 v[100:103], v82 offset:32768
	ds_read_b128 v[104:107], v82 offset:33792
	ds_read_b128 v[108:111], v82 offset:34816
	ds_read_b128 v[112:115], v82 offset:35840
	ds_read_b128 v[116:119], v82 offset:36864
	ds_read_b128 v[120:123], v82 offset:37888
	ds_read_b128 v[124:127], v82 offset:38912
	ds_read_b128 v[128:131], v82 offset:39936
	global_load_lds_dwordx4 v[140:141], off
	v_lshl_add_u64 v[140:141], s[46:47], 0, v[72:73]
	s_mov_b32 m0, s56
	s_nop 0
	global_load_lds_dwordx4 v[140:141], off
	s_waitcnt vmcnt(8)
	s_waitcnt lgkmcnt(0)
	s_barrier
	s_setprio 1
	s_waitcnt lgkmcnt(0)
	v_mfma_f32_16x16x32_bf16 v[64:67], v[84:87], v[100:103], v[64:67]
	v_mfma_f32_16x16x32_bf16 v[60:63], v[92:95], v[100:103], v[60:63]
	v_mfma_f32_16x16x32_bf16 v[56:59], v[84:87], v[108:111], v[56:59]
	v_mfma_f32_16x16x32_bf16 v[52:55], v[92:95], v[108:111], v[52:55]
	v_mfma_f32_16x16x32_bf16 v[48:51], v[84:87], v[116:119], v[48:51]
	v_mfma_f32_16x16x32_bf16 v[44:47], v[92:95], v[116:119], v[44:47]
	v_mfma_f32_16x16x32_bf16 v[40:43], v[84:87], v[124:127], v[40:43]
	v_mfma_f32_16x16x32_bf16 v[36:39], v[92:95], v[124:127], v[36:39]
	v_mfma_f32_16x16x32_bf16 v[64:67], v[88:91], v[104:107], v[64:67]
	v_mfma_f32_16x16x32_bf16 v[60:63], v[96:99], v[104:107], v[60:63]
	v_mfma_f32_16x16x32_bf16 v[56:59], v[88:91], v[112:115], v[56:59]
	v_mfma_f32_16x16x32_bf16 v[52:55], v[96:99], v[112:115], v[52:55]
	v_mfma_f32_16x16x32_bf16 v[48:51], v[88:91], v[120:123], v[48:51]
	v_mfma_f32_16x16x32_bf16 v[44:47], v[96:99], v[120:123], v[44:47]
	v_mfma_f32_16x16x32_bf16 v[40:43], v[88:91], v[128:131], v[40:43]
	v_mfma_f32_16x16x32_bf16 v[36:39], v[96:99], v[128:131], v[36:39]
	s_setprio 0
	s_setprio 1
	s_setprio 0
	s_barrier
	s_mov_b32 m0, s62
	v_lshl_add_u64 v[132:133], v[132:133], 0, s[60:61]
	s_add_u32 s44, s44, 0x20080
	ds_read_b128 v[100:103], v82 offset:49152
	ds_read_b128 v[104:107], v82 offset:50176
	ds_read_b128 v[108:111], v82 offset:51200
	ds_read_b128 v[112:115], v82 offset:52224
	ds_read_b128 v[116:119], v82 offset:53248
	ds_read_b128 v[120:123], v82 offset:54272
	ds_read_b128 v[124:127], v82 offset:55296
	ds_read_b128 v[128:131], v82 offset:56320
	global_load_lds_dwordx4 v[132:133], off
	v_lshl_add_u64 v[132:133], v[134:135], 0, s[60:61]
	s_mov_b32 m0, s63
	s_addc_u32 s45, s45, 0
	global_load_lds_dwordx4 v[132:133], off
	v_lshl_add_u64 v[132:133], s[44:45], 0, v[70:71]
	s_mov_b32 m0, s66
	s_nop 0
	global_load_lds_dwordx4 v[132:133], off
	v_lshl_add_u64 v[132:133], s[44:45], 0, v[74:75]
	s_mov_b32 m0, s67
	s_nop 0
	global_load_lds_dwordx4 v[132:133], off
	v_lshl_add_u64 v[132:133], v[136:137], 0, s[60:61]
	s_mov_b32 m0, s64
	s_nop 0
	global_load_lds_dwordx4 v[132:133], off
	v_lshl_add_u64 v[132:133], v[138:139], 0, s[60:61]
	s_mov_b32 m0, s65
	s_nop 0
	global_load_lds_dwordx4 v[132:133], off
	s_waitcnt vmcnt(8)
	s_waitcnt lgkmcnt(0)
	s_barrier
	s_setprio 1
	s_waitcnt lgkmcnt(0)
	v_mfma_f32_16x16x32_bf16 v[32:35], v[84:87], v[100:103], v[32:35]
	v_mfma_f32_16x16x32_bf16 v[28:31], v[92:95], v[100:103], v[28:31]
	v_mfma_f32_16x16x32_bf16 v[24:27], v[84:87], v[108:111], v[24:27]
	v_mfma_f32_16x16x32_bf16 v[20:23], v[92:95], v[108:111], v[20:23]
	v_mfma_f32_16x16x32_bf16 v[14:17], v[84:87], v[116:119], v[14:17]
	v_mfma_f32_16x16x32_bf16 v[10:13], v[92:95], v[116:119], v[10:13]
	v_mfma_f32_16x16x32_bf16 v[6:9], v[84:87], v[124:127], v[6:9]
	v_mfma_f32_16x16x32_bf16 v[2:5], v[92:95], v[124:127], v[2:5]
	v_mfma_f32_16x16x32_bf16 v[32:35], v[88:91], v[104:107], v[32:35]
	v_mfma_f32_16x16x32_bf16 v[28:31], v[96:99], v[104:107], v[28:31]
	v_mfma_f32_16x16x32_bf16 v[24:27], v[88:91], v[112:115], v[24:27]
	v_mfma_f32_16x16x32_bf16 v[20:23], v[96:99], v[112:115], v[20:23]
	v_mfma_f32_16x16x32_bf16 v[14:17], v[88:91], v[120:123], v[14:17]
	v_mfma_f32_16x16x32_bf16 v[10:13], v[96:99], v[120:123], v[10:13]
	v_mfma_f32_16x16x32_bf16 v[6:9], v[88:91], v[128:131], v[6:9]
	v_mfma_f32_16x16x32_bf16 v[2:5], v[96:99], v[128:131], v[2:5]
	s_setprio 0
	s_setprio 1
	s_add_i32 s72, s72, 2
	s_add_u32 s70, s70, 0x100
	s_addc_u32 s71, s71, 0
	s_add_u32 s42, s42, 0x100
	s_addc_u32 s43, s43, 0
	s_cmp_gt_u32 s72, 5
	s_setprio 0
	s_barrier
	s_cbranch_scc0 .LBB0_914
	s_and_b64 vcc, exec, s[16:17]
	s_cbranch_vccz .LBB0_917
	s_barrier

; #define PG8_STAGE(bufoff, gbase, voff) do { _Pragma("unroll") for (int _i = 0; _i < 2; ++_i) \
;         __builtin_amdgcn_global_load_lds((const unsigned*)((const char*)(gbase) + (voff)[_i]), (LAS unsigned*)(lds + (bufoff) + ldsw + _i * 8192), 16, 0, 0); } while (0)
; #define PG8_LDA(dst, b, h) do { _Pragma("unroll") for (int m = 0; m < 4; ++m) _Pragma("unroll") for (int k = 0; k < 2; ++k) dst[m][k] = *(const LAS bf16x8*)(lds + PG8_SA(b, h) + aoff + m * 2048 + k * 1024); } while (0)
; #define PG8_LDB(dst, b, h) do { _Pragma("unroll") for (int n = 0; n < 2; ++n) _Pragma("unroll") for (int k = 0; k < 2; ++k) dst[n][k] = *(const LAS bf16x8*)(lds + PG8_SB(b, h) + boff + n * 2048 + k * 1024); } while (0)
; #define PG8_MMA(ai, bj, At, Bt) do { __builtin_amdgcn_s_setprio(1); _Pragma("unroll") for (int m = 0; m < 4; ++m) _Pragma("unroll") for (int n = 0; n < 2; ++n) _Pragma("unroll") for (int k = 0; k < 2; ++k) \
;         acc[ai][bj][m][n] = __builtin_amdgcn_mfma_f32_16x16x32_bf16(Bt[n][k], At[m][k], acc[ai][bj][m][n], 0, 0, 0); __builtin_amdgcn_s_setprio(0); } while (0)
; #define PG8_WAIT_V(n) asm volatile("s_waitcnt vmcnt(" #n ")" ::: "memory")
; #define PG8_WAIT_L(n) asm volatile("s_waitcnt lgkmcnt(" #n ")" ::: "memory")
; #define PG8_BAR __builtin_amdgcn_s_barrier()
; #define PG8_SCHED __builtin_amdgcn_sched_barrier(0)
; template <class Epi, class Sched, bool ALIGN_EPI>
; DI void gemm_phase(LAS unsigned char* lds, const Gemm g, const Sched& Sc, const Epi& E, const int tid) {
;     ...
;             const bool last = (t == nt - 2);
;             const char* a1 = cA + (size_t)(t + 1) * kstep;
;             const char* a2 = last ? nA : cA + (size_t)(t + 2) * kstep; const char* b2 = last ? nB : cB + (size_t)(t + 2) * kstep;
;             const char* a3 = a2 + kstep; const char* b3 = b2 + kstep;
;             PG8_LDB(B0, 0, 0); PG8_LDB(B1, 0, 1); PG8_SCHED; PG8_LDA(At, 0, 0); PG8_STAGE(PG8_SA(1, 1), a1 + hA, voffA);
;             PG8_WAIT_V(8); PG8_WAIT_L(0); PG8_BAR; PG8_MMA(0, 0, At, B0); PG8_MMA(0, 1, At, B1); PG8_BAR; PG8_SCHED;
.LBB0_995:
	v_add_u32_e32 v18, s76, v239
	ds_read_b128 v[132:135], v18
	ds_read_b128 v[136:139], v18 offset:1024
	ds_read_b128 v[140:143], v18 offset:2048
	ds_read_b128 v[144:147], v18 offset:3072
	v_add_u32_e32 v18, s79, v239
	ds_read_b128 v[148:151], v18
	ds_read_b128 v[152:155], v18 offset:1024
	ds_read_b128 v[156:159], v18 offset:2048
	ds_read_b128 v[160:163], v18 offset:3072
	s_add_u32 s22, s18, 0xfffe0080
	s_addc_u32 s23, s19, -1
	s_cmp_eq_u32 s52, 4
	s_cselect_b32 s31, s3, s23
	s_cselect_b32 s30, s13, s22
	s_cselect_b32 s23, s17, s39
	s_cselect_b32 s22, s25, s38
	v_lshl_add_u64 v[198:199], s[18:19], 0, v[190:191]
	s_add_i32 m0, s82, 0xc000
	ds_read_b128 v[164:167], v241
	ds_read_b128 v[168:171], v241 offset:1024
	ds_read_b128 v[172:175], v241 offset:2048
	ds_read_b128 v[176:179], v241 offset:3072
	ds_read_b128 v[192:195], v241 offset:4096
	ds_read_b128 v[210:213], v241 offset:5120
	ds_read_b128 v[214:217], v241 offset:6144
	ds_read_b128 v[218:221], v241 offset:7168
	global_load_lds_dwordx4 v[198:199], off
	v_lshl_add_u64 v[198:199], s[18:19], 0, v[188:189]
	s_add_i32 m0, s82, 0xe000
	s_nop 0
	global_load_lds_dwordx4 v[198:199], off
	s_waitcnt vmcnt(8)
	s_waitcnt lgkmcnt(0)
	s_barrier
	s_setprio 1
	s_waitcnt lgkmcnt(0)
	v_mfma_f32_16x16x32_bf16 v[128:131], v[132:135], v[164:167], v[128:131]
	v_mfma_f32_16x16x32_bf16 v[124:127], v[140:143], v[164:167], v[124:127]
	v_mfma_f32_16x16x32_bf16 v[112:115], v[132:135], v[172:175], v[112:115]
	v_mfma_f32_16x16x32_bf16 v[108:111], v[140:143], v[172:175], v[108:111]
	v_mfma_f32_16x16x32_bf16 v[96:99], v[132:135], v[192:195], v[96:99]
	v_mfma_f32_16x16x32_bf16 v[92:95], v[140:143], v[192:195], v[92:95]
	v_mfma_f32_16x16x32_bf16 v[80:83], v[132:135], v[214:217], v[80:83]
	v_mfma_f32_16x16x32_bf16 v[76:79], v[140:143], v[214:217], v[76:79]
	v_mfma_f32_16x16x32_bf16 v[128:131], v[136:139], v[168:171], v[128:131]
	v_mfma_f32_16x16x32_bf16 v[124:127], v[144:147], v[168:171], v[124:127]
	v_mfma_f32_16x16x32_bf16 v[112:115], v[136:139], v[176:179], v[112:115]
	v_mfma_f32_16x16x32_bf16 v[108:111], v[144:147], v[176:179], v[108:111]
	v_mfma_f32_16x16x32_bf16 v[96:99], v[136:139], v[210:213], v[96:99]
	v_mfma_f32_16x16x32_bf16 v[92:95], v[144:147], v[210:213], v[92:95]
	v_mfma_f32_16x16x32_bf16 v[80:83], v[136:139], v[218:221], v[80:83]
	v_mfma_f32_16x16x32_bf16 v[76:79], v[144:147], v[218:221], v[76:79]
	s_setprio 0
	s_setprio 1
	v_mfma_f32_16x16x32_bf16 v[120:123], v[148:151], v[164:167], v[120:123]
	v_mfma_f32_16x16x32_bf16 v[116:119], v[156:159], v[164:167], v[116:119]
	v_mfma_f32_16x16x32_bf16 v[104:107], v[148:151], v[172:175], v[104:107]
	v_mfma_f32_16x16x32_bf16 v[100:103], v[156:159], v[172:175], v[100:103]
	v_mfma_f32_16x16x32_bf16 v[88:91], v[148:151], v[192:195], v[88:91]
	v_mfma_f32_16x16x32_bf16 v[84:87], v[156:159], v[192:195], v[84:87]
	v_mfma_f32_16x16x32_bf16 v[72:75], v[148:151], v[214:217], v[72:75]
	v_mfma_f32_16x16x32_bf16 v[68:71], v[156:159], v[214:217], v[68:71]
	v_mfma_f32_16x16x32_bf16 v[120:123], v[152:155], v[168:171], v[120:123]
	v_mfma_f32_16x16x32_bf16 v[116:119], v[160:163], v[168:171], v[116:119]
	v_mfma_f32_16x16x32_bf16 v[104:107], v[152:155], v[176:179], v[104:107]
	v_mfma_f32_16x16x32_bf16 v[100:103], v[160:163], v[176:179], v[100:103]
	v_mfma_f32_16x16x32_bf16 v[88:91], v[152:155], v[210:213], v[88:91]
	v_mfma_f32_16x16x32_bf16 v[84:87], v[160:163], v[210:213], v[84:87]
	v_mfma_f32_16x16x32_bf16 v[72:75], v[152:155], v[218:221], v[72:75]
	v_mfma_f32_16x16x32_bf16 v[68:71], v[160:163], v[218:221], v[68:71]
	s_setprio 0
	s_barrier
	s_mov_b32 m0, s77
	v_lshl_add_u64 v[198:199], s[22:23], 0, v[184:185]
	s_add_u32 s54, s22, 0x20000
	ds_read_b128 v[164:167], v241 offset:16384
	ds_read_b128 v[168:171], v241 offset:17408
	ds_read_b128 v[172:175], v241 offset:18432
	ds_read_b128 v[176:179], v241 offset:19456
	ds_read_b128 v[192:195], v241 offset:20480
	ds_read_b128 v[210:213], v241 offset:21504
	ds_read_b128 v[214:217], v241 offset:22528
	ds_read_b128 v[218:221], v241 offset:23552
	global_load_lds_dwordx4 v[198:199], off
	v_lshl_add_u64 v[200:201], s[22:23], 0, v[180:181]
	s_mov_b32 m0, s78
	s_addc_u32 s55, s23, 0
	global_load_lds_dwordx4 v[200:201], off
	v_lshl_add_u64 v[222:223], s[54:55], 0, v[184:185]
	s_mov_b32 m0, s80
	v_lshl_add_u64 v[224:225], s[30:31], 0, v[182:183]
	global_load_lds_dwordx4 v[222:223], off
	v_lshl_add_u64 v[222:223], s[54:55], 0, v[180:181]
	s_mov_b32 m0, s81
	s_nop 0
	global_load_lds_dwordx4 v[222:223], off
	v_lshl_add_u64 v[222:223], s[30:31], 0, v[186:187]
	s_mov_b32 m0, s82
	s_nop 0
	global_load_lds_dwordx4 v[222:223], off
	s_mov_b32 m0, s83
	s_nop 0
	global_load_lds_dwordx4 v[224:225], off
	s_waitcnt vmcnt(8)
	s_waitcnt lgkmcnt(0)
	s_barrier
; #define PG8_STAGE(bufoff, gbase, voff) do { _Pragma("unroll") for (int _i = 0; _i < 2; ++_i) \
;         __builtin_amdgcn_global_load_lds((const unsigned*)((const char*)(gbase) + (voff)[_i]), (LAS unsigned*)(lds + (bufoff) + ldsw + _i * 8192), 16, 0, 0); } while (0)
; #define PG8_LDA(dst, b, h) do { _Pragma("unroll") for (int m = 0; m < 4; ++m) _Pragma("unroll") for (int k = 0; k < 2; ++k) dst[m][k] = *(const LAS bf16x8*)(lds + PG8_SA(b, h) + aoff + m * 2048 + k * 1024); } while (0)
; #define PG8_LDB(dst, b, h) do { _Pragma("unroll") for (int n = 0; n < 2; ++n) _Pragma("unroll") for (int k = 0; k < 2; ++k) dst[n][k] = *(const LAS bf16x8*)(lds + PG8_SB(b, h) + boff + n * 2048 + k * 1024); } while (0)
; #define PG8_MMA(ai, bj, At, Bt) do { __builtin_amdgcn_s_setprio(1); _Pragma("unroll") for (int m = 0; m < 4; ++m) _Pragma("unroll") for (int n = 0; n < 2; ++n) _Pragma("unroll") for (int k = 0; k < 2; ++k) \
;         acc[ai][bj][m][n] = __builtin_amdgcn_mfma_f32_16x16x32_bf16(Bt[n][k], At[m][k], acc[ai][bj][m][n], 0, 0, 0); __builtin_amdgcn_s_setprio(0); } while (0)
; #define PG8_WAIT_V(n) asm volatile("s_waitcnt vmcnt(" #n ")" ::: "memory")
; #define PG8_WAIT_L(n) asm volatile("s_waitcnt lgkmcnt(" #n ")" ::: "memory")
; #define PG8_BAR __builtin_amdgcn_s_barrier()
; #define PG8_SCHED __builtin_amdgcn_sched_barrier(0)
; template <class Epi, class Sched, bool ALIGN_EPI>
; DI void gemm_phase(LAS unsigned char* lds, const Gemm g, const Sched& Sc, const Epi& E, const int tid) {
;     ...
;             PG8_LDA(At, 0, 1); PG8_STAGE(PG8_SB(0, 0), b2, voffB); PG8_STAGE(PG8_SB(0, 1), b2 + hB, voffB); PG8_STAGE(PG8_SA(0, 0), a2, voffA);
;             PG8_WAIT_V(8); PG8_WAIT_L(0); PG8_BAR; PG8_MMA(1, 0, At, B0); PG8_MMA(1, 1, At, B1); PG8_BAR; PG8_SCHED;
;             PG8_LDB(B0, 1, 0); PG8_LDB(B1, 1, 1); PG8_SCHED; PG8_LDA(At, 1, 0); PG8_STAGE(PG8_SA(0, 1), a2 + hA, voffA);
;             PG8_WAIT_V(8); PG8_WAIT_L(0); PG8_BAR; PG8_MMA(0, 0, At, B0); PG8_MMA(0, 1, At, B1); PG8_BAR; PG8_SCHED;
	s_setprio 1
	s_waitcnt lgkmcnt(0)
	v_mfma_f32_16x16x32_bf16 v[64:67], v[132:135], v[164:167], v[64:67]
	v_mfma_f32_16x16x32_bf16 v[60:63], v[140:143], v[164:167], v[60:63]
	v_mfma_f32_16x16x32_bf16 v[48:51], v[132:135], v[172:175], v[48:51]
	v_mfma_f32_16x16x32_bf16 v[44:47], v[140:143], v[172:175], v[44:47]
	v_mfma_f32_16x16x32_bf16 v[32:35], v[132:135], v[192:195], v[32:35]
	v_mfma_f32_16x16x32_bf16 v[28:31], v[140:143], v[192:195], v[28:31]
	v_mfma_f32_16x16x32_bf16 v[14:17], v[132:135], v[214:217], v[14:17]
	v_mfma_f32_16x16x32_bf16 v[10:13], v[140:143], v[214:217], v[10:13]
	v_mfma_f32_16x16x32_bf16 v[64:67], v[136:139], v[168:171], v[64:67]
	v_mfma_f32_16x16x32_bf16 v[60:63], v[144:147], v[168:171], v[60:63]
	v_mfma_f32_16x16x32_bf16 v[48:51], v[136:139], v[176:179], v[48:51]
	v_mfma_f32_16x16x32_bf16 v[44:47], v[144:147], v[176:179], v[44:47]
	v_mfma_f32_16x16x32_bf16 v[32:35], v[136:139], v[210:213], v[32:35]
	v_mfma_f32_16x16x32_bf16 v[28:31], v[144:147], v[210:213], v[28:31]
	v_mfma_f32_16x16x32_bf16 v[14:17], v[136:139], v[218:221], v[14:17]
	v_mfma_f32_16x16x32_bf16 v[10:13], v[144:147], v[218:221], v[10:13]
	s_setprio 0
	s_setprio 1
	v_mfma_f32_16x16x32_bf16 v[56:59], v[148:151], v[164:167], v[56:59]
	v_mfma_f32_16x16x32_bf16 v[52:55], v[156:159], v[164:167], v[52:55]
	v_mfma_f32_16x16x32_bf16 v[40:43], v[148:151], v[172:175], v[40:43]
	v_mfma_f32_16x16x32_bf16 v[36:39], v[156:159], v[172:175], v[36:39]
	v_mfma_f32_16x16x32_bf16 v[24:27], v[148:151], v[192:195], v[24:27]
	v_mfma_f32_16x16x32_bf16 v[20:23], v[156:159], v[192:195], v[20:23]
	v_mfma_f32_16x16x32_bf16 v[6:9], v[148:151], v[214:217], v[6:9]
	v_mfma_f32_16x16x32_bf16 v[2:5], v[156:159], v[214:217], v[2:5]
	v_mfma_f32_16x16x32_bf16 v[56:59], v[152:155], v[168:171], v[56:59]
	v_mfma_f32_16x16x32_bf16 v[52:55], v[160:163], v[168:171], v[52:55]
	v_mfma_f32_16x16x32_bf16 v[40:43], v[152:155], v[176:179], v[40:43]
	v_mfma_f32_16x16x32_bf16 v[36:39], v[160:163], v[176:179], v[36:39]
	v_mfma_f32_16x16x32_bf16 v[24:27], v[152:155], v[210:213], v[24:27]
	v_mfma_f32_16x16x32_bf16 v[20:23], v[160:163], v[210:213], v[20:23]
	v_mfma_f32_16x16x32_bf16 v[6:9], v[152:155], v[218:221], v[6:9]
	v_mfma_f32_16x16x32_bf16 v[2:5], v[160:163], v[218:221], v[2:5]
	s_setprio 0
	s_barrier
	v_add_u32_e32 v18, s86, v239
	ds_read_b128 v[132:135], v18
	ds_read_b128 v[136:139], v18 offset:1024
	ds_read_b128 v[140:143], v18 offset:2048
	ds_read_b128 v[144:147], v18 offset:3072
	v_add_u32_e32 v18, s42, v239
	ds_read_b128 v[148:151], v18
	ds_read_b128 v[152:155], v18 offset:1024
	ds_read_b128 v[156:159], v18 offset:2048
	ds_read_b128 v[160:163], v18 offset:3072
	s_add_u32 s30, s30, 0x20000
	s_addc_u32 s31, s31, 0
	s_mov_b32 m0, s84
	v_lshl_add_u64 v[226:227], s[30:31], 0, v[186:187]
	ds_read_b128 v[164:167], v241 offset:32768
	ds_read_b128 v[168:171], v241 offset:33792
	ds_read_b128 v[172:175], v241 offset:34816
	ds_read_b128 v[176:179], v241 offset:35840
	ds_read_b128 v[192:195], v241 offset:36864
	ds_read_b128 v[210:213], v241 offset:37888
	ds_read_b128 v[214:217], v241 offset:38912
	ds_read_b128 v[218:221], v241 offset:39936
	global_load_lds_dwordx4 v[226:227], off
	v_lshl_add_u64 v[226:227], s[30:31], 0, v[182:183]
	s_mov_b32 m0, s85
	s_nop 0
	global_load_lds_dwordx4 v[226:227], off
	s_waitcnt vmcnt(8)
	s_waitcnt lgkmcnt(0)
	s_barrier
	s_setprio 1
	s_waitcnt lgkmcnt(0)
	v_mfma_f32_16x16x32_bf16 v[128:131], v[132:135], v[164:167], v[128:131]
	v_mfma_f32_16x16x32_bf16 v[124:127], v[140:143], v[164:167], v[124:127]
	v_mfma_f32_16x16x32_bf16 v[112:115], v[132:135], v[172:175], v[112:115]
	v_mfma_f32_16x16x32_bf16 v[108:111], v[140:143], v[172:175], v[108:111]
	v_mfma_f32_16x16x32_bf16 v[96:99], v[132:135], v[192:195], v[96:99]
	v_mfma_f32_16x16x32_bf16 v[92:95], v[140:143], v[192:195], v[92:95]
	v_mfma_f32_16x16x32_bf16 v[80:83], v[132:135], v[214:217], v[80:83]
	v_mfma_f32_16x16x32_bf16 v[76:79], v[140:143], v[214:217], v[76:79]
	v_mfma_f32_16x16x32_bf16 v[128:131], v[136:139], v[168:171], v[128:131]
	v_mfma_f32_16x16x32_bf16 v[124:127], v[144:147], v[168:171], v[124:127]
	v_mfma_f32_16x16x32_bf16 v[112:115], v[136:139], v[176:179], v[112:115]
	v_mfma_f32_16x16x32_bf16 v[108:111], v[144:147], v[176:179], v[108:111]
	v_mfma_f32_16x16x32_bf16 v[96:99], v[136:139], v[210:213], v[96:99]
	v_mfma_f32_16x16x32_bf16 v[92:95], v[144:147], v[210:213], v[92:95]
	v_mfma_f32_16x16x32_bf16 v[80:83], v[136:139], v[218:221], v[80:83]
	v_mfma_f32_16x16x32_bf16 v[76:79], v[144:147], v[218:221], v[76:79]
	s_setprio 0
	s_setprio 1
	v_mfma_f32_16x16x32_bf16 v[120:123], v[148:151], v[164:167], v[120:123]
	v_mfma_f32_16x16x32_bf16 v[116:119], v[156:159], v[164:167], v[116:119]
	v_mfma_f32_16x16x32_bf16 v[104:107], v[148:151], v[172:175], v[104:107]
	v_mfma_f32_16x16x32_bf16 v[100:103], v[156:159], v[172:175], v[100:103]
	v_mfma_f32_16x16x32_bf16 v[88:91], v[148:151], v[192:195], v[88:91]
	v_mfma_f32_16x16x32_bf16 v[84:87], v[156:159], v[192:195], v[84:87]
	v_mfma_f32_16x16x32_bf16 v[72:75], v[148:151], v[214:217], v[72:75]
	v_mfma_f32_16x16x32_bf16 v[68:71], v[156:159], v[214:217], v[68:71]
	v_mfma_f32_16x16x32_bf16 v[120:123], v[152:155], v[168:171], v[120:123]
	v_mfma_f32_16x16x32_bf16 v[116:119], v[160:163], v[168:171], v[116:119]
	v_mfma_f32_16x16x32_bf16 v[104:107], v[152:155], v[176:179], v[104:107]
	v_mfma_f32_16x16x32_bf16 v[100:103], v[160:163], v[176:179], v[100:103]
	v_mfma_f32_16x16x32_bf16 v[88:91], v[152:155], v[210:213], v[88:91]
	v_mfma_f32_16x16x32_bf16 v[84:87], v[160:163], v[210:213], v[84:87]
	v_mfma_f32_16x16x32_bf16 v[72:75], v[152:155], v[218:221], v[72:75]
	v_mfma_f32_16x16x32_bf16 v[68:71], v[160:163], v[218:221], v[68:71]
	s_setprio 0
	s_barrier
; #define PG8_STAGE(bufoff, gbase, voff) do { _Pragma("unroll") for (int _i = 0; _i < 2; ++_i) \
;         __builtin_amdgcn_global_load_lds((const unsigned*)((const char*)(gbase) + (voff)[_i]), (LAS unsigned*)(lds + (bufoff) + ldsw + _i * 8192), 16, 0, 0); } while (0)
; #define PG8_LDA(dst, b, h) do { _Pragma("unroll") for (int m = 0; m < 4; ++m) _Pragma("unroll") for (int k = 0; k < 2; ++k) dst[m][k] = *(const LAS bf16x8*)(lds + PG8_SA(b, h) + aoff + m * 2048 + k * 1024); } while (0)
; #define PG8_MMA(ai, bj, At, Bt) do { __builtin_amdgcn_s_setprio(1); _Pragma("unroll") for (int m = 0; m < 4; ++m) _Pragma("unroll") for (int n = 0; n < 2; ++n) _Pragma("unroll") for (int k = 0; k < 2; ++k) \
;         acc[ai][bj][m][n] = __builtin_amdgcn_mfma_f32_16x16x32_bf16(Bt[n][k], At[m][k], acc[ai][bj][m][n], 0, 0, 0); __builtin_amdgcn_s_setprio(0); } while (0)
; #define PG8_WAIT_V(n) asm volatile("s_waitcnt vmcnt(" #n ")" ::: "memory")
; #define PG8_WAIT_L(n) asm volatile("s_waitcnt lgkmcnt(" #n ")" ::: "memory")
; #define PG8_BAR __builtin_amdgcn_s_barrier()
; #define PG8_SCHED __builtin_amdgcn_sched_barrier(0)
; template <class Epi, class Sched, bool ALIGN_EPI>
; DI void gemm_phase(LAS unsigned char* lds, const Gemm g, const Sched& Sc, const Epi& E, const int tid) {
;     ...
;             PG8_LDA(At, 1, 1); PG8_STAGE(PG8_SB(1, 0), b3, voffB); PG8_STAGE(PG8_SB(1, 1), b3 + hB, voffB); PG8_STAGE(PG8_SA(1, 0), a3, voffA);
;             PG8_WAIT_V(8); PG8_WAIT_L(0); PG8_BAR; PG8_MMA(1, 0, At, B0); PG8_MMA(1, 1, At, B1); PG8_BAR; PG8_SCHED;
;         }
;         if constexpr (ALIGN_EPI) { if (wr == 0) PG8_BAR; }
	s_mov_b32 m0, s87
	v_lshl_add_u64 v[198:199], v[198:199], 0, s[60:61]
	s_add_u32 s22, s22, 0x20080
	ds_read_b128 v[164:167], v241 offset:49152
	ds_read_b128 v[168:171], v241 offset:50176
	ds_read_b128 v[172:175], v241 offset:51200
	ds_read_b128 v[176:179], v241 offset:52224
	ds_read_b128 v[192:195], v241 offset:53248
	ds_read_b128 v[210:213], v241 offset:54272
	ds_read_b128 v[214:217], v241 offset:55296
	ds_read_b128 v[218:221], v241 offset:56320
	global_load_lds_dwordx4 v[198:199], off
	v_lshl_add_u64 v[198:199], v[200:201], 0, s[60:61]
	s_mov_b32 m0, s88
	s_addc_u32 s23, s23, 0
	global_load_lds_dwordx4 v[198:199], off
	v_lshl_add_u64 v[198:199], s[22:23], 0, v[184:185]
	s_mov_b32 m0, s43
	s_nop 0
	global_load_lds_dwordx4 v[198:199], off
	v_lshl_add_u64 v[198:199], s[22:23], 0, v[180:181]
	s_mov_b32 m0, s66
	s_nop 0
	global_load_lds_dwordx4 v[198:199], off
	v_lshl_add_u64 v[198:199], v[222:223], 0, s[60:61]
	s_mov_b32 m0, s89
	s_nop 0
	global_load_lds_dwordx4 v[198:199], off
	v_lshl_add_u64 v[198:199], v[224:225], 0, s[60:61]
	s_mov_b32 m0, s11
	s_nop 0
	global_load_lds_dwordx4 v[198:199], off
	s_waitcnt vmcnt(8)
	s_waitcnt lgkmcnt(0)
	s_barrier
	s_setprio 1
	s_waitcnt lgkmcnt(0)
	v_mfma_f32_16x16x32_bf16 v[64:67], v[132:135], v[164:167], v[64:67]
	v_mfma_f32_16x16x32_bf16 v[60:63], v[140:143], v[164:167], v[60:63]
	v_mfma_f32_16x16x32_bf16 v[48:51], v[132:135], v[172:175], v[48:51]
	v_mfma_f32_16x16x32_bf16 v[44:47], v[140:143], v[172:175], v[44:47]
	v_mfma_f32_16x16x32_bf16 v[32:35], v[132:135], v[192:195], v[32:35]
	v_mfma_f32_16x16x32_bf16 v[28:31], v[140:143], v[192:195], v[28:31]
	v_mfma_f32_16x16x32_bf16 v[14:17], v[132:135], v[214:217], v[14:17]
	v_mfma_f32_16x16x32_bf16 v[10:13], v[140:143], v[214:217], v[10:13]
	v_mfma_f32_16x16x32_bf16 v[64:67], v[136:139], v[168:171], v[64:67]
	v_mfma_f32_16x16x32_bf16 v[60:63], v[144:147], v[168:171], v[60:63]
	v_mfma_f32_16x16x32_bf16 v[48:51], v[136:139], v[176:179], v[48:51]
	v_mfma_f32_16x16x32_bf16 v[44:47], v[144:147], v[176:179], v[44:47]
	v_mfma_f32_16x16x32_bf16 v[32:35], v[136:139], v[210:213], v[32:35]
	v_mfma_f32_16x16x32_bf16 v[28:31], v[144:147], v[210:213], v[28:31]
	v_mfma_f32_16x16x32_bf16 v[14:17], v[136:139], v[218:221], v[14:17]
	v_mfma_f32_16x16x32_bf16 v[10:13], v[144:147], v[218:221], v[10:13]
	s_setprio 0
	s_setprio 1
	v_mfma_f32_16x16x32_bf16 v[56:59], v[148:151], v[164:167], v[56:59]
	v_mfma_f32_16x16x32_bf16 v[52:55], v[156:159], v[164:167], v[52:55]
	v_mfma_f32_16x16x32_bf16 v[40:43], v[148:151], v[172:175], v[40:43]
	v_mfma_f32_16x16x32_bf16 v[36:39], v[156:159], v[172:175], v[36:39]
	v_mfma_f32_16x16x32_bf16 v[24:27], v[148:151], v[192:195], v[24:27]
	v_mfma_f32_16x16x32_bf16 v[20:23], v[156:159], v[192:195], v[20:23]
	v_mfma_f32_16x16x32_bf16 v[6:9], v[148:151], v[214:217], v[6:9]
	v_mfma_f32_16x16x32_bf16 v[2:5], v[156:159], v[214:217], v[2:5]
	v_mfma_f32_16x16x32_bf16 v[56:59], v[152:155], v[168:171], v[56:59]
	v_mfma_f32_16x16x32_bf16 v[52:55], v[160:163], v[168:171], v[52:55]
	v_mfma_f32_16x16x32_bf16 v[40:43], v[152:155], v[176:179], v[40:43]
	v_mfma_f32_16x16x32_bf16 v[36:39], v[160:163], v[176:179], v[36:39]
	v_mfma_f32_16x16x32_bf16 v[24:27], v[152:155], v[210:213], v[24:27]
	v_mfma_f32_16x16x32_bf16 v[20:23], v[160:163], v[210:213], v[20:23]
	v_mfma_f32_16x16x32_bf16 v[6:9], v[152:155], v[218:221], v[6:9]
	v_mfma_f32_16x16x32_bf16 v[2:5], v[160:163], v[218:221], v[2:5]
	s_add_i32 s52, s52, 2
	s_add_u32 s38, s38, 0x100
	s_addc_u32 s39, s39, 0
	s_add_u32 s18, s18, 0x100
	s_addc_u32 s19, s19, 0
	s_cmp_gt_u32 s52, 5
	s_setprio 0
	s_barrier
	s_cbranch_scc0 .LBB0_995
	s_and_b64 vcc, exec, s[62:63]
	s_cbranch_vccz .LBB0_998
	s_barrier

; #define PG8_STAGE(bufoff, gbase, voff) do { _Pragma("unroll") for (int _i = 0; _i < 2; ++_i) \
;         __builtin_amdgcn_global_load_lds((const unsigned*)((const char*)(gbase) + (voff)[_i]), (LAS unsigned*)(lds + (bufoff) + ldsw + _i * 8192), 16, 0, 0); } while (0)
; #define PG8_LDA(dst, b, h) do { _Pragma("unroll") for (int m = 0; m < 4; ++m) _Pragma("unroll") for (int k = 0; k < 2; ++k) dst[m][k] = *(const LAS bf16x8*)(lds + PG8_SA(b, h) + aoff + m * 2048 + k * 1024); } while (0)
; #define PG8_LDB(dst, b, h) do { _Pragma("unroll") for (int n = 0; n < 2; ++n) _Pragma("unroll") for (int k = 0; k < 2; ++k) dst[n][k] = *(const LAS bf16x8*)(lds + PG8_SB(b, h) + boff + n * 2048 + k * 1024); } while (0)
; #define PG8_MMA(ai, bj, At, Bt) do { __builtin_amdgcn_s_setprio(1); _Pragma("unroll") for (int m = 0; m < 4; ++m) _Pragma("unroll") for (int n = 0; n < 2; ++n) _Pragma("unroll") for (int k = 0; k < 2; ++k) \
;         acc[ai][bj][m][n] = __builtin_amdgcn_mfma_f32_16x16x32_bf16(Bt[n][k], At[m][k], acc[ai][bj][m][n], 0, 0, 0); __builtin_amdgcn_s_setprio(0); } while (0)
; #define PG8_WAIT_V(n) asm volatile("s_waitcnt vmcnt(" #n ")" ::: "memory")
; #define PG8_WAIT_L(n) asm volatile("s_waitcnt lgkmcnt(" #n ")" ::: "memory")
; #define PG8_BAR __builtin_amdgcn_s_barrier()
; #define PG8_SCHED __builtin_amdgcn_sched_barrier(0)
; template <class Epi, class Sched, bool ALIGN_EPI>
; DI void gemm_phase(LAS unsigned char* lds, const Gemm g, const Sched& Sc, const Epi& E, const int tid) {
;     ...
;             const bool last = (t == nt - 2);
;             const char* a1 = cA + (size_t)(t + 1) * kstep;
;             const char* a2 = last ? nA : cA + (size_t)(t + 2) * kstep; const char* b2 = last ? nB : cB + (size_t)(t + 2) * kstep;
;             const char* a3 = a2 + kstep; const char* b3 = b2 + kstep;
;             PG8_LDB(B0, 0, 0); PG8_LDB(B1, 0, 1); PG8_SCHED; PG8_LDA(At, 0, 0); PG8_STAGE(PG8_SA(1, 1), a1 + hA, voffA);
;             PG8_WAIT_V(8); PG8_WAIT_L(0); PG8_BAR; PG8_MMA(0, 0, At, B0); PG8_MMA(0, 1, At, B1); PG8_BAR; PG8_SCHED;
.LBB0_2429:
	v_add_u32_e32 v18, s47, v195
	ds_read_b128 v[70:73], v18
	ds_read_b128 v[74:77], v18 offset:1024
	ds_read_b128 v[94:97], v18 offset:2048
	ds_read_b128 v[98:101], v18 offset:3072
	v_add_u32_e32 v18, s50, v195
	ds_read_b128 v[126:129], v18
	ds_read_b128 v[130:133], v18 offset:1024
	ds_read_b128 v[150:153], v18 offset:2048
	ds_read_b128 v[154:157], v18 offset:3072
	s_add_u32 s42, s40, 0xfff80080
	s_addc_u32 s43, s41, -1
	s_cmp_eq_u32 s77, 4
	s_cselect_b32 s45, s17, s43
	s_cselect_b32 s44, s19, s42
	s_cselect_b32 s43, s23, s76
	s_cselect_b32 s42, s39, s75
	v_lshl_add_u64 v[20:21], s[40:41], 0, v[180:181]
	s_add_i32 m0, s53, 0xc000
	ds_read_b128 v[166:169], v210
	ds_read_b128 v[182:185], v210 offset:1024
	ds_read_b128 v[186:189], v210 offset:2048
	ds_read_b128 v[190:193], v210 offset:3072
	ds_read_b128 v[198:201], v210 offset:4096
	ds_read_b128 v[212:215], v210 offset:5120
	ds_read_b128 v[216:219], v210 offset:6144
	ds_read_b128 v[220:223], v210 offset:7168
	global_load_lds_dwordx4 v[20:21], off
	v_lshl_add_u64 v[20:21], s[40:41], 0, v[178:179]
	s_add_i32 m0, s53, 0xe000
	s_nop 0
	global_load_lds_dwordx4 v[20:21], off
	s_waitcnt vmcnt(8)
	s_waitcnt lgkmcnt(0)
	s_barrier
	s_setprio 1
	s_waitcnt lgkmcnt(0)
	v_mfma_f32_16x16x32_bf16 v[82:85], v[70:73], v[166:169], v[82:85]
	v_mfma_f32_16x16x32_bf16 v[78:81], v[94:97], v[166:169], v[78:81]
	v_mfma_f32_16x16x32_bf16 v[114:117], v[70:73], v[186:189], v[114:117]
	v_mfma_f32_16x16x32_bf16 v[110:113], v[94:97], v[186:189], v[110:113]
	v_mfma_f32_16x16x32_bf16 v[138:141], v[70:73], v[198:201], v[138:141]
	v_mfma_f32_16x16x32_bf16 v[134:137], v[94:97], v[198:201], v[134:137]
	v_mfma_f32_16x16x32_bf16 v[106:109], v[70:73], v[216:219], v[106:109]
	v_mfma_f32_16x16x32_bf16 v[102:105], v[94:97], v[216:219], v[102:105]
	v_mfma_f32_16x16x32_bf16 v[82:85], v[74:77], v[182:185], v[82:85]
	v_mfma_f32_16x16x32_bf16 v[78:81], v[98:101], v[182:185], v[78:81]
	v_mfma_f32_16x16x32_bf16 v[114:117], v[74:77], v[190:193], v[114:117]
	v_mfma_f32_16x16x32_bf16 v[110:113], v[98:101], v[190:193], v[110:113]
	v_mfma_f32_16x16x32_bf16 v[138:141], v[74:77], v[212:215], v[138:141]
	v_mfma_f32_16x16x32_bf16 v[134:137], v[98:101], v[212:215], v[134:137]
	v_mfma_f32_16x16x32_bf16 v[106:109], v[74:77], v[220:223], v[106:109]
	v_mfma_f32_16x16x32_bf16 v[102:105], v[98:101], v[220:223], v[102:105]
	s_setprio 0
	s_setprio 1
	v_mfma_f32_16x16x32_bf16 v[162:165], v[126:129], v[166:169], v[162:165]
	v_mfma_f32_16x16x32_bf16 v[158:161], v[150:153], v[166:169], v[158:161]
	v_mfma_f32_16x16x32_bf16 v[146:149], v[126:129], v[186:189], v[146:149]
	v_mfma_f32_16x16x32_bf16 v[142:145], v[150:153], v[186:189], v[142:145]
	v_mfma_f32_16x16x32_bf16 v[122:125], v[126:129], v[198:201], v[122:125]
	v_mfma_f32_16x16x32_bf16 v[118:121], v[150:153], v[198:201], v[118:121]
	v_mfma_f32_16x16x32_bf16 v[90:93], v[126:129], v[216:219], v[90:93]
	v_mfma_f32_16x16x32_bf16 v[86:89], v[150:153], v[216:219], v[86:89]
	v_mfma_f32_16x16x32_bf16 v[162:165], v[130:133], v[182:185], v[162:165]
	v_mfma_f32_16x16x32_bf16 v[158:161], v[154:157], v[182:185], v[158:161]
	v_mfma_f32_16x16x32_bf16 v[146:149], v[130:133], v[190:193], v[146:149]
	v_mfma_f32_16x16x32_bf16 v[142:145], v[154:157], v[190:193], v[142:145]
	v_mfma_f32_16x16x32_bf16 v[122:125], v[130:133], v[212:215], v[122:125]
	v_mfma_f32_16x16x32_bf16 v[118:121], v[154:157], v[212:215], v[118:121]
	v_mfma_f32_16x16x32_bf16 v[90:93], v[130:133], v[220:223], v[90:93]
	v_mfma_f32_16x16x32_bf16 v[86:89], v[154:157], v[220:223], v[86:89]
	s_setprio 0
	s_barrier
	s_mov_b32 m0, s48
	v_lshl_add_u64 v[224:225], s[42:43], 0, v[172:173]
	s_add_u32 s78, s42, 0x20000
	ds_read_b128 v[166:169], v210 offset:16384
	ds_read_b128 v[182:185], v210 offset:17408
	ds_read_b128 v[186:189], v210 offset:18432
	ds_read_b128 v[190:193], v210 offset:19456
	ds_read_b128 v[198:201], v210 offset:20480
	ds_read_b128 v[212:215], v210 offset:21504
	ds_read_b128 v[216:219], v210 offset:22528
	ds_read_b128 v[220:223], v210 offset:23552
	global_load_lds_dwordx4 v[224:225], off
	v_lshl_add_u64 v[226:227], s[42:43], 0, v[176:177]
	s_mov_b32 m0, s49
	s_addc_u32 s79, s43, 0
	global_load_lds_dwordx4 v[226:227], off
	v_lshl_add_u64 v[20:21], s[78:79], 0, v[172:173]
	s_mov_b32 m0, s51
	v_lshl_add_u64 v[228:229], s[44:45], 0, v[170:171]
	global_load_lds_dwordx4 v[20:21], off
	v_lshl_add_u64 v[20:21], s[78:79], 0, v[176:177]
	s_mov_b32 m0, s52
	v_lshl_add_u64 v[230:231], s[44:45], 0, v[174:175]
	global_load_lds_dwordx4 v[20:21], off
	s_mov_b32 m0, s53
	s_nop 0
	global_load_lds_dwordx4 v[228:229], off
	s_mov_b32 m0, s54
	s_nop 0
	global_load_lds_dwordx4 v[230:231], off
	s_waitcnt vmcnt(8)
	s_waitcnt lgkmcnt(0)
	s_barrier
; #define PG8_STAGE(bufoff, gbase, voff) do { _Pragma("unroll") for (int _i = 0; _i < 2; ++_i) \
;         __builtin_amdgcn_global_load_lds((const unsigned*)((const char*)(gbase) + (voff)[_i]), (LAS unsigned*)(lds + (bufoff) + ldsw + _i * 8192), 16, 0, 0); } while (0)
; #define PG8_LDA(dst, b, h) do { _Pragma("unroll") for (int m = 0; m < 4; ++m) _Pragma("unroll") for (int k = 0; k < 2; ++k) dst[m][k] = *(const LAS bf16x8*)(lds + PG8_SA(b, h) + aoff + m * 2048 + k * 1024); } while (0)
; #define PG8_LDB(dst, b, h) do { _Pragma("unroll") for (int n = 0; n < 2; ++n) _Pragma("unroll") for (int k = 0; k < 2; ++k) dst[n][k] = *(const LAS bf16x8*)(lds + PG8_SB(b, h) + boff + n * 2048 + k * 1024); } while (0)
; #define PG8_MMA(ai, bj, At, Bt) do { __builtin_amdgcn_s_setprio(1); _Pragma("unroll") for (int m = 0; m < 4; ++m) _Pragma("unroll") for (int n = 0; n < 2; ++n) _Pragma("unroll") for (int k = 0; k < 2; ++k) \
;         acc[ai][bj][m][n] = __builtin_amdgcn_mfma_f32_16x16x32_bf16(Bt[n][k], At[m][k], acc[ai][bj][m][n], 0, 0, 0); __builtin_amdgcn_s_setprio(0); } while (0)
; #define PG8_WAIT_V(n) asm volatile("s_waitcnt vmcnt(" #n ")" ::: "memory")
; #define PG8_WAIT_L(n) asm volatile("s_waitcnt lgkmcnt(" #n ")" ::: "memory")
; #define PG8_BAR __builtin_amdgcn_s_barrier()
; #define PG8_SCHED __builtin_amdgcn_sched_barrier(0)
; template <class Epi, class Sched, bool ALIGN_EPI>
; DI void gemm_phase(LAS unsigned char* lds, const Gemm g, const Sched& Sc, const Epi& E, const int tid) {
;     ...
;             PG8_LDA(At, 0, 1); PG8_STAGE(PG8_SB(0, 0), b2, voffB); PG8_STAGE(PG8_SB(0, 1), b2 + hB, voffB); PG8_STAGE(PG8_SA(0, 0), a2, voffA);
;             PG8_WAIT_V(8); PG8_WAIT_L(0); PG8_BAR; PG8_MMA(1, 0, At, B0); PG8_MMA(1, 1, At, B1); PG8_BAR; PG8_SCHED;
;             PG8_LDB(B0, 1, 0); PG8_LDB(B1, 1, 1); PG8_SCHED; PG8_LDA(At, 1, 0); PG8_STAGE(PG8_SA(0, 1), a2 + hA, voffA);
;             PG8_WAIT_V(8); PG8_WAIT_L(0); PG8_BAR; PG8_MMA(0, 0, At, B0); PG8_MMA(0, 1, At, B1); PG8_BAR; PG8_SCHED;
	s_setprio 1
	s_waitcnt lgkmcnt(0)
	v_mfma_f32_16x16x32_bf16 v[66:69], v[70:73], v[166:169], v[66:69]
	v_mfma_f32_16x16x32_bf16 v[62:65], v[94:97], v[166:169], v[62:65]
	v_mfma_f32_16x16x32_bf16 v[50:53], v[70:73], v[186:189], v[50:53]
	v_mfma_f32_16x16x32_bf16 v[46:49], v[94:97], v[186:189], v[46:49]
	v_mfma_f32_16x16x32_bf16 v[34:37], v[70:73], v[198:201], v[34:37]
	v_mfma_f32_16x16x32_bf16 v[30:33], v[94:97], v[198:201], v[30:33]
	v_mfma_f32_16x16x32_bf16 v[14:17], v[70:73], v[216:219], v[14:17]
	v_mfma_f32_16x16x32_bf16 v[10:13], v[94:97], v[216:219], v[10:13]
	v_mfma_f32_16x16x32_bf16 v[66:69], v[74:77], v[182:185], v[66:69]
	v_mfma_f32_16x16x32_bf16 v[62:65], v[98:101], v[182:185], v[62:65]
	v_mfma_f32_16x16x32_bf16 v[50:53], v[74:77], v[190:193], v[50:53]
	v_mfma_f32_16x16x32_bf16 v[46:49], v[98:101], v[190:193], v[46:49]
	v_mfma_f32_16x16x32_bf16 v[34:37], v[74:77], v[212:215], v[34:37]
	v_mfma_f32_16x16x32_bf16 v[30:33], v[98:101], v[212:215], v[30:33]
	v_mfma_f32_16x16x32_bf16 v[14:17], v[74:77], v[220:223], v[14:17]
	v_mfma_f32_16x16x32_bf16 v[10:13], v[98:101], v[220:223], v[10:13]
	s_setprio 0
	s_setprio 1
	v_mfma_f32_16x16x32_bf16 v[58:61], v[126:129], v[166:169], v[58:61]
	v_mfma_f32_16x16x32_bf16 v[54:57], v[150:153], v[166:169], v[54:57]
	v_mfma_f32_16x16x32_bf16 v[42:45], v[126:129], v[186:189], v[42:45]
	v_mfma_f32_16x16x32_bf16 v[38:41], v[150:153], v[186:189], v[38:41]
	v_mfma_f32_16x16x32_bf16 v[26:29], v[126:129], v[198:201], v[26:29]
	v_mfma_f32_16x16x32_bf16 v[20:23], v[150:153], v[198:201], v[22:25]
	v_mfma_f32_16x16x32_bf16 v[6:9], v[126:129], v[216:219], v[6:9]
	v_mfma_f32_16x16x32_bf16 v[2:5], v[150:153], v[216:219], v[2:5]
	v_mfma_f32_16x16x32_bf16 v[58:61], v[130:133], v[182:185], v[58:61]
	v_mfma_f32_16x16x32_bf16 v[54:57], v[154:157], v[182:185], v[54:57]
	v_mfma_f32_16x16x32_bf16 v[42:45], v[130:133], v[190:193], v[42:45]
	v_mfma_f32_16x16x32_bf16 v[38:41], v[154:157], v[190:193], v[38:41]
	v_mfma_f32_16x16x32_bf16 v[26:29], v[130:133], v[212:215], v[26:29]
	v_mfma_f32_16x16x32_bf16 v[20:23], v[154:157], v[212:215], v[20:23]
	v_mfma_f32_16x16x32_bf16 v[6:9], v[130:133], v[220:223], v[6:9]
	v_mfma_f32_16x16x32_bf16 v[2:5], v[154:157], v[220:223], v[2:5]
	s_setprio 0
	s_barrier
	v_add_u32_e32 v18, s57, v195
	ds_read_b128 v[70:73], v18
	ds_read_b128 v[74:77], v18 offset:1024
	ds_read_b128 v[94:97], v18 offset:2048
	ds_read_b128 v[98:101], v18 offset:3072
	v_add_u32_e32 v18, s66, v195
	ds_read_b128 v[126:129], v18
	ds_read_b128 v[130:133], v18 offset:1024
	ds_read_b128 v[150:153], v18 offset:2048
	ds_read_b128 v[154:157], v18 offset:3072
	s_add_u32 s44, s44, 0x80000
	s_addc_u32 s45, s45, 0
	s_mov_b32 m0, s55
	v_lshl_add_u64 v[24:25], s[44:45], 0, v[170:171]
	ds_read_b128 v[166:169], v210 offset:32768
	ds_read_b128 v[182:185], v210 offset:33792
	ds_read_b128 v[186:189], v210 offset:34816
	ds_read_b128 v[190:193], v210 offset:35840
	ds_read_b128 v[198:201], v210 offset:36864
	ds_read_b128 v[212:215], v210 offset:37888
	ds_read_b128 v[216:219], v210 offset:38912
	ds_read_b128 v[220:223], v210 offset:39936
	global_load_lds_dwordx4 v[24:25], off
	v_lshl_add_u64 v[24:25], s[44:45], 0, v[174:175]
	s_mov_b32 m0, s56
	s_nop 0
	global_load_lds_dwordx4 v[24:25], off
	s_waitcnt vmcnt(8)
	s_waitcnt lgkmcnt(0)
	s_barrier
	s_setprio 1
	s_waitcnt lgkmcnt(0)
	v_mfma_f32_16x16x32_bf16 v[82:85], v[70:73], v[166:169], v[82:85]
	v_mfma_f32_16x16x32_bf16 v[78:81], v[94:97], v[166:169], v[78:81]
	v_mfma_f32_16x16x32_bf16 v[114:117], v[70:73], v[186:189], v[114:117]
	v_mfma_f32_16x16x32_bf16 v[110:113], v[94:97], v[186:189], v[110:113]
	v_mfma_f32_16x16x32_bf16 v[138:141], v[70:73], v[198:201], v[138:141]
	v_mfma_f32_16x16x32_bf16 v[134:137], v[94:97], v[198:201], v[134:137]
	v_mfma_f32_16x16x32_bf16 v[106:109], v[70:73], v[216:219], v[106:109]
	v_mfma_f32_16x16x32_bf16 v[102:105], v[94:97], v[216:219], v[102:105]
	v_mfma_f32_16x16x32_bf16 v[82:85], v[74:77], v[182:185], v[82:85]
	v_mfma_f32_16x16x32_bf16 v[78:81], v[98:101], v[182:185], v[78:81]
	v_mfma_f32_16x16x32_bf16 v[114:117], v[74:77], v[190:193], v[114:117]
	v_mfma_f32_16x16x32_bf16 v[110:113], v[98:101], v[190:193], v[110:113]
	v_mfma_f32_16x16x32_bf16 v[138:141], v[74:77], v[212:215], v[138:141]
	v_mfma_f32_16x16x32_bf16 v[134:137], v[98:101], v[212:215], v[134:137]
	v_mfma_f32_16x16x32_bf16 v[106:109], v[74:77], v[220:223], v[106:109]
	v_mfma_f32_16x16x32_bf16 v[102:105], v[98:101], v[220:223], v[102:105]
	s_setprio 0
	s_setprio 1
	v_mfma_f32_16x16x32_bf16 v[162:165], v[126:129], v[166:169], v[162:165]
	v_mfma_f32_16x16x32_bf16 v[158:161], v[150:153], v[166:169], v[158:161]
	v_mfma_f32_16x16x32_bf16 v[146:149], v[126:129], v[186:189], v[146:149]
	v_mfma_f32_16x16x32_bf16 v[142:145], v[150:153], v[186:189], v[142:145]
	v_mfma_f32_16x16x32_bf16 v[122:125], v[126:129], v[198:201], v[122:125]
	v_mfma_f32_16x16x32_bf16 v[118:121], v[150:153], v[198:201], v[118:121]
	v_mfma_f32_16x16x32_bf16 v[90:93], v[126:129], v[216:219], v[90:93]
	v_mfma_f32_16x16x32_bf16 v[86:89], v[150:153], v[216:219], v[86:89]
	v_mfma_f32_16x16x32_bf16 v[162:165], v[130:133], v[182:185], v[162:165]
	v_mfma_f32_16x16x32_bf16 v[158:161], v[154:157], v[182:185], v[158:161]
	v_mfma_f32_16x16x32_bf16 v[146:149], v[130:133], v[190:193], v[146:149]
	v_mfma_f32_16x16x32_bf16 v[142:145], v[154:157], v[190:193], v[142:145]
	v_mfma_f32_16x16x32_bf16 v[122:125], v[130:133], v[212:215], v[122:125]
	v_mfma_f32_16x16x32_bf16 v[118:121], v[154:157], v[212:215], v[118:121]
	v_mfma_f32_16x16x32_bf16 v[90:93], v[130:133], v[220:223], v[90:93]
	v_mfma_f32_16x16x32_bf16 v[86:89], v[154:157], v[220:223], v[86:89]
	s_setprio 0
	s_barrier
; #define PG8_STAGE(bufoff, gbase, voff) do { _Pragma("unroll") for (int _i = 0; _i < 2; ++_i) \
;         __builtin_amdgcn_global_load_lds((const unsigned*)((const char*)(gbase) + (voff)[_i]), (LAS unsigned*)(lds + (bufoff) + ldsw + _i * 8192), 16, 0, 0); } while (0)
; #define PG8_LDA(dst, b, h) do { _Pragma("unroll") for (int m = 0; m < 4; ++m) _Pragma("unroll") for (int k = 0; k < 2; ++k) dst[m][k] = *(const LAS bf16x8*)(lds + PG8_SA(b, h) + aoff + m * 2048 + k * 1024); } while (0)
; #define PG8_MMA(ai, bj, At, Bt) do { __builtin_amdgcn_s_setprio(1); _Pragma("unroll") for (int m = 0; m < 4; ++m) _Pragma("unroll") for (int n = 0; n < 2; ++n) _Pragma("unroll") for (int k = 0; k < 2; ++k) \
;         acc[ai][bj][m][n] = __builtin_amdgcn_mfma_f32_16x16x32_bf16(Bt[n][k], At[m][k], acc[ai][bj][m][n], 0, 0, 0); __builtin_amdgcn_s_setprio(0); } while (0)
; #define PG8_WAIT_V(n) asm volatile("s_waitcnt vmcnt(" #n ")" ::: "memory")
; #define PG8_WAIT_L(n) asm volatile("s_waitcnt lgkmcnt(" #n ")" ::: "memory")
; #define PG8_BAR __builtin_amdgcn_s_barrier()
; #define PG8_SCHED __builtin_amdgcn_sched_barrier(0)
; template <class Epi, class Sched, bool ALIGN_EPI>
; DI void gemm_phase(LAS unsigned char* lds, const Gemm g, const Sched& Sc, const Epi& E, const int tid) {
;     ...
;             PG8_LDA(At, 1, 1); PG8_STAGE(PG8_SB(1, 0), b3, voffB); PG8_STAGE(PG8_SB(1, 1), b3 + hB, voffB); PG8_STAGE(PG8_SA(1, 0), a3, voffA);
;             PG8_WAIT_V(8); PG8_WAIT_L(0); PG8_BAR; PG8_MMA(1, 0, At, B0); PG8_MMA(1, 1, At, B1); PG8_BAR; PG8_SCHED;
;         }
;         if constexpr (ALIGN_EPI) { if (wr == 0) PG8_BAR; }
	s_mov_b32 m0, s62
	v_lshl_add_u64 v[24:25], v[224:225], 0, s[60:61]
	s_add_u32 s42, s42, 0x20080
	ds_read_b128 v[166:169], v210 offset:49152
	ds_read_b128 v[182:185], v210 offset:50176
	ds_read_b128 v[186:189], v210 offset:51200
	ds_read_b128 v[190:193], v210 offset:52224
	ds_read_b128 v[198:201], v210 offset:53248
	ds_read_b128 v[212:215], v210 offset:54272
	ds_read_b128 v[216:219], v210 offset:55296
	ds_read_b128 v[220:223], v210 offset:56320
	global_load_lds_dwordx4 v[24:25], off
	v_lshl_add_u64 v[24:25], v[226:227], 0, s[60:61]
	s_mov_b32 m0, s63
	s_addc_u32 s43, s43, 0
	global_load_lds_dwordx4 v[24:25], off
	v_lshl_add_u64 v[24:25], s[42:43], 0, v[172:173]
	s_mov_b32 m0, s67
	s_nop 0
	global_load_lds_dwordx4 v[24:25], off
	v_lshl_add_u64 v[24:25], s[42:43], 0, v[176:177]
	s_mov_b32 m0, s68
	s_nop 0
	global_load_lds_dwordx4 v[24:25], off
	v_lshl_add_u64 v[24:25], v[228:229], 0, s[60:61]
	s_mov_b32 m0, s64
	s_nop 0
	global_load_lds_dwordx4 v[24:25], off
	v_lshl_add_u64 v[24:25], v[230:231], 0, s[60:61]
	s_mov_b32 m0, s65
	s_nop 0
	global_load_lds_dwordx4 v[24:25], off
	s_waitcnt vmcnt(8)
	s_waitcnt lgkmcnt(0)
	s_barrier
	s_setprio 1
	s_waitcnt lgkmcnt(0)
	v_mfma_f32_16x16x32_bf16 v[66:69], v[70:73], v[166:169], v[66:69]
	v_mfma_f32_16x16x32_bf16 v[62:65], v[94:97], v[166:169], v[62:65]
	v_mfma_f32_16x16x32_bf16 v[50:53], v[70:73], v[186:189], v[50:53]
	v_mfma_f32_16x16x32_bf16 v[46:49], v[94:97], v[186:189], v[46:49]
	v_mfma_f32_16x16x32_bf16 v[34:37], v[70:73], v[198:201], v[34:37]
	v_mfma_f32_16x16x32_bf16 v[30:33], v[94:97], v[198:201], v[30:33]
	v_mfma_f32_16x16x32_bf16 v[14:17], v[70:73], v[216:219], v[14:17]
	v_mfma_f32_16x16x32_bf16 v[10:13], v[94:97], v[216:219], v[10:13]
	v_mfma_f32_16x16x32_bf16 v[66:69], v[74:77], v[182:185], v[66:69]
	v_mfma_f32_16x16x32_bf16 v[62:65], v[98:101], v[182:185], v[62:65]
	v_mfma_f32_16x16x32_bf16 v[50:53], v[74:77], v[190:193], v[50:53]
	v_mfma_f32_16x16x32_bf16 v[46:49], v[98:101], v[190:193], v[46:49]
	v_mfma_f32_16x16x32_bf16 v[34:37], v[74:77], v[212:215], v[34:37]
	v_mfma_f32_16x16x32_bf16 v[30:33], v[98:101], v[212:215], v[30:33]
	v_mfma_f32_16x16x32_bf16 v[14:17], v[74:77], v[220:223], v[14:17]
	v_mfma_f32_16x16x32_bf16 v[10:13], v[98:101], v[220:223], v[10:13]
	s_setprio 0
	s_setprio 1
	v_mfma_f32_16x16x32_bf16 v[58:61], v[126:129], v[166:169], v[58:61]
	v_mfma_f32_16x16x32_bf16 v[54:57], v[150:153], v[166:169], v[54:57]
	v_mfma_f32_16x16x32_bf16 v[42:45], v[126:129], v[186:189], v[42:45]
	v_mfma_f32_16x16x32_bf16 v[38:41], v[150:153], v[186:189], v[38:41]
	v_mfma_f32_16x16x32_bf16 v[24:27], v[126:129], v[198:201], v[26:29]
	v_mfma_f32_16x16x32_bf16 v[20:23], v[150:153], v[198:201], v[20:23]
	v_mfma_f32_16x16x32_bf16 v[6:9], v[126:129], v[216:219], v[6:9]
	v_mfma_f32_16x16x32_bf16 v[2:5], v[150:153], v[216:219], v[2:5]
	v_mfma_f32_16x16x32_bf16 v[58:61], v[130:133], v[182:185], v[58:61]
	v_mfma_f32_16x16x32_bf16 v[54:57], v[154:157], v[182:185], v[54:57]
	v_mfma_f32_16x16x32_bf16 v[42:45], v[130:133], v[190:193], v[42:45]
	v_mfma_f32_16x16x32_bf16 v[38:41], v[154:157], v[190:193], v[38:41]
	v_mfma_f32_16x16x32_bf16 v[26:29], v[130:133], v[212:215], v[24:27]
	v_mfma_f32_16x16x32_bf16 v[22:25], v[154:157], v[212:215], v[20:23]
	v_mfma_f32_16x16x32_bf16 v[6:9], v[130:133], v[220:223], v[6:9]
	v_mfma_f32_16x16x32_bf16 v[2:5], v[154:157], v[220:223], v[2:5]
	s_add_i32 s77, s77, 2
	s_add_u32 s75, s75, 0x100
	s_addc_u32 s76, s76, 0
	s_add_u32 s40, s40, 0x100
	s_addc_u32 s41, s41, 0
	s_cmp_gt_u32 s77, 5
	s_setprio 0
	s_barrier
	s_cbranch_scc0 .LBB0_2429
	s_and_b64 vcc, exec, s[12:13]
	s_cbranch_vccz .LBB0_2432
	s_barrier

; #define PG8_STAGE(bufoff, gbase, voff) do { _Pragma("unroll") for (int _i = 0; _i < 2; ++_i) \
;         __builtin_amdgcn_global_load_lds((const unsigned*)((const char*)(gbase) + (voff)[_i]), (LAS unsigned*)(lds + (bufoff) + ldsw + _i * 8192), 16, 0, 0); } while (0)
; #define PG8_LDA(dst, b, h) do { _Pragma("unroll") for (int m = 0; m < 4; ++m) _Pragma("unroll") for (int k = 0; k < 2; ++k) dst[m][k] = *(const LAS bf16x8*)(lds + PG8_SA(b, h) + aoff + m * 2048 + k * 1024); } while (0)
; #define PG8_LDB(dst, b, h) do { _Pragma("unroll") for (int n = 0; n < 2; ++n) _Pragma("unroll") for (int k = 0; k < 2; ++k) dst[n][k] = *(const LAS bf16x8*)(lds + PG8_SB(b, h) + boff + n * 2048 + k * 1024); } while (0)
; #define PG8_MMA(ai, bj, At, Bt) do { __builtin_amdgcn_s_setprio(1); _Pragma("unroll") for (int m = 0; m < 4; ++m) _Pragma("unroll") for (int n = 0; n < 2; ++n) _Pragma("unroll") for (int k = 0; k < 2; ++k) \
;         acc[ai][bj][m][n] = __builtin_amdgcn_mfma_f32_16x16x32_bf16(Bt[n][k], At[m][k], acc[ai][bj][m][n], 0, 0, 0); __builtin_amdgcn_s_setprio(0); } while (0)
; #define PG8_WAIT_V(n) asm volatile("s_waitcnt vmcnt(" #n ")" ::: "memory")
; #define PG8_WAIT_L(n) asm volatile("s_waitcnt lgkmcnt(" #n ")" ::: "memory")
; #define PG8_BAR __builtin_amdgcn_s_barrier()
; #define PG8_SCHED __builtin_amdgcn_sched_barrier(0)
; template <class Epi, class Sched, bool ALIGN_EPI>
; DI void gemm_phase(LAS unsigned char* lds, const Gemm g, const Sched& Sc, const Epi& E, const int tid) {
;     ...
;             const bool last = (t == nt - 2);
;             const char* a1 = cA + (size_t)(t + 1) * kstep;
;             const char* a2 = last ? nA : cA + (size_t)(t + 2) * kstep; const char* b2 = last ? nB : cB + (size_t)(t + 2) * kstep;
;             const char* a3 = a2 + kstep; const char* b3 = b2 + kstep;
;             PG8_LDB(B0, 0, 0); PG8_LDB(B1, 0, 1); PG8_SCHED; PG8_LDA(At, 0, 0); PG8_STAGE(PG8_SA(1, 1), a1 + hA, voffA);
;             PG8_WAIT_V(8); PG8_WAIT_L(0); PG8_BAR; PG8_MMA(0, 0, At, B0); PG8_MMA(0, 1, At, B1); PG8_BAR; PG8_SCHED;
.LBB0_2541:
	v_add_u32_e32 v144, s52, v216
	v_add_u32_e32 v160, s55, v216
	ds_read_b128 v[132:135], v144
	ds_read_b128 v[136:139], v144 offset:1024
	ds_read_b128 v[140:143], v144 offset:2048
	ds_read_b128 v[144:147], v144 offset:3072
	ds_read_b128 v[148:151], v160
	ds_read_b128 v[152:155], v160 offset:1024
	ds_read_b128 v[156:159], v160 offset:2048
	ds_read_b128 v[160:163], v160 offset:3072
	s_add_u32 s46, s44, 0xfff80080
	s_addc_u32 s47, s45, -1
	s_cmp_eq_u32 s81, 28
	s_cselect_b32 s49, s27, s47
	s_cselect_b32 s48, s43, s46
	s_cselect_b32 s47, s23, s80
	s_cselect_b32 s46, s78, s79
	v_lshl_add_u64 v[194:195], s[44:45], 0, v[188:189]
	s_add_i32 m0, s62, 0xc000
	ds_read_b128 v[164:167], v218
	ds_read_b128 v[168:171], v218 offset:1024
	ds_read_b128 v[172:175], v218 offset:2048
	ds_read_b128 v[176:179], v218 offset:3072
	ds_read_b128 v[190:193], v218 offset:4096
	ds_read_b128 v[198:201], v218 offset:5120
	ds_read_b128 v[210:213], v218 offset:6144
	ds_read_b128 v[220:223], v218 offset:7168
	global_load_lds_dwordx4 v[194:195], off
	v_lshl_add_u64 v[194:195], s[44:45], 0, v[186:187]
	s_add_i32 m0, s62, 0xe000
	s_nop 0
	global_load_lds_dwordx4 v[194:195], off
	s_waitcnt vmcnt(8)
	s_waitcnt lgkmcnt(0)
	s_barrier
	s_setprio 1
	s_waitcnt lgkmcnt(0)
	v_mfma_f32_16x16x32_bf16 v[128:131], v[132:135], v[164:167], v[128:131]
	v_mfma_f32_16x16x32_bf16 v[124:127], v[140:143], v[164:167], v[124:127]
	v_mfma_f32_16x16x32_bf16 v[112:115], v[132:135], v[172:175], v[112:115]
	v_mfma_f32_16x16x32_bf16 v[108:111], v[140:143], v[172:175], v[108:111]
	v_mfma_f32_16x16x32_bf16 v[96:99], v[132:135], v[190:193], v[96:99]
	v_mfma_f32_16x16x32_bf16 v[92:95], v[140:143], v[190:193], v[92:95]
	v_mfma_f32_16x16x32_bf16 v[80:83], v[132:135], v[210:213], v[80:83]
	v_mfma_f32_16x16x32_bf16 v[76:79], v[140:143], v[210:213], v[76:79]
	v_mfma_f32_16x16x32_bf16 v[128:131], v[136:139], v[168:171], v[128:131]
	v_mfma_f32_16x16x32_bf16 v[124:127], v[144:147], v[168:171], v[124:127]
	v_mfma_f32_16x16x32_bf16 v[112:115], v[136:139], v[176:179], v[112:115]
	v_mfma_f32_16x16x32_bf16 v[108:111], v[144:147], v[176:179], v[108:111]
	v_mfma_f32_16x16x32_bf16 v[96:99], v[136:139], v[198:201], v[96:99]
	v_mfma_f32_16x16x32_bf16 v[92:95], v[144:147], v[198:201], v[92:95]
	v_mfma_f32_16x16x32_bf16 v[80:83], v[136:139], v[220:223], v[80:83]
	v_mfma_f32_16x16x32_bf16 v[76:79], v[144:147], v[220:223], v[76:79]
	s_setprio 0
	s_setprio 1
	v_mfma_f32_16x16x32_bf16 v[120:123], v[148:151], v[164:167], v[120:123]
	v_mfma_f32_16x16x32_bf16 v[116:119], v[156:159], v[164:167], v[116:119]
	v_mfma_f32_16x16x32_bf16 v[104:107], v[148:151], v[172:175], v[104:107]
	v_mfma_f32_16x16x32_bf16 v[100:103], v[156:159], v[172:175], v[100:103]
	v_mfma_f32_16x16x32_bf16 v[88:91], v[148:151], v[190:193], v[88:91]
	v_mfma_f32_16x16x32_bf16 v[84:87], v[156:159], v[190:193], v[84:87]
	v_mfma_f32_16x16x32_bf16 v[72:75], v[148:151], v[210:213], v[72:75]
	v_mfma_f32_16x16x32_bf16 v[68:71], v[156:159], v[210:213], v[68:71]
	v_mfma_f32_16x16x32_bf16 v[120:123], v[152:155], v[168:171], v[120:123]
	v_mfma_f32_16x16x32_bf16 v[116:119], v[160:163], v[168:171], v[116:119]
	v_mfma_f32_16x16x32_bf16 v[104:107], v[152:155], v[176:179], v[104:107]
	v_mfma_f32_16x16x32_bf16 v[100:103], v[160:163], v[176:179], v[100:103]
	v_mfma_f32_16x16x32_bf16 v[88:91], v[152:155], v[198:201], v[88:91]
	v_mfma_f32_16x16x32_bf16 v[84:87], v[160:163], v[198:201], v[84:87]
	v_mfma_f32_16x16x32_bf16 v[72:75], v[152:155], v[220:223], v[72:75]
	v_mfma_f32_16x16x32_bf16 v[68:71], v[160:163], v[220:223], v[68:71]
	s_setprio 0
	s_barrier
	s_mov_b32 m0, s53
	v_lshl_add_u64 v[194:195], s[46:47], 0, v[18:19]
	s_add_u32 s82, s46, 0x80000
	ds_read_b128 v[164:167], v218 offset:16384
	ds_read_b128 v[168:171], v218 offset:17408
	ds_read_b128 v[172:175], v218 offset:18432
	ds_read_b128 v[176:179], v218 offset:19456
	ds_read_b128 v[190:193], v218 offset:20480
	ds_read_b128 v[198:201], v218 offset:21504
	ds_read_b128 v[210:213], v218 offset:22528
	ds_read_b128 v[220:223], v218 offset:23552
	global_load_lds_dwordx4 v[194:195], off
	v_lshl_add_u64 v[214:215], s[46:47], 0, v[184:185]
	s_mov_b32 m0, s54
	s_addc_u32 s83, s47, 0
	global_load_lds_dwordx4 v[214:215], off
	v_lshl_add_u64 v[224:225], s[82:83], 0, v[18:19]
	s_mov_b32 m0, s56
	v_lshl_add_u64 v[226:227], s[48:49], 0, v[182:183]
	global_load_lds_dwordx4 v[224:225], off
	v_lshl_add_u64 v[224:225], s[82:83], 0, v[184:185]
	s_mov_b32 m0, s57
	s_nop 0
	global_load_lds_dwordx4 v[224:225], off
	v_lshl_add_u64 v[224:225], s[48:49], 0, v[180:181]
	s_mov_b32 m0, s62
	s_nop 0
	global_load_lds_dwordx4 v[224:225], off
	s_mov_b32 m0, s63
	s_nop 0
	global_load_lds_dwordx4 v[226:227], off
	s_waitcnt vmcnt(8)
	s_waitcnt lgkmcnt(0)
	s_barrier
; #define PG8_STAGE(bufoff, gbase, voff) do { _Pragma("unroll") for (int _i = 0; _i < 2; ++_i) \
;         __builtin_amdgcn_global_load_lds((const unsigned*)((const char*)(gbase) + (voff)[_i]), (LAS unsigned*)(lds + (bufoff) + ldsw + _i * 8192), 16, 0, 0); } while (0)
; #define PG8_LDA(dst, b, h) do { _Pragma("unroll") for (int m = 0; m < 4; ++m) _Pragma("unroll") for (int k = 0; k < 2; ++k) dst[m][k] = *(const LAS bf16x8*)(lds + PG8_SA(b, h) + aoff + m * 2048 + k * 1024); } while (0)
; #define PG8_LDB(dst, b, h) do { _Pragma("unroll") for (int n = 0; n < 2; ++n) _Pragma("unroll") for (int k = 0; k < 2; ++k) dst[n][k] = *(const LAS bf16x8*)(lds + PG8_SB(b, h) + boff + n * 2048 + k * 1024); } while (0)
; #define PG8_MMA(ai, bj, At, Bt) do { __builtin_amdgcn_s_setprio(1); _Pragma("unroll") for (int m = 0; m < 4; ++m) _Pragma("unroll") for (int n = 0; n < 2; ++n) _Pragma("unroll") for (int k = 0; k < 2; ++k) \
;         acc[ai][bj][m][n] = __builtin_amdgcn_mfma_f32_16x16x32_bf16(Bt[n][k], At[m][k], acc[ai][bj][m][n], 0, 0, 0); __builtin_amdgcn_s_setprio(0); } while (0)
; #define PG8_WAIT_V(n) asm volatile("s_waitcnt vmcnt(" #n ")" ::: "memory")
; #define PG8_WAIT_L(n) asm volatile("s_waitcnt lgkmcnt(" #n ")" ::: "memory")
; #define PG8_BAR __builtin_amdgcn_s_barrier()
; #define PG8_SCHED __builtin_amdgcn_sched_barrier(0)
; template <class Epi, class Sched, bool ALIGN_EPI>
; DI void gemm_phase(LAS unsigned char* lds, const Gemm g, const Sched& Sc, const Epi& E, const int tid) {
;     ...
;             PG8_LDA(At, 0, 1); PG8_STAGE(PG8_SB(0, 0), b2, voffB); PG8_STAGE(PG8_SB(0, 1), b2 + hB, voffB); PG8_STAGE(PG8_SA(0, 0), a2, voffA);
;             PG8_WAIT_V(8); PG8_WAIT_L(0); PG8_BAR; PG8_MMA(1, 0, At, B0); PG8_MMA(1, 1, At, B1); PG8_BAR; PG8_SCHED;
;             PG8_LDB(B0, 1, 0); PG8_LDB(B1, 1, 1); PG8_SCHED; PG8_LDA(At, 1, 0); PG8_STAGE(PG8_SA(0, 1), a2 + hA, voffA);
;             PG8_WAIT_V(8); PG8_WAIT_L(0); PG8_BAR; PG8_MMA(0, 0, At, B0); PG8_MMA(0, 1, At, B1); PG8_BAR; PG8_SCHED;
	s_setprio 1
	s_waitcnt lgkmcnt(0)
	v_mfma_f32_16x16x32_bf16 v[64:67], v[132:135], v[164:167], v[64:67]
	v_mfma_f32_16x16x32_bf16 v[60:63], v[140:143], v[164:167], v[60:63]
	v_mfma_f32_16x16x32_bf16 v[48:51], v[132:135], v[172:175], v[48:51]
	v_mfma_f32_16x16x32_bf16 v[44:47], v[140:143], v[172:175], v[44:47]
	v_mfma_f32_16x16x32_bf16 v[32:35], v[132:135], v[190:193], v[32:35]
	v_mfma_f32_16x16x32_bf16 v[28:31], v[140:143], v[190:193], v[28:31]
	v_mfma_f32_16x16x32_bf16 v[14:17], v[132:135], v[210:213], v[14:17]
	v_mfma_f32_16x16x32_bf16 v[10:13], v[140:143], v[210:213], v[10:13]
	v_mfma_f32_16x16x32_bf16 v[64:67], v[136:139], v[168:171], v[64:67]
	v_mfma_f32_16x16x32_bf16 v[60:63], v[144:147], v[168:171], v[60:63]
	v_mfma_f32_16x16x32_bf16 v[48:51], v[136:139], v[176:179], v[48:51]
	v_mfma_f32_16x16x32_bf16 v[44:47], v[144:147], v[176:179], v[44:47]
	v_mfma_f32_16x16x32_bf16 v[32:35], v[136:139], v[198:201], v[32:35]
	v_mfma_f32_16x16x32_bf16 v[28:31], v[144:147], v[198:201], v[28:31]
	v_mfma_f32_16x16x32_bf16 v[14:17], v[136:139], v[220:223], v[14:17]
	v_mfma_f32_16x16x32_bf16 v[10:13], v[144:147], v[220:223], v[10:13]
	s_setprio 0
	s_setprio 1
	v_mfma_f32_16x16x32_bf16 v[56:59], v[148:151], v[164:167], v[56:59]
	v_mfma_f32_16x16x32_bf16 v[52:55], v[156:159], v[164:167], v[52:55]
	v_mfma_f32_16x16x32_bf16 v[40:43], v[148:151], v[172:175], v[40:43]
	v_mfma_f32_16x16x32_bf16 v[36:39], v[156:159], v[172:175], v[36:39]
	v_mfma_f32_16x16x32_bf16 v[24:27], v[148:151], v[190:193], v[24:27]
	v_mfma_f32_16x16x32_bf16 v[20:23], v[156:159], v[190:193], v[20:23]
	v_mfma_f32_16x16x32_bf16 v[6:9], v[148:151], v[210:213], v[6:9]
	v_mfma_f32_16x16x32_bf16 v[2:5], v[156:159], v[210:213], v[2:5]
	v_mfma_f32_16x16x32_bf16 v[56:59], v[152:155], v[168:171], v[56:59]
	v_mfma_f32_16x16x32_bf16 v[52:55], v[160:163], v[168:171], v[52:55]
	v_mfma_f32_16x16x32_bf16 v[40:43], v[152:155], v[176:179], v[40:43]
	v_mfma_f32_16x16x32_bf16 v[36:39], v[160:163], v[176:179], v[36:39]
	v_mfma_f32_16x16x32_bf16 v[24:27], v[152:155], v[198:201], v[24:27]
	v_mfma_f32_16x16x32_bf16 v[20:23], v[160:163], v[198:201], v[20:23]
	v_mfma_f32_16x16x32_bf16 v[6:9], v[152:155], v[220:223], v[6:9]
	v_mfma_f32_16x16x32_bf16 v[2:5], v[160:163], v[220:223], v[2:5]
	s_setprio 0
	s_barrier
	v_add_u32_e32 v144, s67, v216
	v_add_u32_e32 v160, s72, v216
	ds_read_b128 v[132:135], v144
	ds_read_b128 v[136:139], v144 offset:1024
	ds_read_b128 v[140:143], v144 offset:2048
	ds_read_b128 v[144:147], v144 offset:3072
	ds_read_b128 v[148:151], v160
	ds_read_b128 v[152:155], v160 offset:1024
	ds_read_b128 v[156:159], v160 offset:2048
	ds_read_b128 v[160:163], v160 offset:3072
	s_add_u32 s48, s48, 0x80000
	s_addc_u32 s49, s49, 0
	s_mov_b32 m0, s64
	v_lshl_add_u64 v[228:229], s[48:49], 0, v[180:181]
	ds_read_b128 v[164:167], v218 offset:32768
	ds_read_b128 v[168:171], v218 offset:33792
	ds_read_b128 v[172:175], v218 offset:34816
	ds_read_b128 v[176:179], v218 offset:35840
	ds_read_b128 v[190:193], v218 offset:36864
	ds_read_b128 v[198:201], v218 offset:37888
	ds_read_b128 v[210:213], v218 offset:38912
	ds_read_b128 v[220:223], v218 offset:39936
	global_load_lds_dwordx4 v[228:229], off
	v_lshl_add_u64 v[228:229], s[48:49], 0, v[182:183]
	s_mov_b32 m0, s65
	s_nop 0
	global_load_lds_dwordx4 v[228:229], off
	s_waitcnt vmcnt(8)
	s_waitcnt lgkmcnt(0)
	s_barrier
	s_setprio 1
	s_waitcnt lgkmcnt(0)
	v_mfma_f32_16x16x32_bf16 v[128:131], v[132:135], v[164:167], v[128:131]
	v_mfma_f32_16x16x32_bf16 v[124:127], v[140:143], v[164:167], v[124:127]
	v_mfma_f32_16x16x32_bf16 v[112:115], v[132:135], v[172:175], v[112:115]
	v_mfma_f32_16x16x32_bf16 v[108:111], v[140:143], v[172:175], v[108:111]
	v_mfma_f32_16x16x32_bf16 v[96:99], v[132:135], v[190:193], v[96:99]
	v_mfma_f32_16x16x32_bf16 v[92:95], v[140:143], v[190:193], v[92:95]
	v_mfma_f32_16x16x32_bf16 v[80:83], v[132:135], v[210:213], v[80:83]
	v_mfma_f32_16x16x32_bf16 v[76:79], v[140:143], v[210:213], v[76:79]
	v_mfma_f32_16x16x32_bf16 v[128:131], v[136:139], v[168:171], v[128:131]
	v_mfma_f32_16x16x32_bf16 v[124:127], v[144:147], v[168:171], v[124:127]
	v_mfma_f32_16x16x32_bf16 v[112:115], v[136:139], v[176:179], v[112:115]
	v_mfma_f32_16x16x32_bf16 v[108:111], v[144:147], v[176:179], v[108:111]
	v_mfma_f32_16x16x32_bf16 v[96:99], v[136:139], v[198:201], v[96:99]
	v_mfma_f32_16x16x32_bf16 v[92:95], v[144:147], v[198:201], v[92:95]
	v_mfma_f32_16x16x32_bf16 v[80:83], v[136:139], v[220:223], v[80:83]
	v_mfma_f32_16x16x32_bf16 v[76:79], v[144:147], v[220:223], v[76:79]
	s_setprio 0
	s_setprio 1
	v_mfma_f32_16x16x32_bf16 v[120:123], v[148:151], v[164:167], v[120:123]
	v_mfma_f32_16x16x32_bf16 v[116:119], v[156:159], v[164:167], v[116:119]
	v_mfma_f32_16x16x32_bf16 v[104:107], v[148:151], v[172:175], v[104:107]
	v_mfma_f32_16x16x32_bf16 v[100:103], v[156:159], v[172:175], v[100:103]
	v_mfma_f32_16x16x32_bf16 v[88:91], v[148:151], v[190:193], v[88:91]
	v_mfma_f32_16x16x32_bf16 v[84:87], v[156:159], v[190:193], v[84:87]
	v_mfma_f32_16x16x32_bf16 v[72:75], v[148:151], v[210:213], v[72:75]
	v_mfma_f32_16x16x32_bf16 v[68:71], v[156:159], v[210:213], v[68:71]
	v_mfma_f32_16x16x32_bf16 v[120:123], v[152:155], v[168:171], v[120:123]
	v_mfma_f32_16x16x32_bf16 v[116:119], v[160:163], v[168:171], v[116:119]
	v_mfma_f32_16x16x32_bf16 v[104:107], v[152:155], v[176:179], v[104:107]
	v_mfma_f32_16x16x32_bf16 v[100:103], v[160:163], v[176:179], v[100:103]
	v_mfma_f32_16x16x32_bf16 v[88:91], v[152:155], v[198:201], v[88:91]
	v_mfma_f32_16x16x32_bf16 v[84:87], v[160:163], v[198:201], v[84:87]
	v_mfma_f32_16x16x32_bf16 v[72:75], v[152:155], v[220:223], v[72:75]
	v_mfma_f32_16x16x32_bf16 v[68:71], v[160:163], v[220:223], v[68:71]
	s_setprio 0
	s_barrier
; #define PG8_STAGE(bufoff, gbase, voff) do { _Pragma("unroll") for (int _i = 0; _i < 2; ++_i) \
;         __builtin_amdgcn_global_load_lds((const unsigned*)((const char*)(gbase) + (voff)[_i]), (LAS unsigned*)(lds + (bufoff) + ldsw + _i * 8192), 16, 0, 0); } while (0)
; #define PG8_LDA(dst, b, h) do { _Pragma("unroll") for (int m = 0; m < 4; ++m) _Pragma("unroll") for (int k = 0; k < 2; ++k) dst[m][k] = *(const LAS bf16x8*)(lds + PG8_SA(b, h) + aoff + m * 2048 + k * 1024); } while (0)
; #define PG8_MMA(ai, bj, At, Bt) do { __builtin_amdgcn_s_setprio(1); _Pragma("unroll") for (int m = 0; m < 4; ++m) _Pragma("unroll") for (int n = 0; n < 2; ++n) _Pragma("unroll") for (int k = 0; k < 2; ++k) \
;         acc[ai][bj][m][n] = __builtin_amdgcn_mfma_f32_16x16x32_bf16(Bt[n][k], At[m][k], acc[ai][bj][m][n], 0, 0, 0); __builtin_amdgcn_s_setprio(0); } while (0)
; #define PG8_WAIT_V(n) asm volatile("s_waitcnt vmcnt(" #n ")" ::: "memory")
; #define PG8_WAIT_L(n) asm volatile("s_waitcnt lgkmcnt(" #n ")" ::: "memory")
; #define PG8_BAR __builtin_amdgcn_s_barrier()
; #define PG8_SCHED __builtin_amdgcn_sched_barrier(0)
; template <class Epi, class Sched, bool ALIGN_EPI>
; DI void gemm_phase(LAS unsigned char* lds, const Gemm g, const Sched& Sc, const Epi& E, const int tid) {
;     ...
;             PG8_LDA(At, 1, 1); PG8_STAGE(PG8_SB(1, 0), b3, voffB); PG8_STAGE(PG8_SB(1, 1), b3 + hB, voffB); PG8_STAGE(PG8_SA(1, 0), a3, voffA);
;             PG8_WAIT_V(8); PG8_WAIT_L(0); PG8_BAR; PG8_MMA(1, 0, At, B0); PG8_MMA(1, 1, At, B1); PG8_BAR; PG8_SCHED;
;         }
;         if constexpr (ALIGN_EPI) { if (wr == 0) PG8_BAR; }
	s_mov_b32 m0, s68
	v_lshl_add_u64 v[194:195], v[194:195], 0, s[60:61]
	s_add_u32 s46, s46, 0x80080
	ds_read_b128 v[164:167], v218 offset:49152
	ds_read_b128 v[168:171], v218 offset:50176
	ds_read_b128 v[172:175], v218 offset:51200
	ds_read_b128 v[176:179], v218 offset:52224
	ds_read_b128 v[190:193], v218 offset:53248
	ds_read_b128 v[198:201], v218 offset:54272
	ds_read_b128 v[210:213], v218 offset:55296
	ds_read_b128 v[220:223], v218 offset:56320
	global_load_lds_dwordx4 v[194:195], off
	v_lshl_add_u64 v[194:195], v[214:215], 0, s[60:61]
	s_mov_b32 m0, s69
	s_addc_u32 s47, s47, 0
	global_load_lds_dwordx4 v[194:195], off
	v_lshl_add_u64 v[194:195], s[46:47], 0, v[18:19]
	s_mov_b32 m0, s73
	s_nop 0
	global_load_lds_dwordx4 v[194:195], off
	v_lshl_add_u64 v[194:195], s[46:47], 0, v[184:185]
	s_mov_b32 m0, s74
	s_nop 0
	global_load_lds_dwordx4 v[194:195], off
	v_lshl_add_u64 v[194:195], v[224:225], 0, s[60:61]
	s_mov_b32 m0, s70
	s_nop 0
	global_load_lds_dwordx4 v[194:195], off
	v_lshl_add_u64 v[194:195], v[226:227], 0, s[60:61]
	s_mov_b32 m0, s71
	s_nop 0
	global_load_lds_dwordx4 v[194:195], off
	s_waitcnt vmcnt(8)
	s_waitcnt lgkmcnt(0)
	s_barrier
	s_setprio 1
	s_waitcnt lgkmcnt(0)
	v_mfma_f32_16x16x32_bf16 v[64:67], v[132:135], v[164:167], v[64:67]
	v_mfma_f32_16x16x32_bf16 v[60:63], v[140:143], v[164:167], v[60:63]
	v_mfma_f32_16x16x32_bf16 v[48:51], v[132:135], v[172:175], v[48:51]
	v_mfma_f32_16x16x32_bf16 v[44:47], v[140:143], v[172:175], v[44:47]
	v_mfma_f32_16x16x32_bf16 v[32:35], v[132:135], v[190:193], v[32:35]
	v_mfma_f32_16x16x32_bf16 v[28:31], v[140:143], v[190:193], v[28:31]
	v_mfma_f32_16x16x32_bf16 v[14:17], v[132:135], v[210:213], v[14:17]
	v_mfma_f32_16x16x32_bf16 v[10:13], v[140:143], v[210:213], v[10:13]
	v_mfma_f32_16x16x32_bf16 v[64:67], v[136:139], v[168:171], v[64:67]
	v_mfma_f32_16x16x32_bf16 v[60:63], v[144:147], v[168:171], v[60:63]
	v_mfma_f32_16x16x32_bf16 v[48:51], v[136:139], v[176:179], v[48:51]
	v_mfma_f32_16x16x32_bf16 v[44:47], v[144:147], v[176:179], v[44:47]
	v_mfma_f32_16x16x32_bf16 v[32:35], v[136:139], v[198:201], v[32:35]
	v_mfma_f32_16x16x32_bf16 v[28:31], v[144:147], v[198:201], v[28:31]
	v_mfma_f32_16x16x32_bf16 v[14:17], v[136:139], v[220:223], v[14:17]
	v_mfma_f32_16x16x32_bf16 v[10:13], v[144:147], v[220:223], v[10:13]
	s_setprio 0
	s_setprio 1
	v_mfma_f32_16x16x32_bf16 v[56:59], v[148:151], v[164:167], v[56:59]
	v_mfma_f32_16x16x32_bf16 v[52:55], v[156:159], v[164:167], v[52:55]
	v_mfma_f32_16x16x32_bf16 v[40:43], v[148:151], v[172:175], v[40:43]
	v_mfma_f32_16x16x32_bf16 v[36:39], v[156:159], v[172:175], v[36:39]
	v_mfma_f32_16x16x32_bf16 v[24:27], v[148:151], v[190:193], v[24:27]
	v_mfma_f32_16x16x32_bf16 v[20:23], v[156:159], v[190:193], v[20:23]
	v_mfma_f32_16x16x32_bf16 v[6:9], v[148:151], v[210:213], v[6:9]
	v_mfma_f32_16x16x32_bf16 v[2:5], v[156:159], v[210:213], v[2:5]
	v_mfma_f32_16x16x32_bf16 v[56:59], v[152:155], v[168:171], v[56:59]
	v_mfma_f32_16x16x32_bf16 v[52:55], v[160:163], v[168:171], v[52:55]
	v_mfma_f32_16x16x32_bf16 v[40:43], v[152:155], v[176:179], v[40:43]
	v_mfma_f32_16x16x32_bf16 v[36:39], v[160:163], v[176:179], v[36:39]
	v_mfma_f32_16x16x32_bf16 v[24:27], v[152:155], v[198:201], v[24:27]
	v_mfma_f32_16x16x32_bf16 v[20:23], v[160:163], v[198:201], v[20:23]
	v_mfma_f32_16x16x32_bf16 v[6:9], v[152:155], v[220:223], v[6:9]
	v_mfma_f32_16x16x32_bf16 v[2:5], v[160:163], v[220:223], v[2:5]
	s_add_i32 s81, s81, 2
	s_add_u32 s79, s79, 0x100
	s_addc_u32 s80, s80, 0
	s_add_u32 s44, s44, 0x100
	s_addc_u32 s45, s45, 0
	s_cmp_gt_u32 s81, 29
	s_setprio 0
	s_barrier
	s_cbranch_scc0 .LBB0_2541
	s_and_b64 vcc, exec, s[18:19]
	s_cbranch_vccz .LBB0_2544
	s_barrier

; #define PG8_STAGE(bufoff, gbase, voff) do { _Pragma("unroll") for (int _i = 0; _i < 2; ++_i) \
;         __builtin_amdgcn_global_load_lds((const unsigned*)((const char*)(gbase) + (voff)[_i]), (LAS unsigned*)(lds + (bufoff) + ldsw + _i * 8192), 16, 0, 0); } while (0)
; #define PG8_LDA(dst, b, h) do { _Pragma("unroll") for (int m = 0; m < 4; ++m) _Pragma("unroll") for (int k = 0; k < 2; ++k) dst[m][k] = *(const LAS bf16x8*)(lds + PG8_SA(b, h) + aoff + m * 2048 + k * 1024); } while (0)
; #define PG8_LDB(dst, b, h) do { _Pragma("unroll") for (int n = 0; n < 2; ++n) _Pragma("unroll") for (int k = 0; k < 2; ++k) dst[n][k] = *(const LAS bf16x8*)(lds + PG8_SB(b, h) + boff + n * 2048 + k * 1024); } while (0)
; #define PG8_MMA(ai, bj, At, Bt) do { __builtin_amdgcn_s_setprio(1); _Pragma("unroll") for (int m = 0; m < 4; ++m) _Pragma("unroll") for (int n = 0; n < 2; ++n) _Pragma("unroll") for (int k = 0; k < 2; ++k) \
;         acc[ai][bj][m][n] = __builtin_amdgcn_mfma_f32_16x16x32_bf16(Bt[n][k], At[m][k], acc[ai][bj][m][n], 0, 0, 0); __builtin_amdgcn_s_setprio(0); } while (0)
; #define PG8_WAIT_V(n) asm volatile("s_waitcnt vmcnt(" #n ")" ::: "memory")
; #define PG8_WAIT_L(n) asm volatile("s_waitcnt lgkmcnt(" #n ")" ::: "memory")
; #define PG8_BAR __builtin_amdgcn_s_barrier()
; #define PG8_SCHED __builtin_amdgcn_sched_barrier(0)
; template <class Epi, class Sched, bool ALIGN_EPI>
; DI void gemm_phase(LAS unsigned char* lds, const Gemm g, const Sched& Sc, const Epi& E, const int tid) {
;     ...
;             const bool last = (t == nt - 2);
;             const char* a1 = cA + (size_t)(t + 1) * kstep;
;             const char* a2 = last ? nA : cA + (size_t)(t + 2) * kstep; const char* b2 = last ? nB : cB + (size_t)(t + 2) * kstep;
;             const char* a3 = a2 + kstep; const char* b3 = b2 + kstep;
;             PG8_LDB(B0, 0, 0); PG8_LDB(B1, 0, 1); PG8_SCHED; PG8_LDA(At, 0, 0); PG8_STAGE(PG8_SA(1, 1), a1 + hA, voffA);
;             PG8_WAIT_V(8); PG8_WAIT_L(0); PG8_BAR; PG8_MMA(0, 0, At, B0); PG8_MMA(0, 1, At, B1); PG8_BAR; PG8_SCHED;
.LBB0_2634:
	v_add_u32_e32 v147, s39, v143
	ds_read_b128 v[148:151], v147
	ds_read_b128 v[152:155], v147 offset:1024
	ds_read_b128 v[156:159], v147 offset:2048
	ds_read_b128 v[160:163], v147 offset:3072
	v_add_u32_e32 v147, s48, v143
	ds_read_b128 v[164:167], v147
	ds_read_b128 v[168:171], v147 offset:1024
	ds_read_b128 v[172:175], v147 offset:2048
	ds_read_b128 v[176:179], v147 offset:3072
	s_add_u32 s42, s40, 0xfff80080
	s_addc_u32 s43, s41, -1
	s_cmp_eq_u32 s75, 28
	s_cselect_b32 s45, s23, s43
	s_cselect_b32 s44, s71, s42
	s_cselect_b32 s43, s19, s74
	s_cselect_b32 s42, s72, s73
	v_lshl_add_u64 v[222:223], s[40:41], 0, v[140:141]
	s_add_i32 m0, s51, 0xc000
	ds_read_b128 v[180:183], v146
	ds_read_b128 v[184:187], v146 offset:1024
	ds_read_b128 v[188:191], v146 offset:2048
	ds_read_b128 v[192:195], v146 offset:3072
	ds_read_b128 v[198:201], v146 offset:4096
	ds_read_b128 v[210:213], v146 offset:5120
	ds_read_b128 v[214:217], v146 offset:6144
	ds_read_b128 v[218:221], v146 offset:7168
	global_load_lds_dwordx4 v[222:223], off
	v_lshl_add_u64 v[222:223], s[40:41], 0, v[138:139]
	s_add_i32 m0, s51, 0xe000
	s_nop 0
	global_load_lds_dwordx4 v[222:223], off
	s_waitcnt vmcnt(8)
	s_waitcnt lgkmcnt(0)
	s_barrier
	s_setprio 1
	s_waitcnt lgkmcnt(0)
	v_mfma_f32_16x16x32_bf16 v[128:131], v[148:151], v[180:183], v[128:131]
	v_mfma_f32_16x16x32_bf16 v[124:127], v[156:159], v[180:183], v[124:127]
	v_mfma_f32_16x16x32_bf16 v[120:123], v[148:151], v[188:191], v[120:123]
	v_mfma_f32_16x16x32_bf16 v[116:119], v[156:159], v[188:191], v[116:119]
	v_mfma_f32_16x16x32_bf16 v[104:107], v[148:151], v[198:201], v[104:107]
	v_mfma_f32_16x16x32_bf16 v[100:103], v[156:159], v[198:201], v[100:103]
	v_mfma_f32_16x16x32_bf16 v[88:91], v[148:151], v[214:217], v[88:91]
	v_mfma_f32_16x16x32_bf16 v[84:87], v[156:159], v[214:217], v[84:87]
	v_mfma_f32_16x16x32_bf16 v[128:131], v[152:155], v[184:187], v[128:131]
	v_mfma_f32_16x16x32_bf16 v[124:127], v[160:163], v[184:187], v[124:127]
	v_mfma_f32_16x16x32_bf16 v[120:123], v[152:155], v[192:195], v[120:123]
	v_mfma_f32_16x16x32_bf16 v[116:119], v[160:163], v[192:195], v[116:119]
	v_mfma_f32_16x16x32_bf16 v[104:107], v[152:155], v[210:213], v[104:107]
	v_mfma_f32_16x16x32_bf16 v[100:103], v[160:163], v[210:213], v[100:103]
	v_mfma_f32_16x16x32_bf16 v[88:91], v[152:155], v[218:221], v[88:91]
	v_mfma_f32_16x16x32_bf16 v[84:87], v[160:163], v[218:221], v[84:87]
	s_setprio 0
	s_setprio 1
	v_mfma_f32_16x16x32_bf16 v[112:115], v[164:167], v[180:183], v[112:115]
	v_mfma_f32_16x16x32_bf16 v[108:111], v[172:175], v[180:183], v[108:111]
	v_mfma_f32_16x16x32_bf16 v[96:99], v[164:167], v[188:191], v[96:99]
	v_mfma_f32_16x16x32_bf16 v[92:95], v[172:175], v[188:191], v[92:95]
	v_mfma_f32_16x16x32_bf16 v[80:83], v[164:167], v[198:201], v[80:83]
	v_mfma_f32_16x16x32_bf16 v[76:79], v[172:175], v[198:201], v[76:79]
	v_mfma_f32_16x16x32_bf16 v[72:75], v[164:167], v[214:217], v[72:75]
	v_mfma_f32_16x16x32_bf16 v[68:71], v[172:175], v[214:217], v[68:71]
	v_mfma_f32_16x16x32_bf16 v[112:115], v[168:171], v[184:187], v[112:115]
	v_mfma_f32_16x16x32_bf16 v[108:111], v[176:179], v[184:187], v[108:111]
	v_mfma_f32_16x16x32_bf16 v[96:99], v[168:171], v[192:195], v[96:99]
	v_mfma_f32_16x16x32_bf16 v[92:95], v[176:179], v[192:195], v[92:95]
	v_mfma_f32_16x16x32_bf16 v[80:83], v[168:171], v[210:213], v[80:83]
	v_mfma_f32_16x16x32_bf16 v[76:79], v[176:179], v[210:213], v[76:79]
	v_mfma_f32_16x16x32_bf16 v[72:75], v[168:171], v[218:221], v[72:75]
	v_mfma_f32_16x16x32_bf16 v[68:71], v[176:179], v[218:221], v[68:71]
	s_setprio 0
	s_barrier
	s_mov_b32 m0, s46
	v_lshl_add_u64 v[222:223], s[42:43], 0, v[18:19]
	s_add_u32 s76, s42, 0x80000
	ds_read_b128 v[180:183], v146 offset:16384
	ds_read_b128 v[184:187], v146 offset:17408
	ds_read_b128 v[188:191], v146 offset:18432
	ds_read_b128 v[192:195], v146 offset:19456
	ds_read_b128 v[198:201], v146 offset:20480
	ds_read_b128 v[210:213], v146 offset:21504
	ds_read_b128 v[214:217], v146 offset:22528
	ds_read_b128 v[218:221], v146 offset:23552
	global_load_lds_dwordx4 v[222:223], off
	v_lshl_add_u64 v[224:225], s[42:43], 0, v[132:133]
	s_mov_b32 m0, s47
	s_addc_u32 s77, s43, 0
	global_load_lds_dwordx4 v[224:225], off
	v_lshl_add_u64 v[226:227], s[76:77], 0, v[18:19]
	s_mov_b32 m0, s49
	v_lshl_add_u64 v[228:229], s[44:45], 0, v[134:135]
	global_load_lds_dwordx4 v[226:227], off
	v_lshl_add_u64 v[226:227], s[76:77], 0, v[132:133]
	s_mov_b32 m0, s50
	s_nop 0
	global_load_lds_dwordx4 v[226:227], off
	v_lshl_add_u64 v[226:227], s[44:45], 0, v[136:137]
	s_mov_b32 m0, s51
	s_nop 0
	global_load_lds_dwordx4 v[226:227], off
	s_mov_b32 m0, s52
	s_nop 0
	global_load_lds_dwordx4 v[228:229], off
	s_waitcnt vmcnt(8)
	s_waitcnt lgkmcnt(0)
	s_barrier
; #define PG8_STAGE(bufoff, gbase, voff) do { _Pragma("unroll") for (int _i = 0; _i < 2; ++_i) \
;         __builtin_amdgcn_global_load_lds((const unsigned*)((const char*)(gbase) + (voff)[_i]), (LAS unsigned*)(lds + (bufoff) + ldsw + _i * 8192), 16, 0, 0); } while (0)
; #define PG8_LDA(dst, b, h) do { _Pragma("unroll") for (int m = 0; m < 4; ++m) _Pragma("unroll") for (int k = 0; k < 2; ++k) dst[m][k] = *(const LAS bf16x8*)(lds + PG8_SA(b, h) + aoff + m * 2048 + k * 1024); } while (0)
; #define PG8_LDB(dst, b, h) do { _Pragma("unroll") for (int n = 0; n < 2; ++n) _Pragma("unroll") for (int k = 0; k < 2; ++k) dst[n][k] = *(const LAS bf16x8*)(lds + PG8_SB(b, h) + boff + n * 2048 + k * 1024); } while (0)
; #define PG8_MMA(ai, bj, At, Bt) do { __builtin_amdgcn_s_setprio(1); _Pragma("unroll") for (int m = 0; m < 4; ++m) _Pragma("unroll") for (int n = 0; n < 2; ++n) _Pragma("unroll") for (int k = 0; k < 2; ++k) \
;         acc[ai][bj][m][n] = __builtin_amdgcn_mfma_f32_16x16x32_bf16(Bt[n][k], At[m][k], acc[ai][bj][m][n], 0, 0, 0); __builtin_amdgcn_s_setprio(0); } while (0)
; #define PG8_WAIT_V(n) asm volatile("s_waitcnt vmcnt(" #n ")" ::: "memory")
; #define PG8_WAIT_L(n) asm volatile("s_waitcnt lgkmcnt(" #n ")" ::: "memory")
; #define PG8_BAR __builtin_amdgcn_s_barrier()
; #define PG8_SCHED __builtin_amdgcn_sched_barrier(0)
; template <class Epi, class Sched, bool ALIGN_EPI>
; DI void gemm_phase(LAS unsigned char* lds, const Gemm g, const Sched& Sc, const Epi& E, const int tid) {
;     ...
;             PG8_LDA(At, 0, 1); PG8_STAGE(PG8_SB(0, 0), b2, voffB); PG8_STAGE(PG8_SB(0, 1), b2 + hB, voffB); PG8_STAGE(PG8_SA(0, 0), a2, voffA);
;             PG8_WAIT_V(8); PG8_WAIT_L(0); PG8_BAR; PG8_MMA(1, 0, At, B0); PG8_MMA(1, 1, At, B1); PG8_BAR; PG8_SCHED;
;             PG8_LDB(B0, 1, 0); PG8_LDB(B1, 1, 1); PG8_SCHED; PG8_LDA(At, 1, 0); PG8_STAGE(PG8_SA(0, 1), a2 + hA, voffA);
;             PG8_WAIT_V(8); PG8_WAIT_L(0); PG8_BAR; PG8_MMA(0, 0, At, B0); PG8_MMA(0, 1, At, B1); PG8_BAR; PG8_SCHED;
	s_setprio 1
	s_waitcnt lgkmcnt(0)
	v_mfma_f32_16x16x32_bf16 v[64:67], v[148:151], v[180:183], v[64:67]
	v_mfma_f32_16x16x32_bf16 v[60:63], v[156:159], v[180:183], v[60:63]
	v_mfma_f32_16x16x32_bf16 v[56:59], v[148:151], v[188:191], v[56:59]
	v_mfma_f32_16x16x32_bf16 v[52:55], v[156:159], v[188:191], v[52:55]
	v_mfma_f32_16x16x32_bf16 v[40:43], v[148:151], v[198:201], v[40:43]
	v_mfma_f32_16x16x32_bf16 v[36:39], v[156:159], v[198:201], v[36:39]
	v_mfma_f32_16x16x32_bf16 v[24:27], v[148:151], v[214:217], v[24:27]
	v_mfma_f32_16x16x32_bf16 v[20:23], v[156:159], v[214:217], v[20:23]
	v_mfma_f32_16x16x32_bf16 v[64:67], v[152:155], v[184:187], v[64:67]
	v_mfma_f32_16x16x32_bf16 v[60:63], v[160:163], v[184:187], v[60:63]
	v_mfma_f32_16x16x32_bf16 v[56:59], v[152:155], v[192:195], v[56:59]
	v_mfma_f32_16x16x32_bf16 v[52:55], v[160:163], v[192:195], v[52:55]
	v_mfma_f32_16x16x32_bf16 v[40:43], v[152:155], v[210:213], v[40:43]
	v_mfma_f32_16x16x32_bf16 v[36:39], v[160:163], v[210:213], v[36:39]
	v_mfma_f32_16x16x32_bf16 v[24:27], v[152:155], v[218:221], v[24:27]
	v_mfma_f32_16x16x32_bf16 v[20:23], v[160:163], v[218:221], v[20:23]
	s_setprio 0
	s_setprio 1
	v_mfma_f32_16x16x32_bf16 v[48:51], v[164:167], v[180:183], v[48:51]
	v_mfma_f32_16x16x32_bf16 v[44:47], v[172:175], v[180:183], v[44:47]
	v_mfma_f32_16x16x32_bf16 v[32:35], v[164:167], v[188:191], v[32:35]
	v_mfma_f32_16x16x32_bf16 v[28:31], v[172:175], v[188:191], v[28:31]
	v_mfma_f32_16x16x32_bf16 v[14:17], v[164:167], v[198:201], v[14:17]
	v_mfma_f32_16x16x32_bf16 v[10:13], v[172:175], v[198:201], v[10:13]
	v_mfma_f32_16x16x32_bf16 v[6:9], v[164:167], v[214:217], v[6:9]
	v_mfma_f32_16x16x32_bf16 v[2:5], v[172:175], v[214:217], v[2:5]
	v_mfma_f32_16x16x32_bf16 v[48:51], v[168:171], v[184:187], v[48:51]
	v_mfma_f32_16x16x32_bf16 v[44:47], v[176:179], v[184:187], v[44:47]
	v_mfma_f32_16x16x32_bf16 v[32:35], v[168:171], v[192:195], v[32:35]
	v_mfma_f32_16x16x32_bf16 v[28:31], v[176:179], v[192:195], v[28:31]
	v_mfma_f32_16x16x32_bf16 v[14:17], v[168:171], v[210:213], v[14:17]
	v_mfma_f32_16x16x32_bf16 v[10:13], v[176:179], v[210:213], v[10:13]
	v_mfma_f32_16x16x32_bf16 v[6:9], v[168:171], v[218:221], v[6:9]
	v_mfma_f32_16x16x32_bf16 v[2:5], v[176:179], v[218:221], v[2:5]
	s_setprio 0
	s_barrier
	v_add_u32_e32 v147, s55, v143
	ds_read_b128 v[148:151], v147
	ds_read_b128 v[152:155], v147 offset:1024
	ds_read_b128 v[156:159], v147 offset:2048
	ds_read_b128 v[160:163], v147 offset:3072
	v_add_u32_e32 v147, s64, v143
	ds_read_b128 v[164:167], v147
	ds_read_b128 v[168:171], v147 offset:1024
	ds_read_b128 v[172:175], v147 offset:2048
	ds_read_b128 v[176:179], v147 offset:3072
	s_add_u32 s44, s44, 0x80000
	s_addc_u32 s45, s45, 0
	s_mov_b32 m0, s53
	v_lshl_add_u64 v[230:231], s[44:45], 0, v[136:137]
	ds_read_b128 v[180:183], v146 offset:32768
	ds_read_b128 v[184:187], v146 offset:33792
	ds_read_b128 v[188:191], v146 offset:34816
	ds_read_b128 v[192:195], v146 offset:35840
	ds_read_b128 v[198:201], v146 offset:36864
	ds_read_b128 v[210:213], v146 offset:37888
	ds_read_b128 v[214:217], v146 offset:38912
	ds_read_b128 v[218:221], v146 offset:39936
	global_load_lds_dwordx4 v[230:231], off
	v_lshl_add_u64 v[230:231], s[44:45], 0, v[134:135]
	s_mov_b32 m0, s54
	s_nop 0
	global_load_lds_dwordx4 v[230:231], off
	s_waitcnt vmcnt(8)
	s_waitcnt lgkmcnt(0)
	s_barrier
	s_setprio 1
	s_waitcnt lgkmcnt(0)
	v_mfma_f32_16x16x32_bf16 v[128:131], v[148:151], v[180:183], v[128:131]
	v_mfma_f32_16x16x32_bf16 v[124:127], v[156:159], v[180:183], v[124:127]
	v_mfma_f32_16x16x32_bf16 v[120:123], v[148:151], v[188:191], v[120:123]
	v_mfma_f32_16x16x32_bf16 v[116:119], v[156:159], v[188:191], v[116:119]
	v_mfma_f32_16x16x32_bf16 v[104:107], v[148:151], v[198:201], v[104:107]
	v_mfma_f32_16x16x32_bf16 v[100:103], v[156:159], v[198:201], v[100:103]
	v_mfma_f32_16x16x32_bf16 v[88:91], v[148:151], v[214:217], v[88:91]
	v_mfma_f32_16x16x32_bf16 v[84:87], v[156:159], v[214:217], v[84:87]
	v_mfma_f32_16x16x32_bf16 v[128:131], v[152:155], v[184:187], v[128:131]
	v_mfma_f32_16x16x32_bf16 v[124:127], v[160:163], v[184:187], v[124:127]
	v_mfma_f32_16x16x32_bf16 v[120:123], v[152:155], v[192:195], v[120:123]
	v_mfma_f32_16x16x32_bf16 v[116:119], v[160:163], v[192:195], v[116:119]
	v_mfma_f32_16x16x32_bf16 v[104:107], v[152:155], v[210:213], v[104:107]
	v_mfma_f32_16x16x32_bf16 v[100:103], v[160:163], v[210:213], v[100:103]
	v_mfma_f32_16x16x32_bf16 v[88:91], v[152:155], v[218:221], v[88:91]
	v_mfma_f32_16x16x32_bf16 v[84:87], v[160:163], v[218:221], v[84:87]
	s_setprio 0
	s_setprio 1
	v_mfma_f32_16x16x32_bf16 v[112:115], v[164:167], v[180:183], v[112:115]
	v_mfma_f32_16x16x32_bf16 v[108:111], v[172:175], v[180:183], v[108:111]
	v_mfma_f32_16x16x32_bf16 v[96:99], v[164:167], v[188:191], v[96:99]
	v_mfma_f32_16x16x32_bf16 v[92:95], v[172:175], v[188:191], v[92:95]
	v_mfma_f32_16x16x32_bf16 v[80:83], v[164:167], v[198:201], v[80:83]
	v_mfma_f32_16x16x32_bf16 v[76:79], v[172:175], v[198:201], v[76:79]
	v_mfma_f32_16x16x32_bf16 v[72:75], v[164:167], v[214:217], v[72:75]
	v_mfma_f32_16x16x32_bf16 v[68:71], v[172:175], v[214:217], v[68:71]
	v_mfma_f32_16x16x32_bf16 v[112:115], v[168:171], v[184:187], v[112:115]
	v_mfma_f32_16x16x32_bf16 v[108:111], v[176:179], v[184:187], v[108:111]
	v_mfma_f32_16x16x32_bf16 v[96:99], v[168:171], v[192:195], v[96:99]
	v_mfma_f32_16x16x32_bf16 v[92:95], v[176:179], v[192:195], v[92:95]
	v_mfma_f32_16x16x32_bf16 v[80:83], v[168:171], v[210:213], v[80:83]
	v_mfma_f32_16x16x32_bf16 v[76:79], v[176:179], v[210:213], v[76:79]
	v_mfma_f32_16x16x32_bf16 v[72:75], v[168:171], v[218:221], v[72:75]
	v_mfma_f32_16x16x32_bf16 v[68:71], v[176:179], v[218:221], v[68:71]
	s_setprio 0
	s_barrier
; #define PG8_STAGE(bufoff, gbase, voff) do { _Pragma("unroll") for (int _i = 0; _i < 2; ++_i) \
;         __builtin_amdgcn_global_load_lds((const unsigned*)((const char*)(gbase) + (voff)[_i]), (LAS unsigned*)(lds + (bufoff) + ldsw + _i * 8192), 16, 0, 0); } while (0)
; #define PG8_LDA(dst, b, h) do { _Pragma("unroll") for (int m = 0; m < 4; ++m) _Pragma("unroll") for (int k = 0; k < 2; ++k) dst[m][k] = *(const LAS bf16x8*)(lds + PG8_SA(b, h) + aoff + m * 2048 + k * 1024); } while (0)
; #define PG8_MMA(ai, bj, At, Bt) do { __builtin_amdgcn_s_setprio(1); _Pragma("unroll") for (int m = 0; m < 4; ++m) _Pragma("unroll") for (int n = 0; n < 2; ++n) _Pragma("unroll") for (int k = 0; k < 2; ++k) \
;         acc[ai][bj][m][n] = __builtin_amdgcn_mfma_f32_16x16x32_bf16(Bt[n][k], At[m][k], acc[ai][bj][m][n], 0, 0, 0); __builtin_amdgcn_s_setprio(0); } while (0)
; #define PG8_WAIT_V(n) asm volatile("s_waitcnt vmcnt(" #n ")" ::: "memory")
; #define PG8_WAIT_L(n) asm volatile("s_waitcnt lgkmcnt(" #n ")" ::: "memory")
; #define PG8_BAR __builtin_amdgcn_s_barrier()
; #define PG8_SCHED __builtin_amdgcn_sched_barrier(0)
; template <class Epi, class Sched, bool ALIGN_EPI>
; DI void gemm_phase(LAS unsigned char* lds, const Gemm g, const Sched& Sc, const Epi& E, const int tid) {
;     ...
;             PG8_LDA(At, 1, 1); PG8_STAGE(PG8_SB(1, 0), b3, voffB); PG8_STAGE(PG8_SB(1, 1), b3 + hB, voffB); PG8_STAGE(PG8_SA(1, 0), a3, voffA);
;             PG8_WAIT_V(8); PG8_WAIT_L(0); PG8_BAR; PG8_MMA(1, 0, At, B0); PG8_MMA(1, 1, At, B1); PG8_BAR; PG8_SCHED;
;         }
;         if constexpr (ALIGN_EPI) { if (wr == 0) PG8_BAR; }
	s_mov_b32 m0, s56
	v_lshl_add_u64 v[222:223], v[222:223], 0, s[60:61]
	s_add_u32 s42, s42, 0x80080
	ds_read_b128 v[180:183], v146 offset:49152
	ds_read_b128 v[184:187], v146 offset:50176
	ds_read_b128 v[188:191], v146 offset:51200
	ds_read_b128 v[192:195], v146 offset:52224
	ds_read_b128 v[198:201], v146 offset:53248
	ds_read_b128 v[210:213], v146 offset:54272
	ds_read_b128 v[214:217], v146 offset:55296
	ds_read_b128 v[218:221], v146 offset:56320
	global_load_lds_dwordx4 v[222:223], off
	v_lshl_add_u64 v[222:223], v[224:225], 0, s[60:61]
	s_mov_b32 m0, s57
	s_addc_u32 s43, s43, 0
	global_load_lds_dwordx4 v[222:223], off
	v_lshl_add_u64 v[222:223], s[42:43], 0, v[18:19]
	s_mov_b32 m0, s65
	s_nop 0
	global_load_lds_dwordx4 v[222:223], off
	v_lshl_add_u64 v[222:223], s[42:43], 0, v[132:133]
	s_mov_b32 m0, s66
	s_nop 0
	global_load_lds_dwordx4 v[222:223], off
	v_lshl_add_u64 v[222:223], v[226:227], 0, s[60:61]
	s_mov_b32 m0, s62
	s_nop 0
	global_load_lds_dwordx4 v[222:223], off
	v_lshl_add_u64 v[222:223], v[228:229], 0, s[60:61]
	s_mov_b32 m0, s63
	s_nop 0
	global_load_lds_dwordx4 v[222:223], off
	s_waitcnt vmcnt(8)
	s_waitcnt lgkmcnt(0)
	s_barrier
	s_setprio 1
	s_waitcnt lgkmcnt(0)
	v_mfma_f32_16x16x32_bf16 v[64:67], v[148:151], v[180:183], v[64:67]
	v_mfma_f32_16x16x32_bf16 v[60:63], v[156:159], v[180:183], v[60:63]
	v_mfma_f32_16x16x32_bf16 v[56:59], v[148:151], v[188:191], v[56:59]
	v_mfma_f32_16x16x32_bf16 v[52:55], v[156:159], v[188:191], v[52:55]
	v_mfma_f32_16x16x32_bf16 v[40:43], v[148:151], v[198:201], v[40:43]
	v_mfma_f32_16x16x32_bf16 v[36:39], v[156:159], v[198:201], v[36:39]
	v_mfma_f32_16x16x32_bf16 v[24:27], v[148:151], v[214:217], v[24:27]
	v_mfma_f32_16x16x32_bf16 v[20:23], v[156:159], v[214:217], v[20:23]
	v_mfma_f32_16x16x32_bf16 v[64:67], v[152:155], v[184:187], v[64:67]
	v_mfma_f32_16x16x32_bf16 v[60:63], v[160:163], v[184:187], v[60:63]
	v_mfma_f32_16x16x32_bf16 v[56:59], v[152:155], v[192:195], v[56:59]
	v_mfma_f32_16x16x32_bf16 v[52:55], v[160:163], v[192:195], v[52:55]
	v_mfma_f32_16x16x32_bf16 v[40:43], v[152:155], v[210:213], v[40:43]
	v_mfma_f32_16x16x32_bf16 v[36:39], v[160:163], v[210:213], v[36:39]
	v_mfma_f32_16x16x32_bf16 v[24:27], v[152:155], v[218:221], v[24:27]
	v_mfma_f32_16x16x32_bf16 v[20:23], v[160:163], v[218:221], v[20:23]
	s_setprio 0
	s_setprio 1
	v_mfma_f32_16x16x32_bf16 v[48:51], v[164:167], v[180:183], v[48:51]
	v_mfma_f32_16x16x32_bf16 v[44:47], v[172:175], v[180:183], v[44:47]
	v_mfma_f32_16x16x32_bf16 v[32:35], v[164:167], v[188:191], v[32:35]
	v_mfma_f32_16x16x32_bf16 v[28:31], v[172:175], v[188:191], v[28:31]
	v_mfma_f32_16x16x32_bf16 v[14:17], v[164:167], v[198:201], v[14:17]
	v_mfma_f32_16x16x32_bf16 v[10:13], v[172:175], v[198:201], v[10:13]
	v_mfma_f32_16x16x32_bf16 v[6:9], v[164:167], v[214:217], v[6:9]
	v_mfma_f32_16x16x32_bf16 v[2:5], v[172:175], v[214:217], v[2:5]
	v_mfma_f32_16x16x32_bf16 v[48:51], v[168:171], v[184:187], v[48:51]
	v_mfma_f32_16x16x32_bf16 v[44:47], v[176:179], v[184:187], v[44:47]
	v_mfma_f32_16x16x32_bf16 v[32:35], v[168:171], v[192:195], v[32:35]
	v_mfma_f32_16x16x32_bf16 v[28:31], v[176:179], v[192:195], v[28:31]
	v_mfma_f32_16x16x32_bf16 v[14:17], v[168:171], v[210:213], v[14:17]
	v_mfma_f32_16x16x32_bf16 v[10:13], v[176:179], v[210:213], v[10:13]
	v_mfma_f32_16x16x32_bf16 v[6:9], v[168:171], v[218:221], v[6:9]
	v_mfma_f32_16x16x32_bf16 v[2:5], v[176:179], v[218:221], v[2:5]
	s_add_i32 s75, s75, 2
	s_add_u32 s73, s73, 0x100
	s_addc_u32 s74, s74, 0
	s_add_u32 s40, s40, 0x100
	s_addc_u32 s41, s41, 0
	s_cmp_gt_u32 s75, 29
	s_setprio 0
	s_barrier
	s_cbranch_scc0 .LBB0_2634
	s_and_b64 vcc, exec, s[16:17]
	s_cbranch_vccz .LBB0_2637
	s_barrier
